# gemm_tile: (row>>3)&3 added to the LDS chunk swizzle of all ds_write_b128 tiles and their fragment reads (2-way read conflicts removed)
# speedup vs baseline: 1.0418x; 1.0033x over previous
.LBB0_239:
	s_waitcnt vmcnt(0)
	v_mov_b32_e32 v64, v208
	s_lshl_b32 s1, s2, 6
	v_bfe_u32 v0, v64, 5, 1
	v_and_b32_e32 v1, 7, v64
	v_ashrrev_i32_e32 v3, 1, v64
	v_and_b32_e32 v66, 31, v64
	v_lshlrev_b32_e32 v2, 7, v64
	v_and_b32_e32 v67, 0xffffffc0, v3
	v_bitop3_b32 v4, v0, v64, 7 bitop3:0x78
	v_bitop3_b32 v5, v0, v1, 2 bitop3:0x36
	v_bitop3_b32 v6, v0, v1, 4 bitop3:0x36
	v_bitop3_b32 v0, v0, v1, 6 bitop3:0x36
	s_lshl_b32 s0, s2, 7
	s_and_b32 s1, s1, 0x7fffff80
	v_and_b32_e32 v2, 0x2f80, v2
	v_or_b32_e32 v3, v67, v66
	v_lshlrev_b32_e32 v4, 4, v4
	v_lshlrev_b32_e32 v5, 4, v5
	v_lshlrev_b32_e32 v6, 4, v6
	v_lshlrev_b32_e32 v0, 4, v0
	s_and_b32 s0, s0, 0x80
	s_addk_i32 s1, 0x9d00
	v_lshl_add_u32 v3, v3, 7, v214
	v_or_b32_e32 v16, v4, v2
	v_bfe_u32 v168, v208, 3, 2
	v_lshlrev_b32_e32 v168, 4, v168
	v_xor_b32_e32 v16, v168, v16
	v_or_b32_e32 v17, v5, v2
	v_bfe_u32 v168, v208, 3, 2
	v_lshlrev_b32_e32 v168, 4, v168
	v_xor_b32_e32 v17, v168, v17
	v_or_b32_e32 v18, v6, v2
	v_bfe_u32 v168, v208, 3, 2
	v_lshlrev_b32_e32 v168, 4, v168
	v_xor_b32_e32 v18, v168, v18
	v_or_b32_e32 v19, v0, v2
	v_bfe_u32 v168, v208, 3, 2
	v_lshlrev_b32_e32 v168, 4, v168
	v_xor_b32_e32 v19, v168, v19
	v_ashrrev_i32_e32 v25, 3, v64
	v_lshlrev_b32_e32 v2, 4, v64
	v_or_b32_e32 v23, v3, v0
	v_bfe_u32 v168, v208, 3, 2
	v_lshlrev_b32_e32 v168, 4, v168
	v_xor_b32_e32 v23, v168, v23
	v_add_u32_e32 v0, s0, v25
	v_and_b32_e32 v192, 0x70, v2
	v_add_u32_e32 v2, s1, v25
	v_ashrrev_i32_e32 v1, 31, v0
	v_readlane_b32 s4, v253, 22
	v_min_i32_e32 v2, 0x41ff, v2
	v_or_b32_e32 v20, v3, v4
	v_bfe_u32 v168, v208, 3, 2
	v_lshlrev_b32_e32 v168, 4, v168
	v_xor_b32_e32 v20, v168, v20
	v_or_b32_e32 v21, v3, v5
	v_bfe_u32 v168, v208, 3, 2
	v_lshlrev_b32_e32 v168, 4, v168
	v_xor_b32_e32 v21, v168, v21
	v_or_b32_e32 v22, v3, v6
	v_bfe_u32 v168, v208, 3, 2
	v_lshlrev_b32_e32 v168, 4, v168
	v_xor_b32_e32 v22, v168, v22
	v_lshlrev_b64 v[0:1], 10, v[0:1]
	v_readlane_b32 s5, v253, 23
	v_ashrrev_i32_e32 v3, 31, v2
	v_readlane_b32 s6, v254, 1
	v_add_u32_e32 v4, 0x100, v64
	v_lshl_add_u64 v[0:1], s[4:5], 0, v[0:1]
	v_lshlrev_b64 v[2:3], 10, v[2:3]
	v_readlane_b32 s7, v254, 2
	v_ashrrev_i32_e32 v30, 3, v4
	v_lshl_add_u64 v[0:1], v[0:1], 0, v[192:193]
	v_lshl_add_u64 v[2:3], s[6:7], 0, v[2:3]
	v_add_u32_e32 v4, s0, v30
	v_add_u32_e32 v6, s1, v30
	v_add_u32_e32 v8, 0x200, v64
	global_load_dwordx4 v[26:29], v[0:1], off
	v_lshl_add_u64 v[2:3], v[2:3], 0, v[192:193]
	v_ashrrev_i32_e32 v5, 31, v4
	v_min_i32_e32 v6, 0x41ff, v6
	v_ashrrev_i32_e32 v31, 3, v8
	global_load_dwordx4 v[68:71], v[2:3], off
	v_lshlrev_b64 v[4:5], 10, v[4:5]
	v_ashrrev_i32_e32 v7, 31, v6
	v_add_u32_e32 v8, s0, v31
	v_add_u32_e32 v10, s1, v31
	v_add_u32_e32 v12, 0x300, v64
	v_lshl_add_u64 v[4:5], s[4:5], 0, v[4:5]
	v_lshlrev_b64 v[6:7], 10, v[6:7]
	v_ashrrev_i32_e32 v9, 31, v8
	v_min_i32_e32 v10, 0x41ff, v10
	v_ashrrev_i32_e32 v96, 3, v12
	v_lshl_add_u64 v[4:5], v[4:5], 0, v[192:193]
	v_lshl_add_u64 v[6:7], s[6:7], 0, v[6:7]
	v_lshlrev_b64 v[8:9], 10, v[8:9]
	v_ashrrev_i32_e32 v11, 31, v10
	v_add_u32_e32 v12, s0, v96
	global_load_dwordx4 v[72:75], v[4:5], off
	v_lshl_add_u64 v[6:7], v[6:7], 0, v[192:193]
	v_lshl_add_u64 v[8:9], s[4:5], 0, v[8:9]
	v_lshlrev_b64 v[10:11], 10, v[10:11]
	v_ashrrev_i32_e32 v13, 31, v12
	global_load_dwordx4 v[76:79], v[6:7], off
	v_lshl_add_u64 v[8:9], v[8:9], 0, v[192:193]
	v_lshl_add_u64 v[10:11], s[6:7], 0, v[10:11]
	v_lshlrev_b64 v[12:13], 10, v[12:13]
	global_load_dwordx4 v[80:83], v[8:9], off
	v_lshl_add_u64 v[10:11], v[10:11], 0, v[192:193]
	v_lshl_add_u64 v[12:13], s[4:5], 0, v[12:13]
	global_load_dwordx4 v[84:87], v[10:11], off
	v_lshl_add_u64 v[12:13], v[12:13], 0, v[192:193]
	global_load_dwordx4 v[88:91], v[12:13], off
	v_add_u32_e32 v14, s1, v96
	v_min_i32_e32 v14, 0x41ff, v14
	v_ashrrev_i32_e32 v15, 31, v14
	v_lshlrev_b64 v[14:15], 10, v[14:15]
	v_lshl_add_u64 v[14:15], s[6:7], 0, v[14:15]
	v_lshl_add_u64 v[14:15], v[14:15], 0, v[192:193]
	global_load_dwordx4 v[92:95], v[14:15], off
	global_load_dwordx4 v[32:35], v[0:1], off offset:128
	global_load_dwordx4 v[36:39], v[2:3], off offset:128
	global_load_dwordx4 v[40:43], v[4:5], off offset:128
	global_load_dwordx4 v[44:47], v[6:7], off offset:128
	global_load_dwordx4 v[48:51], v[8:9], off offset:128
	global_load_dwordx4 v[52:55], v[10:11], off offset:128
	global_load_dwordx4 v[56:59], v[12:13], off offset:128
	global_load_dwordx4 v[60:63], v[14:15], off offset:128
	v_lshlrev_b32_e32 v24, 7, v25
	v_xor_b32_e32 v25, v25, v64
	v_lshlrev_b32_e32 v25, 4, v25
	v_and_b32_e32 v25, 0x70, v25
	v_or_b32_e32 v97, v24, v25
	v_bfe_u32 v168, v208, 6, 2
	v_lshlrev_b32_e32 v168, 4, v168
	v_xor_b32_e32 v97, v168, v97
	s_waitcnt vmcnt(15)
	ds_write_b128 v97, v[26:29]
	s_waitcnt vmcnt(14)
	ds_write_b128 v97, v[68:71] offset:16384
	v_xor_b32_e32 v27, v30, v64
	v_lshlrev_b32_e32 v27, 4, v27
	v_lshlrev_b32_e32 v26, 7, v30
	v_and_b32_e32 v27, 0x70, v27
	v_xor_b32_e32 v29, v31, v64
	v_or_b32_e32 v28, v26, v27
	v_bfe_u32 v168, v208, 6, 2
	v_lshlrev_b32_e32 v168, 4, v168
	v_xor_b32_e32 v28, v168, v28
	v_lshlrev_b32_e32 v29, 4, v29
	s_waitcnt vmcnt(13)
	ds_write_b128 v28, v[72:75]
	s_waitcnt vmcnt(12)
	ds_write_b128 v28, v[76:79] offset:16384
	v_lshlrev_b32_e32 v28, 7, v31
	v_and_b32_e32 v29, 0x70, v29
	v_xor_b32_e32 v31, v96, v64
	v_or_b32_e32 v30, v28, v29
	v_bfe_u32 v168, v208, 6, 2
	v_lshlrev_b32_e32 v168, 4, v168
	v_xor_b32_e32 v30, v168, v30
	v_lshlrev_b32_e32 v31, 4, v31
	s_waitcnt vmcnt(11)
	ds_write_b128 v30, v[80:83]
	s_waitcnt vmcnt(10)
	ds_write_b128 v30, v[84:87] offset:16384
	v_lshlrev_b32_e32 v30, 7, v96
	v_and_b32_e32 v31, 0x70, v31
	v_and_b32_e32 v65, 63, v64
	v_or_b32_e32 v68, v30, v31
	v_bfe_u32 v168, v208, 6, 2
	v_lshlrev_b32_e32 v168, 4, v168
	v_xor_b32_e32 v68, v168, v68
	v_accvgpr_write_b32 a47, 0
	v_accvgpr_write_b32 a46, 0
	v_accvgpr_write_b32 a45, 0
	v_accvgpr_write_b32 a44, 0
	v_accvgpr_write_b32 a43, 0
	v_accvgpr_write_b32 a42, 0
	v_accvgpr_write_b32 a41, 0
	v_accvgpr_write_b32 a40, 0
	v_accvgpr_write_b32 a39, 0
	v_accvgpr_write_b32 a38, 0
	v_accvgpr_write_b32 a37, 0
	v_accvgpr_write_b32 a36, 0
	v_accvgpr_write_b32 a35, 0
	v_accvgpr_write_b32 a34, 0
	v_accvgpr_write_b32 a33, 0
	v_accvgpr_write_b32 a32, 0
	v_accvgpr_write_b32 a63, 0
	v_accvgpr_write_b32 a62, 0
	v_accvgpr_write_b32 a61, 0
	v_accvgpr_write_b32 a60, 0
	v_accvgpr_write_b32 a59, 0
	v_accvgpr_write_b32 a58, 0
	v_accvgpr_write_b32 a57, 0
	v_accvgpr_write_b32 a56, 0
	v_accvgpr_write_b32 a55, 0
	v_accvgpr_write_b32 a54, 0
	v_accvgpr_write_b32 a53, 0
	v_accvgpr_write_b32 a52, 0
	v_accvgpr_write_b32 a51, 0
	v_accvgpr_write_b32 a50, 0
	v_accvgpr_write_b32 a49, 0
	v_accvgpr_write_b32 a48, 0
	v_accvgpr_write_b32 a15, 0
	v_accvgpr_write_b32 a14, 0
	v_accvgpr_write_b32 a13, 0
	v_accvgpr_write_b32 a12, 0
	v_accvgpr_write_b32 a11, 0
	v_accvgpr_write_b32 a10, 0
	v_accvgpr_write_b32 a9, 0
	v_accvgpr_write_b32 a8, 0
	v_accvgpr_write_b32 a7, 0
	v_accvgpr_write_b32 a6, 0
	v_accvgpr_write_b32 a5, 0
	v_accvgpr_write_b32 a4, 0
	v_accvgpr_write_b32 a3, 0
	v_accvgpr_write_b32 a2, 0
	v_accvgpr_write_b32 a1, 0
	v_accvgpr_write_b32 a0, 0
	v_accvgpr_write_b32 a31, 0
	v_accvgpr_write_b32 a30, 0
	v_accvgpr_write_b32 a29, 0
	v_accvgpr_write_b32 a28, 0
	v_accvgpr_write_b32 a27, 0
	v_accvgpr_write_b32 a26, 0
	v_accvgpr_write_b32 a25, 0
	v_accvgpr_write_b32 a24, 0
	v_accvgpr_write_b32 a23, 0
	v_accvgpr_write_b32 a22, 0
	v_accvgpr_write_b32 a21, 0
	v_accvgpr_write_b32 a20, 0
	v_accvgpr_write_b32 a19, 0
	v_accvgpr_write_b32 a18, 0
	v_accvgpr_write_b32 a17, 0
	v_accvgpr_write_b32 a16, 0
	s_mov_b32 s3, -2
	s_mov_b32 s4, 0
	s_waitcnt vmcnt(9)
	ds_write_b128 v68, v[88:91]
	s_waitcnt vmcnt(8)
	ds_write_b128 v68, v[92:95] offset:16384
	s_waitcnt lgkmcnt(0)
	s_barrier
.LBB0_240:
	s_add_i32 s5, s4, 0x80
	s_min_u32 s6, s5, 0x1c0
	s_lshl_b32 s78, s6, 1
	v_lshl_add_u64 v[68:69], v[0:1], 0, s[78:79]
	v_lshl_add_u64 v[72:73], v[2:3], 0, s[78:79]
	v_lshl_add_u64 v[76:77], v[4:5], 0, s[78:79]
	v_lshl_add_u64 v[80:81], v[6:7], 0, s[78:79]
	v_lshl_add_u64 v[84:85], v[8:9], 0, s[78:79]
	v_lshl_add_u64 v[88:89], v[10:11], 0, s[78:79]
	v_lshl_add_u64 v[92:93], v[12:13], 0, s[78:79]
	v_lshl_add_u64 v[96:97], v[14:15], 0, s[78:79]
	global_load_dwordx4 v[68:71], v[68:69], off
	s_nop 0
	global_load_dwordx4 v[72:75], v[72:73], off
	s_nop 0
	global_load_dwordx4 v[76:79], v[76:77], off
	s_nop 0
	global_load_dwordx4 v[80:83], v[80:81], off
	s_nop 0
	global_load_dwordx4 v[84:87], v[84:85], off
	s_nop 0
	global_load_dwordx4 v[88:91], v[88:89], off
	s_nop 0
	global_load_dwordx4 v[92:95], v[92:93], off
	s_nop 0
	global_load_dwordx4 v[96:99], v[96:97], off
	ds_read_b128 v[100:103], v16 offset:0
	ds_read_b128 v[104:107], v16 offset:0x1000
	ds_read_b128 v[108:111], v20 offset:0
	ds_read_b128 v[112:115], v20 offset:0x1000
	s_min_u32 s4, s4, 0x100
	ds_read_b128 v[116:119], v17 offset:0
	ds_read_b128 v[120:123], v17 offset:0x1000
	ds_read_b128 v[124:127], v21 offset:0
	ds_read_b128 v[128:131], v21 offset:0x1000
	ds_read_b128 v[132:135], v18 offset:0
	ds_read_b128 v[136:139], v18 offset:0x1000
	ds_read_b128 v[140:143], v22 offset:0
	ds_read_b128 v[144:147], v22 offset:0x1000
	ds_read_b128 v[148:151], v19 offset:0
	ds_read_b128 v[152:155], v19 offset:0x1000
	ds_read_b128 v[156:159], v23 offset:0
	ds_read_b128 v[160:163], v23 offset:0x1000
	s_waitcnt lgkmcnt(12)
	s_lshl_b32 s78, s4, 1
	v_mfma_f32_32x32x16_bf16 a[32:47], v[100:103], v[108:111], a[32:47]
	v_add_u32_e32 v164, v24, v25
	v_bfe_u32 v168, v208, 6, 2
	v_lshlrev_b32_e32 v168, 4, v168
	v_xor_b32_e32 v164, v168, v164
	s_waitcnt lgkmcnt(8)
	s_waitcnt lgkmcnt(4)
	v_add_u32_e32 v165, v26, v27
	v_bfe_u32 v168, v208, 6, 2
	v_lshlrev_b32_e32 v168, 4, v168
	v_xor_b32_e32 v165, v168, v165
	v_add_u32_e32 v166, v28, v29
	v_bfe_u32 v168, v208, 6, 2
	v_lshlrev_b32_e32 v168, 4, v168
	v_xor_b32_e32 v166, v168, v166
	v_add_u32_e32 v167, v30, v31
	v_bfe_u32 v168, v208, 6, 2
	v_lshlrev_b32_e32 v168, 4, v168
	v_xor_b32_e32 v167, v168, v167
	s_waitcnt lgkmcnt(0)
	v_mfma_f32_32x32x16_bf16 a[48:63], v[100:103], v[112:115], a[48:63]
	v_lshl_add_u64 v[100:101], v[0:1], 0, s[78:79]
	v_lshl_add_u64 v[102:103], v[2:3], 0, s[78:79]
	s_waitcnt vmcnt(15)
	ds_write_b128 v164, v[32:35] offset:32768
	s_waitcnt vmcnt(14)
	ds_write_b128 v164, v[36:39] offset:49152
	s_waitcnt vmcnt(13)
	ds_write_b128 v165, v[40:43] offset:32768
	s_waitcnt vmcnt(12)
	ds_write_b128 v165, v[44:47] offset:49152
	s_waitcnt vmcnt(11)
	ds_write_b128 v166, v[48:51] offset:32768
	s_waitcnt vmcnt(10)
	ds_write_b128 v166, v[52:55] offset:49152
	s_waitcnt vmcnt(9)
	ds_write_b128 v167, v[56:59] offset:32768
	s_waitcnt vmcnt(8)
	ds_write_b128 v167, v[60:63] offset:49152
	s_waitcnt lgkmcnt(0)
	s_barrier
	v_mfma_f32_32x32x16_bf16 a[0:15], v[104:107], v[108:111], a[0:15]
	v_lshl_add_u64 v[108:109], v[8:9], 0, s[78:79]
	v_lshl_add_u64 v[110:111], v[10:11], 0, s[78:79]
	s_add_i32 s3, s3, 2
	s_mov_b32 s4, s5
	s_cmp_lt_u32 s3, 6
	v_mfma_f32_32x32x16_bf16 a[16:31], v[104:107], v[112:115], a[16:31]
	v_lshl_add_u64 v[104:105], v[4:5], 0, s[78:79]
	v_lshl_add_u64 v[106:107], v[6:7], 0, s[78:79]
	v_lshl_add_u64 v[112:113], v[12:13], 0, s[78:79]
	v_lshl_add_u64 v[114:115], v[14:15], 0, s[78:79]
	global_load_dwordx4 v[32:35], v[100:101], off offset:384
	global_load_dwordx4 v[36:39], v[102:103], off offset:384
	global_load_dwordx4 v[40:43], v[104:105], off offset:384
	global_load_dwordx4 v[44:47], v[106:107], off offset:384
	global_load_dwordx4 v[48:51], v[108:109], off offset:384
	global_load_dwordx4 v[52:55], v[110:111], off offset:384
	global_load_dwordx4 v[56:59], v[112:113], off offset:384
	global_load_dwordx4 v[60:63], v[114:115], off offset:384
	ds_read_b128 v[100:103], v16 offset:0x8000
	v_mfma_f32_32x32x16_bf16 a[32:47], v[116:119], v[124:127], a[32:47]
	ds_read_b128 v[104:107], v16 offset:0x9000
	ds_read_b128 v[108:111], v20 offset:0x8000
	ds_read_b128 v[112:115], v20 offset:0x9000
	v_mfma_f32_32x32x16_bf16 a[48:63], v[116:119], v[128:131], a[48:63]
	ds_read_b128 v[116:119], v17 offset:0x8000
	v_mfma_f32_32x32x16_bf16 a[0:15], v[120:123], v[124:127], a[0:15]
	v_mfma_f32_32x32x16_bf16 a[16:31], v[120:123], v[128:131], a[16:31]
	ds_read_b128 v[120:123], v17 offset:0x9000
	ds_read_b128 v[124:127], v21 offset:0x8000
	ds_read_b128 v[128:131], v21 offset:0x9000
	v_mfma_f32_32x32x16_bf16 a[32:47], v[132:135], v[140:143], a[32:47]
	v_mfma_f32_32x32x16_bf16 a[48:63], v[132:135], v[144:147], a[48:63]
	ds_read_b128 v[132:135], v18 offset:0x8000
	v_mfma_f32_32x32x16_bf16 a[0:15], v[136:139], v[140:143], a[0:15]
	v_mfma_f32_32x32x16_bf16 a[16:31], v[136:139], v[144:147], a[16:31]
	ds_read_b128 v[136:139], v18 offset:0x9000
	ds_read_b128 v[140:143], v22 offset:0x8000
	ds_read_b128 v[144:147], v22 offset:0x9000
	v_mfma_f32_32x32x16_bf16 a[32:47], v[148:151], v[156:159], a[32:47]
	v_mfma_f32_32x32x16_bf16 a[48:63], v[148:151], v[160:163], a[48:63]
	ds_read_b128 v[148:151], v19 offset:0x8000
	v_mfma_f32_32x32x16_bf16 a[0:15], v[152:155], v[156:159], a[0:15]
	v_mfma_f32_32x32x16_bf16 a[16:31], v[152:155], v[160:163], a[16:31]
	ds_read_b128 v[152:155], v19 offset:0x9000
	ds_read_b128 v[156:159], v23 offset:0x8000
	ds_read_b128 v[160:163], v23 offset:0x9000
	s_waitcnt lgkmcnt(12)
	s_waitcnt lgkmcnt(8)
	s_waitcnt lgkmcnt(4)
	s_nop 0
	v_mfma_f32_32x32x16_bf16 a[32:47], v[100:103], v[108:111], a[32:47]
	s_waitcnt lgkmcnt(0)
	s_waitcnt vmcnt(15)
	ds_write_b128 v164, v[68:71]
	s_waitcnt vmcnt(14)
	ds_write_b128 v164, v[72:75] offset:16384
	s_waitcnt vmcnt(13)
	ds_write_b128 v165, v[76:79]
	s_waitcnt vmcnt(12)
	ds_write_b128 v165, v[80:83] offset:16384
	s_waitcnt vmcnt(11)
	ds_write_b128 v166, v[84:87]
	s_waitcnt vmcnt(10)
	ds_write_b128 v166, v[88:91] offset:16384
	s_waitcnt vmcnt(9)
	ds_write_b128 v167, v[92:95]
	s_waitcnt vmcnt(8)
	ds_write_b128 v167, v[96:99] offset:16384
	s_waitcnt lgkmcnt(0)
	s_barrier
	v_mfma_f32_32x32x16_bf16 a[48:63], v[100:103], v[112:115], a[48:63]
	v_mfma_f32_32x32x16_bf16 a[0:15], v[104:107], v[108:111], a[0:15]
	v_mfma_f32_32x32x16_bf16 a[16:31], v[104:107], v[112:115], a[16:31]
	v_mfma_f32_32x32x16_bf16 a[32:47], v[116:119], v[124:127], a[32:47]
	v_mfma_f32_32x32x16_bf16 a[48:63], v[116:119], v[128:131], a[48:63]
	v_mfma_f32_32x32x16_bf16 a[0:15], v[120:123], v[124:127], a[0:15]
	v_mfma_f32_32x32x16_bf16 a[16:31], v[120:123], v[128:131], a[16:31]
	v_mfma_f32_32x32x16_bf16 a[32:47], v[132:135], v[140:143], a[32:47]
	v_mfma_f32_32x32x16_bf16 a[48:63], v[132:135], v[144:147], a[48:63]
	v_mfma_f32_32x32x16_bf16 a[0:15], v[136:139], v[140:143], a[0:15]
	v_mfma_f32_32x32x16_bf16 a[16:31], v[136:139], v[144:147], a[16:31]
	v_mfma_f32_32x32x16_bf16 a[32:47], v[148:151], v[156:159], a[32:47]
	v_mfma_f32_32x32x16_bf16 a[48:63], v[148:151], v[160:163], a[48:63]
	v_mfma_f32_32x32x16_bf16 a[0:15], v[152:155], v[156:159], a[0:15]
	v_mfma_f32_32x32x16_bf16 a[16:31], v[152:155], v[160:163], a[16:31]
	s_cbranch_scc1 .LBB0_240
	s_waitcnt vmcnt(0)
	s_nop 6
	v_accvgpr_read_b32 v63, a47
	v_or_b32_e32 v66, s1, v66
	v_cmp_lt_i32_e32 vcc, v211, v210
	v_accvgpr_read_b32 v48, a32
	v_add_u32_e32 v66, v66, v67
	v_cndmask_b32_e32 v67, v209, v211, vcc
	v_accvgpr_read_b32 v49, a33
	v_lshlrev_b32_e32 v69, 2, v67
	v_cvt_pk_bf16_f32 v48, v48, v49
	v_accvgpr_read_b32 v50, a34
	v_accvgpr_read_b32 v51, a35
	v_cvt_pk_bf16_f32 v49, v50, v51
	v_accvgpr_read_b32 v52, a36
	v_accvgpr_read_b32 v53, a37
	v_cvt_pk_bf16_f32 v52, v52, v53
	v_accvgpr_read_b32 v54, a38
	v_accvgpr_read_b32 v55, a39
	v_cvt_pk_bf16_f32 v53, v54, v55
	v_accvgpr_read_b32 v56, a40
	v_accvgpr_read_b32 v57, a41
	v_cvt_pk_bf16_f32 v50, v56, v57
	v_accvgpr_read_b32 v58, a42
	v_accvgpr_read_b32 v59, a43
	v_cvt_pk_bf16_f32 v51, v58, v59
	v_accvgpr_read_b32 v60, a44
	v_accvgpr_read_b32 v61, a45
	v_cvt_pk_bf16_f32 v54, v60, v61
	v_accvgpr_read_b32 v62, a46
	v_cvt_pk_bf16_f32 v55, v62, v63
	v_cmp_gt_u32_e32 vcc, 32, v65
	v_and_or_b32 v68, v64, 64, s0
	s_nop 0
	v_cndmask_b32_e32 v56, v48, v50, vcc
	v_cndmask_b32_e32 v57, v49, v51, vcc
	ds_bpermute_b32 v56, v69, v56
	ds_bpermute_b32 v57, v69, v57
	v_cndmask_b32_e32 v58, v52, v54, vcc
	v_cndmask_b32_e32 v59, v53, v55, vcc
	ds_bpermute_b32 v58, v69, v58
	ds_bpermute_b32 v59, v69, v59
	v_ashrrev_i32_e32 v67, 31, v66
	v_readlane_b32 s0, v253, 61
	s_waitcnt lgkmcnt(3)
	v_cndmask_b32_e32 v48, v56, v48, vcc
	s_waitcnt lgkmcnt(2)
	v_cndmask_b32_e32 v49, v57, v49, vcc
	v_cndmask_b32_e32 v50, v50, v56, vcc
	v_cndmask_b32_e32 v51, v51, v57, vcc
	v_lshlrev_b64 v[56:57], 11, v[66:67]
	v_readlane_b32 s1, v253, 62
	v_lshlrev_b32_e32 v192, 1, v68
	s_waitcnt lgkmcnt(1)
	v_cndmask_b32_e32 v52, v58, v52, vcc
	v_lshl_add_u64 v[56:57], s[0:1], 0, v[56:57]
	s_waitcnt lgkmcnt(0)
	v_cndmask_b32_e32 v53, v59, v53, vcc
	v_cndmask_b32_e32 v54, v54, v58, vcc
	v_cndmask_b32_e32 v55, v55, v59, vcc
	v_lshl_add_u64 v[56:57], v[56:57], 0, v[192:193]
	v_and_b32_e32 v58, 32, v64
	v_mov_b32_e32 v59, v193
	v_accvgpr_read_b32 v32, a48
	v_lshl_add_u64 v[56:57], v[56:57], 0, v[58:59]
	v_accvgpr_read_b32 v33, a49
	global_store_dwordx4 v[56:57], v[48:51], off offset:768
	global_store_dwordx4 v[56:57], v[52:55], off offset:784
	v_accvgpr_read_b32 v34, a50
	v_cvt_pk_bf16_f32 v32, v32, v33
	v_accvgpr_read_b32 v35, a51
	v_cvt_pk_bf16_f32 v33, v34, v35
	v_accvgpr_read_b32 v36, a52
	v_accvgpr_read_b32 v37, a53
	v_cvt_pk_bf16_f32 v36, v36, v37
	v_accvgpr_read_b32 v38, a54
	v_accvgpr_read_b32 v39, a55
	v_cvt_pk_bf16_f32 v37, v38, v39
	v_accvgpr_read_b32 v40, a56
	v_accvgpr_read_b32 v41, a57
	v_cvt_pk_bf16_f32 v34, v40, v41
	v_accvgpr_read_b32 v42, a58
	v_accvgpr_read_b32 v43, a59
	v_cvt_pk_bf16_f32 v35, v42, v43
	v_accvgpr_read_b32 v44, a60
	v_accvgpr_read_b32 v45, a61
	v_cvt_pk_bf16_f32 v38, v44, v45
	v_accvgpr_read_b32 v46, a62
	v_cndmask_b32_e32 v41, v32, v34, vcc
	v_accvgpr_read_b32 v47, a63
	ds_bpermute_b32 v41, v69, v41
	v_cvt_pk_bf16_f32 v39, v46, v47
	v_cndmask_b32_e32 v42, v33, v35, vcc
	v_or_b32_e32 v40, 32, v66
	v_cndmask_b32_e32 v43, v36, v38, vcc
	ds_bpermute_b32 v42, v69, v42
	v_cndmask_b32_e32 v44, v37, v39, vcc
	ds_bpermute_b32 v43, v69, v43
	ds_bpermute_b32 v44, v69, v44
	s_waitcnt lgkmcnt(3)
	v_cndmask_b32_e32 v32, v41, v32, vcc
	v_cndmask_b32_e32 v34, v34, v41, vcc
	v_ashrrev_i32_e32 v41, 31, v40
	v_lshlrev_b64 v[40:41], 11, v[40:41]
	v_lshl_add_u64 v[40:41], s[0:1], 0, v[40:41]
	v_accvgpr_read_b32 v31, a15
	v_lshl_add_u64 v[40:41], v[40:41], 0, v[192:193]
	v_accvgpr_read_b32 v16, a0
	s_waitcnt lgkmcnt(2)
	v_cndmask_b32_e32 v33, v42, v33, vcc
	v_cndmask_b32_e32 v35, v35, v42, vcc
	v_lshl_add_u64 v[40:41], v[40:41], 0, v[58:59]
	v_accvgpr_read_b32 v17, a1
	s_waitcnt lgkmcnt(1)
	v_cndmask_b32_e32 v36, v43, v36, vcc
	s_waitcnt lgkmcnt(0)
	v_cndmask_b32_e32 v37, v44, v37, vcc
	v_cndmask_b32_e32 v38, v38, v43, vcc
	v_cndmask_b32_e32 v39, v39, v44, vcc
	global_store_dwordx4 v[40:41], v[32:35], off offset:768
	global_store_dwordx4 v[40:41], v[36:39], off offset:784
	v_accvgpr_read_b32 v18, a2
	v_cvt_pk_bf16_f32 v16, v16, v17
	v_accvgpr_read_b32 v19, a3
	v_cvt_pk_bf16_f32 v17, v18, v19
	v_accvgpr_read_b32 v20, a4
	v_accvgpr_read_b32 v21, a5
	v_cvt_pk_bf16_f32 v20, v20, v21
	v_accvgpr_read_b32 v22, a6
	v_accvgpr_read_b32 v23, a7
	v_cvt_pk_bf16_f32 v21, v22, v23
	v_accvgpr_read_b32 v24, a8
	v_accvgpr_read_b32 v25, a9
	v_cvt_pk_bf16_f32 v18, v24, v25
	v_accvgpr_read_b32 v26, a10
	v_accvgpr_read_b32 v27, a11
	v_cvt_pk_bf16_f32 v19, v26, v27
	v_accvgpr_read_b32 v28, a12
	v_accvgpr_read_b32 v29, a13
	v_cvt_pk_bf16_f32 v22, v28, v29
	v_accvgpr_read_b32 v30, a14
	v_cvt_pk_bf16_f32 v23, v30, v31
	v_cndmask_b32_e32 v24, v16, v18, vcc
	v_cndmask_b32_e32 v25, v17, v19, vcc
	v_cndmask_b32_e32 v26, v20, v22, vcc
	ds_bpermute_b32 v24, v69, v24
	ds_bpermute_b32 v25, v69, v25
	v_cndmask_b32_e32 v27, v21, v23, vcc
	ds_bpermute_b32 v26, v69, v26
	ds_bpermute_b32 v27, v69, v27
	v_accvgpr_read_b32 v0, a16
	s_waitcnt lgkmcnt(3)
	v_cndmask_b32_e32 v16, v24, v16, vcc
	s_waitcnt lgkmcnt(2)
	v_cndmask_b32_e32 v17, v25, v17, vcc
	v_cndmask_b32_e32 v18, v18, v24, vcc
	v_cndmask_b32_e32 v19, v19, v25, vcc
	v_accvgpr_read_b32 v1, a17
	s_waitcnt lgkmcnt(1)
	v_cndmask_b32_e32 v20, v26, v20, vcc
	s_waitcnt lgkmcnt(0)
	v_cndmask_b32_e32 v21, v27, v21, vcc
	v_cndmask_b32_e32 v22, v22, v26, vcc
	v_cndmask_b32_e32 v23, v23, v27, vcc
	global_store_dwordx4 v[56:57], v[16:19], off offset:832
	global_store_dwordx4 v[56:57], v[20:23], off offset:848
	v_accvgpr_read_b32 v2, a18
	v_cvt_pk_bf16_f32 v0, v0, v1
	v_accvgpr_read_b32 v3, a19
	v_cvt_pk_bf16_f32 v1, v2, v3
	v_accvgpr_read_b32 v4, a20
	v_accvgpr_read_b32 v5, a21
	v_cvt_pk_bf16_f32 v4, v4, v5
	v_accvgpr_read_b32 v6, a22
	v_accvgpr_read_b32 v7, a23
	v_cvt_pk_bf16_f32 v5, v6, v7
	v_accvgpr_read_b32 v8, a24
	v_accvgpr_read_b32 v9, a25
	v_cvt_pk_bf16_f32 v2, v8, v9
	v_accvgpr_read_b32 v10, a26
	v_accvgpr_read_b32 v11, a27
	v_cvt_pk_bf16_f32 v3, v10, v11
	v_accvgpr_read_b32 v12, a28
	v_accvgpr_read_b32 v13, a29
	v_cvt_pk_bf16_f32 v6, v12, v13
	v_accvgpr_read_b32 v14, a30
	v_accvgpr_read_b32 v15, a31
	v_cvt_pk_bf16_f32 v7, v14, v15
	v_cndmask_b32_e32 v8, v0, v2, vcc
	v_cndmask_b32_e32 v9, v1, v3, vcc
	v_cndmask_b32_e32 v10, v4, v6, vcc
	ds_bpermute_b32 v8, v69, v8
	ds_bpermute_b32 v9, v69, v9
	v_cndmask_b32_e32 v11, v5, v7, vcc
	ds_bpermute_b32 v10, v69, v10
	ds_bpermute_b32 v11, v69, v11
	s_waitcnt lgkmcnt(3)
	v_cndmask_b32_e32 v0, v8, v0, vcc
	s_waitcnt lgkmcnt(2)
	v_cndmask_b32_e32 v1, v9, v1, vcc
	v_cndmask_b32_e32 v2, v2, v8, vcc
	v_cndmask_b32_e32 v3, v3, v9, vcc
	s_waitcnt lgkmcnt(1)
	v_cndmask_b32_e32 v4, v10, v4, vcc
	s_waitcnt lgkmcnt(0)
	v_cndmask_b32_e32 v5, v11, v5, vcc
	v_cndmask_b32_e32 v6, v6, v10, vcc
	v_cndmask_b32_e32 v7, v7, v11, vcc
	global_store_dwordx4 v[40:41], v[0:3], off offset:832
	global_store_dwordx4 v[40:41], v[4:7], off offset:848
	s_branch .LBB0_236
.LBB0_242:
	s_mul_hi_i32 s0, s2, 0x55555556
	s_lshr_b32 s1, s0, 31
	v_mov_b32_e32 v107, v208
	s_add_i32 s0, s0, s1
	s_mul_i32 s1, s0, 3
	v_ashrrev_i32_e32 v3, 1, v107
	v_and_b32_e32 v106, 31, v107
	v_bfe_u32 v0, v107, 5, 1
	v_and_b32_e32 v2, 7, v107
	v_and_b32_e32 v109, 0xffffffc0, v3
	s_sub_i32 s1, s2, s1
	v_lshlrev_b32_e32 v1, 7, v107
	v_or_b32_e32 v3, v109, v106
	v_bitop3_b32 v4, v0, v107, 7 bitop3:0x78
	v_bitop3_b32 v5, v0, v2, 2 bitop3:0x36
	v_bitop3_b32 v6, v0, v2, 4 bitop3:0x36
	v_bitop3_b32 v0, v0, v2, 6 bitop3:0x36
	v_readlane_b32 s4, v253, 32
	v_add_u32_e32 v8, 0x100, v107
	v_add_u32_e32 v16, 0x200, v107
	v_add_u32_e32 v26, 0x300, v107
	s_lshl_b32 s1, s1, 7
	v_and_b32_e32 v1, 0x2f80, v1
	v_lshl_add_u32 v3, v3, 7, v214
	v_lshlrev_b32_e32 v0, 4, v0
	s_waitcnt vmcnt(3)
	v_ashrrev_i32_e32 v52, 3, v107
	v_readlane_b32 s5, v253, 33
	v_ashrrev_i32_e32 v53, 3, v8
	v_ashrrev_i32_e32 v54, 3, v16
	v_ashrrev_i32_e32 v55, 3, v26
	s_lshl_b32 s0, s0, 7
	v_lshlrev_b32_e32 v4, 4, v4
	v_lshlrev_b32_e32 v5, 4, v5
	v_lshlrev_b32_e32 v6, 4, v6
	v_or_b32_e32 v113, v0, v1
	v_bfe_u32 v127, v208, 3, 2
	v_lshlrev_b32_e32 v127, 4, v127
	v_xor_b32_e32 v113, v127, v113
	v_or_b32_e32 v117, v3, v0
	v_bfe_u32 v127, v208, 3, 2
	v_lshlrev_b32_e32 v127, 4, v127
	v_xor_b32_e32 v117, v127, v117
	v_add_u32_e32 v0, s1, v52
	v_mov_b64_e32 v[24:25], s[4:5]
	s_movk_i32 s3, 0x300
	v_add_u32_e32 v8, s1, v53
	v_add_u32_e32 v16, s1, v54
	v_add_u32_e32 v26, s1, v55
	v_or_b32_e32 v110, v4, v1
	v_bfe_u32 v127, v208, 3, 2
	v_lshlrev_b32_e32 v127, 4, v127
	v_xor_b32_e32 v110, v127, v110
	v_or_b32_e32 v111, v5, v1
	v_bfe_u32 v127, v208, 3, 2
	v_lshlrev_b32_e32 v127, 4, v127
	v_xor_b32_e32 v111, v127, v111
	v_or_b32_e32 v112, v6, v1
	v_bfe_u32 v127, v208, 3, 2
	v_lshlrev_b32_e32 v127, 4, v127
	v_xor_b32_e32 v112, v127, v112
	v_mad_i64_i32 v[0:1], s[4:5], v0, s3, v[24:25]
	v_lshlrev_b32_e32 v192, 4, v2
	v_bfe_u32 v50, v107, 1, 2
	v_add_u32_e32 v34, s0, v52
	v_mad_i64_i32 v[8:9], s[4:5], v8, s3, v[24:25]
	v_add_u32_e32 v38, s0, v53
	v_mad_i64_i32 v[16:17], s[4:5], v16, s3, v[24:25]
	v_add_u32_e32 v42, s0, v54
	v_mad_i64_i32 v[24:25], s[4:5], v26, s3, v[24:25]
	v_add_u32_e32 v46, s0, v55
	v_mov_b32_e32 v51, 0x10800
	s_movk_i32 s3, 0x4200
	v_lshl_add_u64 v[32:33], v[0:1], 0, v[192:193]
	v_mul_u32_u24_e32 v28, 0x4200, v50
	v_mov_b32_e32 v29, v193
	v_ashrrev_i32_e32 v35, 31, v34
	v_lshl_add_u64 v[36:37], v[8:9], 0, v[192:193]
	v_ashrrev_i32_e32 v39, 31, v38
	v_lshl_add_u64 v[40:41], v[16:17], 0, v[192:193]
	v_ashrrev_i32_e32 v43, 31, v42
	v_lshl_add_u64 v[44:45], v[24:25], 0, v[192:193]
	v_ashrrev_i32_e32 v47, 31, v46
	v_mad_u32_u24 v192, v50, s3, v51
	v_or_b32_e32 v114, v3, v4
	v_bfe_u32 v127, v208, 3, 2
	v_lshlrev_b32_e32 v127, 4, v127
	v_xor_b32_e32 v114, v127, v114
	v_or_b32_e32 v115, v3, v5
	v_bfe_u32 v127, v208, 3, 2
	v_lshlrev_b32_e32 v127, 4, v127
	v_xor_b32_e32 v115, v127, v115
	v_lshl_add_u64 v[4:5], v[28:29], 0, v[34:35]
	v_readlane_b32 s6, v254, 3
	v_lshl_add_u64 v[12:13], v[28:29], 0, v[38:39]
	v_lshl_add_u64 v[20:21], v[28:29], 0, v[42:43]
	v_lshl_add_u64 v[28:29], v[28:29], 0, v[46:47]
	v_lshl_add_u64 v[50:51], v[192:193], 0, v[34:35]
	v_or_b32_e32 v116, v3, v6
	v_bfe_u32 v127, v208, 3, 2
	v_lshlrev_b32_e32 v127, 4, v127
	v_xor_b32_e32 v116, v127, v116
	v_lshlrev_b64 v[4:5], 5, v[4:5]
	v_readlane_b32 s7, v254, 4
	v_lshlrev_b32_e32 v6, 4, v107
	v_lshlrev_b64 v[12:13], 5, v[12:13]
	v_lshlrev_b64 v[20:21], 5, v[20:21]
	v_lshlrev_b64 v[28:29], 5, v[28:29]
	v_lshlrev_b64 v[50:51], 5, v[50:51]
	v_lshl_add_u64 v[4:5], s[6:7], 0, v[4:5]
	v_and_b32_e32 v48, 16, v6
	v_mov_b32_e32 v49, v193
	v_lshl_add_u64 v[12:13], s[6:7], 0, v[12:13]
	v_lshl_add_u64 v[20:21], s[6:7], 0, v[20:21]
	v_lshl_add_u64 v[28:29], s[6:7], 0, v[28:29]
	v_lshl_add_u64 v[50:51], s[6:7], 0, v[50:51]
	v_lshl_add_u64 v[4:5], v[4:5], 0, v[48:49]
	v_lshl_add_u64 v[12:13], v[12:13], 0, v[48:49]
	v_lshl_add_u64 v[20:21], v[20:21], 0, v[48:49]
	v_lshl_add_u64 v[28:29], v[28:29], 0, v[48:49]
	v_lshl_add_u64 v[50:51], v[50:51], 0, v[48:49]
	v_lshlrev_b32_e32 v118, 3, v2
	global_load_dwordx4 v[0:3], v[32:33], off
	global_load_dwordx4 v[8:11], v[36:37], off
	global_load_dwordx4 v[16:19], v[40:41], off
	global_load_dwordx4 v[24:27], v[44:45], off
	v_lshlrev_b32_e32 v119, 7, v52
	global_load_dwordx4 v[4:7], v[4:5], off
	v_lshlrev_b32_e32 v121, 7, v53
	global_load_dwordx4 v[12:15], v[12:13], off
	v_lshlrev_b32_e32 v123, 7, v54
	global_load_dwordx4 v[20:23], v[20:21], off
	s_nop 0
	global_load_dwordx4 v[28:31], v[28:29], off
	s_nop 0
	global_load_dwordx4 v[136:139], v[32:33], off offset:128
	global_load_dwordx4 v[140:143], v[50:51], off
	global_load_dwordx4 v[144:147], v[36:37], off offset:128
	v_lshl_add_u64 v[50:51], v[192:193], 0, v[38:39]
	v_lshlrev_b64 v[50:51], 5, v[50:51]
	v_lshl_add_u64 v[50:51], s[6:7], 0, v[50:51]
	v_lshl_add_u64 v[50:51], v[50:51], 0, v[48:49]
	global_load_dwordx4 v[148:151], v[50:51], off
	global_load_dwordx4 v[152:155], v[40:41], off offset:128
	v_lshl_add_u64 v[50:51], v[192:193], 0, v[42:43]
	v_lshlrev_b64 v[50:51], 5, v[50:51]
	v_lshl_add_u64 v[50:51], s[6:7], 0, v[50:51]
	v_lshl_add_u64 v[50:51], v[50:51], 0, v[48:49]
	global_load_dwordx4 v[156:159], v[50:51], off
	global_load_dwordx4 v[160:163], v[44:45], off offset:128
	v_lshl_add_u64 v[50:51], v[192:193], 0, v[46:47]
	v_lshlrev_b64 v[50:51], 5, v[50:51]
	v_lshl_add_u64 v[50:51], s[6:7], 0, v[50:51]
	v_lshl_add_u64 v[50:51], v[50:51], 0, v[48:49]
	global_load_dwordx4 v[164:167], v[50:51], off
	v_xor_b32_e32 v50, v52, v107
	v_lshlrev_b32_e32 v50, 4, v50
	v_and_b32_e32 v120, 0x70, v50
	v_or_b32_e32 v50, v119, v120
	v_bfe_u32 v127, v208, 6, 2
	v_lshlrev_b32_e32 v127, 4, v127
	v_xor_b32_e32 v50, v127, v50
	s_waitcnt vmcnt(15)
	ds_write_b128 v50, v[0:3]
	s_waitcnt vmcnt(11)
	ds_write_b128 v50, v[4:7] offset:16384
	v_xor_b32_e32 v0, v53, v107
	v_lshlrev_b32_e32 v0, 4, v0
	v_and_b32_e32 v122, 0x70, v0
	v_or_b32_e32 v0, v121, v122
	v_bfe_u32 v127, v208, 6, 2
	v_lshlrev_b32_e32 v127, 4, v127
	v_xor_b32_e32 v0, v127, v0
	ds_write_b128 v0, v[8:11]
	s_waitcnt vmcnt(10)
	ds_write_b128 v0, v[12:15] offset:16384
	v_xor_b32_e32 v0, v54, v107
	v_lshlrev_b32_e32 v0, 4, v0
	v_and_b32_e32 v124, 0x70, v0
	v_or_b32_e32 v0, v123, v124
	v_bfe_u32 v127, v208, 6, 2
	v_lshlrev_b32_e32 v127, 4, v127
	v_xor_b32_e32 v0, v127, v0
	ds_write_b128 v0, v[16:19]
	s_waitcnt vmcnt(9)
	ds_write_b128 v0, v[20:23] offset:16384
	v_xor_b32_e32 v0, v55, v107
	v_lshlrev_b32_e32 v0, 4, v0
	v_lshlrev_b32_e32 v125, 7, v55
	v_and_b32_e32 v126, 0x70, v0
	v_and_b32_e32 v108, 63, v107
	v_or_b32_e32 v0, v125, v126
	v_bfe_u32 v127, v208, 6, 2
	v_lshlrev_b32_e32 v127, 4, v127
	v_xor_b32_e32 v0, v127, v0
	v_lshl_add_u64 v[48:49], s[6:7], 0, v[48:49]
	v_accvgpr_write_b32 a47, 0
	v_accvgpr_write_b32 a46, 0
	v_accvgpr_write_b32 a45, 0
	v_accvgpr_write_b32 a44, 0
	v_accvgpr_write_b32 a43, 0
	v_accvgpr_write_b32 a42, 0
	v_accvgpr_write_b32 a41, 0
	v_accvgpr_write_b32 a40, 0
	v_accvgpr_write_b32 a39, 0
	v_accvgpr_write_b32 a38, 0
	v_accvgpr_write_b32 a37, 0
	v_accvgpr_write_b32 a36, 0
	v_accvgpr_write_b32 a35, 0
	v_accvgpr_write_b32 a34, 0
	v_accvgpr_write_b32 a33, 0
	v_accvgpr_write_b32 a32, 0
	v_accvgpr_write_b32 a63, 0
	v_accvgpr_write_b32 a62, 0
	v_accvgpr_write_b32 a61, 0
	v_accvgpr_write_b32 a60, 0
	v_accvgpr_write_b32 a59, 0
	v_accvgpr_write_b32 a58, 0
	v_accvgpr_write_b32 a57, 0
	v_accvgpr_write_b32 a56, 0
	v_accvgpr_write_b32 a55, 0
	v_accvgpr_write_b32 a54, 0
	v_accvgpr_write_b32 a53, 0
	v_accvgpr_write_b32 a52, 0
	v_accvgpr_write_b32 a51, 0
	v_accvgpr_write_b32 a50, 0
	v_accvgpr_write_b32 a49, 0
	v_accvgpr_write_b32 a48, 0
	v_accvgpr_write_b32 a15, 0
	v_accvgpr_write_b32 a14, 0
	v_accvgpr_write_b32 a13, 0
	v_accvgpr_write_b32 a12, 0
	v_accvgpr_write_b32 a11, 0
	v_accvgpr_write_b32 a10, 0
	v_accvgpr_write_b32 a9, 0
	v_accvgpr_write_b32 a8, 0
	v_accvgpr_write_b32 a7, 0
	v_accvgpr_write_b32 a6, 0
	v_accvgpr_write_b32 a5, 0
	v_accvgpr_write_b32 a4, 0
	v_accvgpr_write_b32 a3, 0
	v_accvgpr_write_b32 a2, 0
	v_accvgpr_write_b32 a1, 0
	v_accvgpr_write_b32 a0, 0
	v_accvgpr_write_b32 a31, 0
	v_accvgpr_write_b32 a30, 0
	v_accvgpr_write_b32 a29, 0
	v_accvgpr_write_b32 a28, 0
	v_accvgpr_write_b32 a27, 0
	v_accvgpr_write_b32 a26, 0
	v_accvgpr_write_b32 a25, 0
	v_accvgpr_write_b32 a24, 0
	v_accvgpr_write_b32 a23, 0
	v_accvgpr_write_b32 a22, 0
	v_accvgpr_write_b32 a21, 0
	v_accvgpr_write_b32 a20, 0
	v_accvgpr_write_b32 a19, 0
	v_accvgpr_write_b32 a18, 0
	v_accvgpr_write_b32 a17, 0
	v_accvgpr_write_b32 a16, 0
	s_mov_b32 s3, -2
	s_mov_b32 s4, 0
	ds_write_b128 v0, v[24:27]
	s_waitcnt vmcnt(8)
	ds_write_b128 v0, v[28:31] offset:16384
	s_waitcnt lgkmcnt(0)
	s_barrier
.LBB0_243:
	s_add_i32 s5, s4, 0x80
	s_min_u32 s6, s5, 0x140
	v_or_b32_e32 v2, s6, v118
	s_lshl_b32 s78, s6, 1
	v_lshrrev_b32_e32 v6, 4, v2
	v_lshl_add_u64 v[0:1], v[32:33], 0, s[78:79]
	v_lshl_add_u64 v[2:3], v[36:37], 0, s[78:79]
	v_lshl_add_u64 v[4:5], v[40:41], 0, s[78:79]
	v_lshl_add_u64 v[16:17], v[44:45], 0, s[78:79]
	v_mul_u32_u24_e32 v192, 0x4200, v6
	global_load_dwordx4 v[8:11], v[0:1], off
	global_load_dwordx4 v[12:15], v[2:3], off
	s_nop 0
	global_load_dwordx4 v[4:7], v[4:5], off
	s_nop 0
	global_load_dwordx4 v[0:3], v[16:17], off
	v_lshl_add_u64 v[16:17], v[192:193], 0, v[34:35]
	v_lshl_add_u64 v[18:19], v[192:193], 0, v[38:39]
	v_lshl_add_u64 v[20:21], v[192:193], 0, v[42:43]
	v_lshl_add_u64 v[22:23], v[192:193], 0, v[46:47]
	v_lshlrev_b64 v[16:17], 5, v[16:17]
	v_lshlrev_b64 v[18:19], 5, v[18:19]
	v_lshlrev_b64 v[20:21], 5, v[20:21]
	v_lshlrev_b64 v[22:23], 5, v[22:23]
	v_lshl_add_u64 v[16:17], v[48:49], 0, v[16:17]
	v_lshl_add_u64 v[18:19], v[48:49], 0, v[18:19]
	v_lshl_add_u64 v[20:21], v[48:49], 0, v[20:21]
	v_lshl_add_u64 v[50:51], v[48:49], 0, v[22:23]
	global_load_dwordx4 v[28:31], v[16:17], off
	global_load_dwordx4 v[24:27], v[18:19], off
	s_nop 0
	global_load_dwordx4 v[20:23], v[20:21], off
	s_nop 0
	global_load_dwordx4 v[16:19], v[50:51], off
	ds_read_b128 v[50:53], v110 offset:0
	ds_read_b128 v[54:57], v110 offset:0x1000
	ds_read_b128 v[58:61], v114 offset:0
	ds_read_b128 v[62:65], v114 offset:0x1000
	s_min_u32 s4, s4, 0x80
	ds_read_b128 v[66:69], v111 offset:0
	ds_read_b128 v[70:73], v111 offset:0x1000
	ds_read_b128 v[74:77], v115 offset:0
	ds_read_b128 v[78:81], v115 offset:0x1000
	ds_read_b128 v[82:85], v112 offset:0
	ds_read_b128 v[86:89], v112 offset:0x1000
	ds_read_b128 v[90:93], v116 offset:0
	ds_read_b128 v[94:97], v116 offset:0x1000
	ds_read_b128 v[98:101], v113 offset:0
	ds_read_b128 v[102:105], v113 offset:0x1000
	ds_read_b128 v[128:131], v117 offset:0
	ds_read_b128 v[132:135], v117 offset:0x1000
	s_waitcnt lgkmcnt(12)
	s_add_i32 s6, s4, 0xc0
	v_mfma_f32_32x32x16_bf16 a[32:47], v[50:53], v[58:61], a[32:47]
	s_lshl_b32 s78, s4, 1
	v_add_u32_e32 v168, v119, v120
	v_bfe_u32 v127, v208, 6, 2
	v_lshlrev_b32_e32 v127, 4, v127
	v_xor_b32_e32 v168, v127, v168
	s_waitcnt lgkmcnt(8)
	v_add_u32_e32 v169, v121, v122
	v_bfe_u32 v127, v208, 6, 2
	v_lshlrev_b32_e32 v127, 4, v127
	v_xor_b32_e32 v169, v127, v169
	v_add_u32_e32 v170, v123, v124
	v_bfe_u32 v127, v208, 6, 2
	v_lshlrev_b32_e32 v127, 4, v127
	v_xor_b32_e32 v170, v127, v170
	v_add_u32_e32 v171, v125, v126
	v_bfe_u32 v127, v208, 6, 2
	v_lshlrev_b32_e32 v127, 4, v127
	v_xor_b32_e32 v171, v127, v171
	s_waitcnt lgkmcnt(4)
	v_mfma_f32_32x32x16_bf16 a[48:63], v[50:53], v[62:65], a[48:63]
	v_or_b32_e32 v50, s6, v118
	v_lshl_add_u64 v[52:53], v[36:37], 0, s[78:79]
	s_waitcnt lgkmcnt(0)
	s_waitcnt vmcnt(15)
	ds_write_b128 v168, v[136:139] offset:32768
	s_waitcnt vmcnt(14)
	ds_write_b128 v168, v[140:143] offset:49152
	s_waitcnt vmcnt(13)
	ds_write_b128 v169, v[144:147] offset:32768
	s_waitcnt vmcnt(12)
	ds_write_b128 v169, v[148:151] offset:49152
	s_waitcnt vmcnt(11)
	ds_write_b128 v170, v[152:155] offset:32768
	s_waitcnt vmcnt(10)
	ds_write_b128 v170, v[156:159] offset:49152
	s_waitcnt vmcnt(9)
	ds_write_b128 v171, v[160:163] offset:32768
	s_waitcnt vmcnt(8)
	ds_write_b128 v171, v[164:167] offset:49152
	s_waitcnt lgkmcnt(0)
	s_barrier
	v_mfma_f32_32x32x16_bf16 a[0:15], v[54:57], v[58:61], a[0:15]
	v_lshrrev_b32_e32 v58, 4, v50
	v_mul_u32_u24_e32 v192, 0x4200, v58
	v_lshl_add_u64 v[58:59], v[192:193], 0, v[34:35]
	v_lshl_add_u64 v[60:61], v[192:193], 0, v[38:39]
	v_lshl_add_u64 v[50:51], v[32:33], 0, s[78:79]
	v_lshlrev_b64 v[58:59], 5, v[58:59]
	v_lshlrev_b64 v[60:61], 5, v[60:61]
	v_mfma_f32_32x32x16_bf16 a[16:31], v[54:57], v[62:65], a[16:31]
	v_lshl_add_u64 v[62:63], v[192:193], 0, v[42:43]
	v_lshl_add_u64 v[64:65], v[192:193], 0, v[46:47]
	v_lshl_add_u64 v[54:55], v[40:41], 0, s[78:79]
	v_lshlrev_b64 v[62:63], 5, v[62:63]
	v_lshlrev_b64 v[64:65], 5, v[64:65]
	v_lshl_add_u64 v[56:57], v[44:45], 0, s[78:79]
	v_lshl_add_u64 v[58:59], v[48:49], 0, v[58:59]
	v_lshl_add_u64 v[60:61], v[48:49], 0, v[60:61]
	v_lshl_add_u64 v[62:63], v[48:49], 0, v[62:63]
	v_lshl_add_u64 v[64:65], v[48:49], 0, v[64:65]
	global_load_dwordx4 v[136:139], v[50:51], off offset:384
	global_load_dwordx4 v[140:143], v[58:59], off
	global_load_dwordx4 v[144:147], v[52:53], off offset:384
	global_load_dwordx4 v[148:151], v[60:61], off
	global_load_dwordx4 v[152:155], v[54:55], off offset:384
	global_load_dwordx4 v[156:159], v[62:63], off
	global_load_dwordx4 v[160:163], v[56:57], off offset:384
	global_load_dwordx4 v[164:167], v[64:65], off
	v_mfma_f32_32x32x16_bf16 a[32:47], v[66:69], v[74:77], a[32:47]
	ds_read_b128 v[50:53], v110 offset:0x8000
	ds_read_b128 v[54:57], v110 offset:0x9000
	ds_read_b128 v[58:61], v114 offset:0x8000
	ds_read_b128 v[62:65], v114 offset:0x9000
	s_add_i32 s3, s3, 2
	s_mov_b32 s4, s5
	s_cmp_lt_u32 s3, 4
	v_mfma_f32_32x32x16_bf16 a[48:63], v[66:69], v[78:81], a[48:63]
	ds_read_b128 v[66:69], v111 offset:0x8000
	v_mfma_f32_32x32x16_bf16 a[0:15], v[70:73], v[74:77], a[0:15]
	v_mfma_f32_32x32x16_bf16 a[16:31], v[70:73], v[78:81], a[16:31]
	ds_read_b128 v[70:73], v111 offset:0x9000
	ds_read_b128 v[74:77], v115 offset:0x8000
	ds_read_b128 v[78:81], v115 offset:0x9000
	v_mfma_f32_32x32x16_bf16 a[32:47], v[82:85], v[90:93], a[32:47]
	v_mfma_f32_32x32x16_bf16 a[48:63], v[82:85], v[94:97], a[48:63]
	ds_read_b128 v[82:85], v112 offset:0x8000
	v_mfma_f32_32x32x16_bf16 a[0:15], v[86:89], v[90:93], a[0:15]
	v_mfma_f32_32x32x16_bf16 a[16:31], v[86:89], v[94:97], a[16:31]
	ds_read_b128 v[86:89], v112 offset:0x9000
	ds_read_b128 v[90:93], v116 offset:0x8000
	ds_read_b128 v[94:97], v116 offset:0x9000
	v_mfma_f32_32x32x16_bf16 a[32:47], v[98:101], v[128:131], a[32:47]
	v_mfma_f32_32x32x16_bf16 a[48:63], v[98:101], v[132:135], a[48:63]
	ds_read_b128 v[98:101], v113 offset:0x8000
	v_mfma_f32_32x32x16_bf16 a[0:15], v[102:105], v[128:131], a[0:15]
	v_mfma_f32_32x32x16_bf16 a[16:31], v[102:105], v[132:135], a[16:31]
	ds_read_b128 v[102:105], v113 offset:0x9000
	ds_read_b128 v[128:131], v117 offset:0x8000
	ds_read_b128 v[132:135], v117 offset:0x9000
	s_waitcnt lgkmcnt(12)
	s_waitcnt lgkmcnt(8)
	s_waitcnt lgkmcnt(4)
	s_nop 0
	v_mfma_f32_32x32x16_bf16 a[32:47], v[50:53], v[58:61], a[32:47]
	s_waitcnt lgkmcnt(0)
	s_waitcnt vmcnt(15)
	ds_write_b128 v168, v[8:11]
	s_waitcnt vmcnt(11)
	ds_write_b128 v168, v[28:31] offset:16384
	ds_write_b128 v169, v[12:15]
	s_waitcnt vmcnt(10)
	ds_write_b128 v169, v[24:27] offset:16384
	ds_write_b128 v170, v[4:7]
	s_waitcnt vmcnt(9)
	ds_write_b128 v170, v[20:23] offset:16384
	ds_write_b128 v171, v[0:3]
	s_waitcnt vmcnt(8)
	ds_write_b128 v171, v[16:19] offset:16384
	s_waitcnt lgkmcnt(0)
	s_barrier
	v_mfma_f32_32x32x16_bf16 a[48:63], v[50:53], v[62:65], a[48:63]
	v_mfma_f32_32x32x16_bf16 a[0:15], v[54:57], v[58:61], a[0:15]
	v_mfma_f32_32x32x16_bf16 a[16:31], v[54:57], v[62:65], a[16:31]
	v_mfma_f32_32x32x16_bf16 a[32:47], v[66:69], v[74:77], a[32:47]
	v_mfma_f32_32x32x16_bf16 a[48:63], v[66:69], v[78:81], a[48:63]
	v_mfma_f32_32x32x16_bf16 a[0:15], v[70:73], v[74:77], a[0:15]
	v_mfma_f32_32x32x16_bf16 a[16:31], v[70:73], v[78:81], a[16:31]
	v_mfma_f32_32x32x16_bf16 a[32:47], v[82:85], v[90:93], a[32:47]
	v_mfma_f32_32x32x16_bf16 a[48:63], v[82:85], v[94:97], a[48:63]
	v_mfma_f32_32x32x16_bf16 a[0:15], v[86:89], v[90:93], a[0:15]
	v_mfma_f32_32x32x16_bf16 a[16:31], v[86:89], v[94:97], a[16:31]
	v_mfma_f32_32x32x16_bf16 a[32:47], v[98:101], v[128:131], a[32:47]
	v_mfma_f32_32x32x16_bf16 a[48:63], v[98:101], v[132:135], a[48:63]
	v_mfma_f32_32x32x16_bf16 a[0:15], v[102:105], v[128:131], a[0:15]
	v_mfma_f32_32x32x16_bf16 a[16:31], v[102:105], v[132:135], a[16:31]
	s_cbranch_scc1 .LBB0_243
	s_branch .LBB0_235

.LBB0_252:
	s_add_i32 s0, s6, 0xfffffe20
	s_lshr_b32 s4, s0, 1
	s_bfe_u32 s2, s0, 0x70001
	s_lshl_b32 s0, s0, 5
	s_and_b32 s0, s0, 0x7fffe000
	s_or_b32 s78, s0, s2
	s_waitcnt vmcnt(7)
	v_mov_b32_e32 v36, v208
	s_lshl_b64 s[0:1], s[78:79], 10
	v_readlane_b32 s8, v254, 1
	v_readlane_b32 s9, v254, 2
	v_lshlrev_b32_e32 v1, 7, v36
	s_add_u32 s0, s8, s0
	v_and_b32_e32 v39, 0x2f80, v1
	v_ashrrev_i32_e32 v1, 1, v36
	s_addc_u32 s1, s9, s1
	s_lshl_b32 s2, s2, 15
	v_readlane_b32 s8, v253, 36
	v_and_b32_e32 v37, 31, v36
	v_and_b32_e32 v38, 0xffffffc0, v1
	v_ashrrev_i32_e32 v72, 3, v36
	v_readlane_b32 s9, v253, 37
	s_add_u32 s2, s8, s2
	v_lshrrev_b32_e32 v0, 5, v36
	v_and_b32_e32 v5, 7, v36
	v_or_b32_e32 v1, v38, v37
	v_ashrrev_i32_e32 v73, 31, v72
	s_addc_u32 s3, s9, 0
	v_lshl_add_u32 v100, v1, 7, v214
	v_bitop3_b32 v6, v0, v5, 1 bitop3:0x6c
	v_lshlrev_b64 v[0:1], 8, v[72:73]
	v_lshlrev_b32_e32 v3, 4, v36
	v_lshl_add_u64 v[0:1], s[2:3], 0, v[0:1]
	v_and_b32_e32 v192, 0x70, v3
	v_lshl_add_u64 v[32:33], v[0:1], 0, v[192:193]
	global_load_dwordx4 v[40:43], v[32:33], off
	s_mov_b32 s5, s79
	s_lshl_b64 s[4:5], s[4:5], 16
	v_readlane_b32 s7, v254, 5
	s_add_u32 s4, s7, s4
	v_readlane_b32 s7, v254, 6
	v_ashrrev_i32_e32 v74, 4, v36
	s_addc_u32 s5, s7, s5
	s_lshl_b32 s7, s6, 7
	v_ashrrev_i32_e32 v75, 31, v74
	s_and_b32 s7, s7, 0x80
	v_lshlrev_b32_e32 v2, 3, v36
	v_lshlrev_b64 v[0:1], 9, v[74:75]
	v_add_u32_e32 v7, 0x100, v36
	v_lshl_add_u64 v[0:1], s[4:5], 0, v[0:1]
	s_lshl_b32 s78, s7, 1
	v_and_b32_e32 v73, 0x78, v2
	v_ashrrev_i32_e32 v76, 3, v7
	v_lshl_add_u64 v[0:1], v[0:1], 0, s[78:79]
	v_lshlrev_b32_e32 v2, 1, v73
	v_mov_b32_e32 v3, v193
	v_ashrrev_i32_e32 v77, 31, v76
	v_lshl_add_u64 v[12:13], v[0:1], 0, v[2:3]
	v_lshlrev_b64 v[0:1], 8, v[76:77]
	v_bfe_u32 v4, v36, 5, 1
	v_lshl_add_u64 v[0:1], s[2:3], 0, v[0:1]
	v_lshl_add_u64 v[34:35], v[0:1], 0, v[192:193]
	v_bitop3_b32 v0, v4, v5, 2 bitop3:0x36
	v_lshlrev_b32_e32 v77, 4, v0
	v_bitop3_b32 v0, v4, v5, 4 bitop3:0x36
	v_ashrrev_i32_e32 v78, 4, v7
	v_lshlrev_b32_e32 v101, 4, v0
	v_bitop3_b32 v0, v4, v5, 6 bitop3:0x36
	v_ashrrev_i32_e32 v79, 31, v78
	v_lshlrev_b32_e32 v102, 4, v0
	v_lshlrev_b64 v[0:1], 9, v[78:79]
	v_add_u32_e32 v4, 0x200, v36
	v_lshl_add_u64 v[0:1], s[4:5], 0, v[0:1]
	v_ashrrev_i32_e32 v80, 3, v4
	v_lshl_add_u64 v[0:1], v[0:1], 0, s[78:79]
	v_ashrrev_i32_e32 v81, 31, v80
	v_lshl_add_u64 v[14:15], v[0:1], 0, v[2:3]
	v_lshlrev_b64 v[0:1], 8, v[80:81]
	v_ashrrev_i32_e32 v84, 4, v4
	v_lshl_add_u64 v[0:1], s[2:3], 0, v[0:1]
	v_ashrrev_i32_e32 v85, 31, v84
	v_lshl_add_u64 v[82:83], v[0:1], 0, v[192:193]
	v_lshlrev_b64 v[0:1], 9, v[84:85]
	v_add_u32_e32 v8, 0x300, v36
	v_lshl_add_u64 v[0:1], s[4:5], 0, v[0:1]
	v_ashrrev_i32_e32 v86, 3, v8
	v_lshl_add_u64 v[0:1], v[0:1], 0, s[78:79]
	v_ashrrev_i32_e32 v87, 31, v86
	v_lshl_add_u64 v[24:25], v[0:1], 0, v[2:3]
	v_lshlrev_b64 v[0:1], 8, v[86:87]
	v_ashrrev_i32_e32 v90, 4, v8
	v_lshl_add_u64 v[0:1], s[2:3], 0, v[0:1]
	v_ashrrev_i32_e32 v91, 31, v90
	v_lshl_add_u64 v[88:89], v[0:1], 0, v[192:193]
	v_lshlrev_b64 v[0:1], 9, v[90:91]
	v_lshl_add_u64 v[0:1], s[4:5], 0, v[0:1]
	v_lshl_add_u64 v[0:1], v[0:1], 0, s[78:79]
	v_lshl_add_u64 v[26:27], v[0:1], 0, v[2:3]
	v_xor_b32_e32 v0, v72, v36
	v_lshlrev_b32_e32 v0, 4, v0
	v_and_b32_e32 v0, 0x70, v0
	global_load_dwordx4 v[44:47], v[34:35], off
	global_load_dwordx4 v[48:51], v[12:13], off
	v_lshlrev_b32_e32 v75, 4, v6
	global_load_dwordx4 v[4:7], v[34:35], off offset:128
	global_load_dwordx4 v[52:55], v[14:15], off
	global_load_dwordx4 v[16:19], v[32:33], off offset:128
	global_load_dwordx4 v[56:59], v[82:83], off
	global_load_dwordx4 v[8:11], v[82:83], off offset:128
	v_lshl_or_b32 v134, v72, 7, v0
	v_bfe_u32 v182, v208, 6, 2
	v_lshlrev_b32_e32 v182, 4, v182
	v_xor_b32_e32 v134, v182, v134
	global_load_dwordx4 v[60:63], v[88:89], off
	global_load_dwordx4 v[64:67], v[24:25], off
	global_load_dwordx4 v[0:3], v[88:89], off offset:128
	global_load_dwordx4 v[68:71], v[26:27], off
	s_mov_b32 s2, 0x8000
	v_add_co_u32_e32 v92, vcc, s2, v12
	s_movk_i32 s3, 0x50
	s_nop 0
	v_addc_co_u32_e32 v93, vcc, 0, v13, vcc
	v_add_co_u32_e32 v94, vcc, s2, v14
	s_movk_i32 s4, 0x60
	s_nop 0
	v_addc_co_u32_e32 v95, vcc, 0, v15, vcc
	v_add_co_u32_e32 v96, vcc, s2, v24
	global_load_dwordx4 v[28:31], v[92:93], off
	global_load_dwordx4 v[20:23], v[94:95], off
	v_addc_co_u32_e32 v97, vcc, 0, v25, vcc
	v_add_co_u32_e32 v98, vcc, s2, v26
	s_movk_i32 s2, 0x70
	s_nop 0
	v_addc_co_u32_e32 v99, vcc, 0, v27, vcc
	global_load_dwordx4 v[24:27], v[96:97], off
	global_load_dwordx4 v[12:15], v[98:99], off
	s_waitcnt vmcnt(15)
	ds_write_b128 v134, v[40:43]
	v_lshlrev_b32_e32 v40, 1, v74
	v_lshlrev_b32_e32 v41, 7, v73
	v_and_b32_e32 v42, -16, v72
	v_and_b32_e32 v40, 14, v40
	v_add_u32_e32 v43, v41, v42
	v_or_b32_e32 v135, v43, v40
	v_xad_u32 v43, v42, 16, v41
	v_or_b32_e32 v136, v43, v40
	v_xad_u32 v43, v42, 32, v41
	v_or_b32_e32 v137, v43, v40
	v_xad_u32 v43, v42, 48, v41
	v_or_b32_e32 v138, v43, v40
	v_xad_u32 v43, v42, 64, v41
	v_or_b32_e32 v139, v43, v40
	v_xad_u32 v43, v42, s3, v41
	v_or_b32_e32 v140, v43, v40
	v_xad_u32 v43, v42, s4, v41
	v_xad_u32 v42, v42, s2, v41
	v_or_b32_e32 v141, v43, v40
	v_or_b32_e32 v142, v42, v40
	v_xor_b32_e32 v40, v76, v36
	v_lshlrev_b32_e32 v40, 4, v40
	v_and_b32_e32 v40, 0x70, v40
	v_lshl_or_b32 v146, v76, 7, v40
	v_bfe_u32 v182, v208, 6, 2
	v_lshlrev_b32_e32 v182, 4, v182
	v_xor_b32_e32 v146, v182, v146
	v_lshlrev_b32_e32 v40, 1, v78
	v_and_b32_e32 v42, -16, v76
	v_and_b32_e32 v40, 14, v40
	v_add_u32_e32 v43, v41, v42
	v_or_b32_e32 v147, v43, v40
	v_xad_u32 v43, v42, 16, v41
	v_or_b32_e32 v148, v43, v40
	v_xad_u32 v43, v42, 32, v41
	v_or_b32_e32 v149, v43, v40
	v_xad_u32 v43, v42, 48, v41
	v_or_b32_e32 v150, v43, v40
	v_xad_u32 v43, v42, 64, v41
	v_or_b32_e32 v151, v43, v40
	v_xad_u32 v43, v42, s3, v41
	v_or_b32_e32 v152, v43, v40
	v_xad_u32 v43, v42, s4, v41
	v_xad_u32 v42, v42, s2, v41
	v_or_b32_e32 v153, v43, v40
	v_or_b32_e32 v154, v42, v40
	v_xor_b32_e32 v40, v80, v36
	v_lshlrev_b32_e32 v40, 4, v40
	v_and_b32_e32 v40, 0x70, v40
	v_lshl_or_b32 v156, v80, 7, v40
	v_bfe_u32 v182, v208, 6, 2
	v_lshlrev_b32_e32 v182, 4, v182
	v_xor_b32_e32 v156, v182, v156
	v_lshlrev_b32_e32 v40, 1, v84
	v_and_b32_e32 v42, -16, v80
	v_and_b32_e32 v40, 14, v40
	v_add_u32_e32 v43, v41, v42
	v_or_b32_e32 v157, v43, v40
	v_xad_u32 v43, v42, 16, v41
	v_or_b32_e32 v158, v43, v40
	v_xad_u32 v43, v42, 32, v41
	v_or_b32_e32 v159, v43, v40
	v_xad_u32 v43, v42, 48, v41
	v_or_b32_e32 v160, v43, v40
	v_xad_u32 v43, v42, 64, v41
	v_or_b32_e32 v161, v43, v40
	v_xad_u32 v43, v42, s3, v41
	v_or_b32_e32 v162, v43, v40
	v_xad_u32 v43, v42, s4, v41
	v_xad_u32 v42, v42, s2, v41
	v_or_b32_e32 v163, v43, v40
	v_or_b32_e32 v164, v42, v40
	v_xor_b32_e32 v40, v86, v36
	v_lshlrev_b32_e32 v40, 4, v40
	v_and_b32_e32 v40, 0x70, v40
	v_lshl_or_b32 v165, v86, 7, v40
	v_bfe_u32 v182, v208, 6, 2
	v_lshlrev_b32_e32 v182, 4, v182
	v_xor_b32_e32 v165, v182, v165
	v_lshlrev_b32_e32 v40, 1, v90
	v_and_b32_e32 v42, -16, v86
	v_and_b32_e32 v40, 14, v40
	v_add_u32_e32 v43, v41, v42
	v_or_b32_e32 v166, v43, v40
	v_xad_u32 v43, v42, 16, v41
	v_or_b32_e32 v167, v43, v40
	v_xad_u32 v43, v42, 32, v41
	v_or_b32_e32 v168, v43, v40
	v_xad_u32 v43, v42, 48, v41
	v_or_b32_e32 v169, v43, v40
	v_xad_u32 v43, v42, 64, v41
	v_or_b32_e32 v170, v43, v40
	v_xad_u32 v43, v42, s3, v41
	v_or_b32_e32 v171, v43, v40
	v_xad_u32 v43, v42, s4, v41
	v_xad_u32 v41, v42, s2, v41
	v_or_b32_e32 v172, v43, v40
	v_or_b32_e32 v173, v41, v40
	v_and_b32_e32 v175, 7, v208
	v_lshlrev_b32_e32 v175, 4, v175
	v_bfe_u32 v176, v208, 3, 2
	v_lshlrev_b32_e32 v176, 4, v176
	v_xor_b32_e32 v135, v175, v135
	v_xor_b32_e32 v136, v175, v136
	v_xor_b32_e32 v137, v175, v137
	v_xor_b32_e32 v138, v175, v138
	v_xor_b32_e32 v139, v175, v139
	v_xor_b32_e32 v140, v175, v140
	v_xor_b32_e32 v141, v175, v141
	v_xor_b32_e32 v142, v175, v142
	v_xor_b32_e32 v147, v175, v147
	v_xor_b32_e32 v148, v175, v148
	v_xor_b32_e32 v149, v175, v149
	v_xor_b32_e32 v150, v175, v150
	v_xor_b32_e32 v151, v175, v151
	v_xor_b32_e32 v152, v175, v152
	v_xor_b32_e32 v153, v175, v153
	v_xor_b32_e32 v154, v175, v154
	v_xor_b32_e32 v157, v175, v157
	v_xor_b32_e32 v158, v175, v158
	v_xor_b32_e32 v159, v175, v159
	v_xor_b32_e32 v160, v175, v160
	v_xor_b32_e32 v161, v175, v161
	v_xor_b32_e32 v162, v175, v162
	v_xor_b32_e32 v163, v175, v163
	v_xor_b32_e32 v164, v175, v164
	v_xor_b32_e32 v166, v175, v166
	v_xor_b32_e32 v167, v175, v167
	v_xor_b32_e32 v168, v175, v168
	v_xor_b32_e32 v169, v175, v169
	v_xor_b32_e32 v170, v175, v170
	v_xor_b32_e32 v171, v175, v171
	v_xor_b32_e32 v172, v175, v172
	v_xor_b32_e32 v173, v175, v173
	s_waitcnt vmcnt(13)
	ds_write_b16 v135, v48 offset:16384
	ds_write_b16_d16_hi v136, v48 offset:16512
	ds_write_b16 v137, v49 offset:16640
	ds_write_b16_d16_hi v138, v49 offset:16768
	ds_write_b16 v139, v50 offset:16896
	ds_write_b16_d16_hi v140, v50 offset:17024
	ds_write_b16 v141, v51 offset:17152
	ds_write_b16_d16_hi v142, v51 offset:17280
	ds_write_b128 v146, v[44:47]
	s_waitcnt vmcnt(11)
	ds_write_b16 v147, v52 offset:16384
	ds_write_b16_d16_hi v148, v52 offset:16512
	ds_write_b16 v149, v53 offset:16640
	ds_write_b16_d16_hi v150, v53 offset:16768
	ds_write_b16 v151, v54 offset:16896
	ds_write_b16_d16_hi v152, v54 offset:17024
	ds_write_b16 v153, v55 offset:17152
	ds_write_b16_d16_hi v154, v55 offset:17280
	s_waitcnt vmcnt(9)
	ds_write_b128 v156, v[56:59]
	s_waitcnt vmcnt(6)
	ds_write_b16 v157, v64 offset:16384
	ds_write_b16_d16_hi v158, v64 offset:16512
	ds_write_b16 v159, v65 offset:16640
	ds_write_b16_d16_hi v160, v65 offset:16768
	ds_write_b16 v161, v66 offset:16896
	ds_write_b16_d16_hi v162, v66 offset:17024
	ds_write_b16 v163, v67 offset:17152
	ds_write_b16_d16_hi v164, v67 offset:17280
	ds_write_b128 v165, v[60:63]
	s_waitcnt vmcnt(4)
	ds_write_b16 v166, v68 offset:16384
	ds_write_b16_d16_hi v167, v68 offset:16512
	ds_write_b16 v168, v69 offset:16640
	ds_write_b16_d16_hi v169, v69 offset:16768
	ds_write_b16 v170, v70 offset:16896
	ds_write_b16_d16_hi v171, v70 offset:17024
	ds_write_b16 v172, v71 offset:17152
	ds_write_b16_d16_hi v173, v71 offset:17280
	s_waitcnt lgkmcnt(0)
	s_barrier
	global_load_dwordx4 v[40:43], v[32:33], off offset:128
	s_nop 0
	global_load_dwordx4 v[32:35], v[34:35], off offset:128
	s_nop 0
	global_load_dwordx4 v[44:47], v[82:83], off offset:128
	global_load_dwordx4 v[48:51], v[88:89], off offset:128
	global_load_dwordx4 v[52:55], v[92:93], off
	global_load_dwordx4 v[56:59], v[94:95], off
	global_load_dwordx4 v[60:63], v[96:97], off
	global_load_dwordx4 v[64:67], v[98:99], off
	v_or_b32_e32 v132, v100, v75
	v_xor_b32_e32 v132, v176, v132
	v_xor_b32_e32 v177, 64, v132
	v_or_b32_e32 v143, v75, v39
	v_bfe_u32 v182, v208, 3, 2
	v_lshlrev_b32_e32 v182, 4, v182
	v_xor_b32_e32 v143, v182, v143
	v_or_b32_e32 v144, v101, v39
	v_bfe_u32 v182, v208, 3, 2
	v_lshlrev_b32_e32 v182, 4, v182
	v_xor_b32_e32 v144, v182, v144
	v_or_b32_e32 v145, v100, v77
	v_xor_b32_e32 v145, v176, v145
	v_xor_b32_e32 v180, 64, v145
	v_or_b32_e32 v155, v102, v39
	v_bfe_u32 v182, v208, 3, 2
	v_lshlrev_b32_e32 v182, 4, v182
	v_xor_b32_e32 v155, v182, v155
	v_or_b32_e32 v39, v77, v39
	v_bfe_u32 v182, v208, 3, 2
	v_lshlrev_b32_e32 v182, 4, v182
	v_xor_b32_e32 v39, v182, v39
	ds_read_b128 v[68:71], v143 offset:0
	ds_read_b128 v[72:75], v143 offset:0x1000
	ds_read_b128 v[76:79], v132 offset:0
	ds_read_b128 v[80:83], v177 offset:0x1000
	v_or_b32_e32 v133, v100, v101
	v_xor_b32_e32 v133, v176, v133
	v_xor_b32_e32 v178, 64, v133
	v_or_b32_e32 v174, v100, v102
	v_xor_b32_e32 v174, v176, v174
	v_xor_b32_e32 v181, 64, v174
	ds_read_b128 v[84:87], v39 offset:0
	ds_read_b128 v[88:91], v39 offset:0x1000
	ds_read_b128 v[92:95], v145 offset:0
	ds_read_b128 v[96:99], v180 offset:0x1000
	ds_read_b128 v[100:103], v144 offset:0
	ds_read_b128 v[104:107], v144 offset:0x1000
	ds_read_b128 v[108:111], v133 offset:0
	ds_read_b128 v[112:115], v178 offset:0x1000
	ds_read_b128 v[116:119], v155 offset:0
	ds_read_b128 v[120:123], v155 offset:0x1000
	ds_read_b128 v[124:127], v174 offset:0
	ds_read_b128 v[128:131], v181 offset:0x1000
	s_waitcnt lgkmcnt(12)
	s_nop 0
	v_mfma_f32_32x32x16_bf16 a[48:63], v[68:71], v[76:79], 0
	s_waitcnt lgkmcnt(8)
	s_waitcnt lgkmcnt(4)
	s_waitcnt lgkmcnt(0)
	ds_write_b128 v134, v[16:19] offset:32768
	s_waitcnt vmcnt(11)
	ds_write_b16 v135, v28 offset:49152
	ds_write_b16_d16_hi v136, v28 offset:49280
	ds_write_b16 v137, v29 offset:49408
	ds_write_b16_d16_hi v138, v29 offset:49536
	ds_write_b16 v139, v30 offset:49664
	ds_write_b16_d16_hi v140, v30 offset:49792
	ds_write_b16 v141, v31 offset:49920
	ds_write_b16_d16_hi v142, v31 offset:50048
	ds_write_b128 v146, v[4:7] offset:32768
	s_waitcnt vmcnt(10)
	ds_write_b16 v147, v20 offset:49152
	ds_write_b16_d16_hi v148, v20 offset:49280
	ds_write_b16 v149, v21 offset:49408
	ds_write_b16_d16_hi v150, v21 offset:49536
	ds_write_b16 v151, v22 offset:49664
	ds_write_b16_d16_hi v152, v22 offset:49792
	ds_write_b16 v153, v23 offset:49920
	ds_write_b16_d16_hi v154, v23 offset:50048
	ds_write_b128 v156, v[8:11] offset:32768
	s_waitcnt vmcnt(9)
	ds_write_b16 v157, v24 offset:49152
	ds_write_b16_d16_hi v158, v24 offset:49280
	ds_write_b16 v159, v25 offset:49408
	ds_write_b16_d16_hi v160, v25 offset:49536
	ds_write_b16 v161, v26 offset:49664
	ds_write_b16_d16_hi v162, v26 offset:49792
	ds_write_b16 v163, v27 offset:49920
	ds_write_b16_d16_hi v164, v27 offset:50048
	ds_write_b128 v165, v[0:3] offset:32768
	s_waitcnt vmcnt(8)
	ds_write_b16 v166, v12 offset:49152
	ds_write_b16_d16_hi v167, v12 offset:49280
	ds_write_b16 v168, v13 offset:49408
	ds_write_b16_d16_hi v169, v13 offset:49536
	ds_write_b16 v170, v14 offset:49664
	ds_write_b16_d16_hi v171, v14 offset:49792
	ds_write_b16 v172, v15 offset:49920
	ds_write_b16_d16_hi v173, v15 offset:50048
	s_waitcnt lgkmcnt(0)
	s_barrier
	v_mfma_f32_32x32x16_bf16 a[48:63], v[84:87], v[92:95], a[48:63]
	ds_read_b128 v[0:3], v143 offset:0x8000
	ds_read_b128 v[4:7], v143 offset:0x9000
	ds_read_b128 v[8:11], v132 offset:0x8000
	ds_read_b128 v[12:15], v177 offset:0x9000
	ds_read_b128 v[16:19], v39 offset:0x8000
	ds_read_b128 v[20:23], v39 offset:0x9000
	ds_read_b128 v[24:27], v145 offset:0x8000
	v_mfma_f32_32x32x16_bf16 a[48:63], v[100:103], v[108:111], a[48:63]
	ds_read_b128 v[28:31], v180 offset:0x9000
	v_mfma_f32_32x32x16_bf16 a[32:47], v[68:71], v[80:83], 0
	ds_read_b128 v[68:71], v144 offset:0x8000
	v_mfma_f32_32x32x16_bf16 a[16:31], v[72:75], v[76:79], 0
	v_mfma_f32_32x32x16_bf16 a[0:15], v[72:75], v[80:83], 0
	ds_read_b128 v[72:75], v144 offset:0x9000
	ds_read_b128 v[76:79], v133 offset:0x8000
	ds_read_b128 v[80:83], v178 offset:0x9000
	v_mfma_f32_32x32x16_bf16 a[48:63], v[116:119], v[124:127], a[48:63]
	v_mfma_f32_32x32x16_bf16 a[32:47], v[84:87], v[96:99], a[32:47]
	ds_read_b128 v[84:87], v155 offset:0x8000
	v_mfma_f32_32x32x16_bf16 a[16:31], v[88:91], v[92:95], a[16:31]
	v_mfma_f32_32x32x16_bf16 a[0:15], v[88:91], v[96:99], a[0:15]
	ds_read_b128 v[88:91], v155 offset:0x9000
	ds_read_b128 v[92:95], v174 offset:0x8000
	ds_read_b128 v[96:99], v181 offset:0x9000
	s_waitcnt lgkmcnt(12)
	s_waitcnt lgkmcnt(8)
	s_waitcnt lgkmcnt(4)
	s_nop 0
	v_mfma_f32_32x32x16_bf16 a[48:63], v[0:3], v[8:11], a[48:63]
	s_waitcnt lgkmcnt(0)
	s_waitcnt vmcnt(7)
	ds_write_b128 v134, v[40:43]
	s_waitcnt vmcnt(3)
	ds_write_b16 v135, v52 offset:16384
	ds_write_b16_d16_hi v136, v52 offset:16512
	ds_write_b16 v137, v53 offset:16640
	ds_write_b16_d16_hi v138, v53 offset:16768
	ds_write_b16 v139, v54 offset:16896
	ds_write_b16_d16_hi v140, v54 offset:17024
	ds_write_b16 v141, v55 offset:17152
	ds_write_b16_d16_hi v142, v55 offset:17280
	ds_write_b128 v146, v[32:35]
	s_waitcnt vmcnt(2)
	ds_write_b16 v147, v56 offset:16384
	ds_write_b16_d16_hi v148, v56 offset:16512
	ds_write_b16 v149, v57 offset:16640
	ds_write_b16_d16_hi v150, v57 offset:16768
	ds_write_b16 v151, v58 offset:16896
	ds_write_b16_d16_hi v152, v58 offset:17024
	ds_write_b16 v153, v59 offset:17152
	ds_write_b16_d16_hi v154, v59 offset:17280
	ds_write_b128 v156, v[44:47]
	s_waitcnt vmcnt(1)
	ds_write_b16 v157, v60 offset:16384
	ds_write_b16_d16_hi v158, v60 offset:16512
	ds_write_b16 v159, v61 offset:16640
	ds_write_b16_d16_hi v160, v61 offset:16768
	ds_write_b16 v161, v62 offset:16896
	ds_write_b16_d16_hi v162, v62 offset:17024
	ds_write_b16 v163, v63 offset:17152
	ds_write_b16_d16_hi v164, v63 offset:17280
	ds_write_b128 v165, v[48:51]
	s_waitcnt vmcnt(0)
	ds_write_b16 v166, v64 offset:16384
	ds_write_b16_d16_hi v167, v64 offset:16512
	ds_write_b16 v168, v65 offset:16640
	ds_write_b16_d16_hi v169, v65 offset:16768
	ds_write_b16 v170, v66 offset:16896
	ds_write_b16_d16_hi v171, v66 offset:17024
	ds_write_b16 v172, v67 offset:17152
	ds_write_b16_d16_hi v173, v67 offset:17280
	s_waitcnt lgkmcnt(0)
	s_barrier
	v_mfma_f32_32x32x16_bf16 a[48:63], v[16:19], v[24:27], a[48:63]
	v_mfma_f32_32x32x16_bf16 a[32:47], v[100:103], v[112:115], a[32:47]
	v_mfma_f32_32x32x16_bf16 a[48:63], v[68:71], v[76:79], a[48:63]
	v_mfma_f32_32x32x16_bf16 a[16:31], v[104:107], v[108:111], a[16:31]
	v_mfma_f32_32x32x16_bf16 a[0:15], v[104:107], v[112:115], a[0:15]
	v_mfma_f32_32x32x16_bf16 a[32:47], v[116:119], v[128:131], a[32:47]
	v_mfma_f32_32x32x16_bf16 a[48:63], v[84:87], v[92:95], a[48:63]
	v_mfma_f32_32x32x16_bf16 a[16:31], v[120:123], v[124:127], a[16:31]
	v_mfma_f32_32x32x16_bf16 a[0:15], v[120:123], v[128:131], a[0:15]
	v_mfma_f32_32x32x16_bf16 a[32:47], v[0:3], v[12:15], a[32:47]
	v_and_b32_e32 v0, 64, v36
	v_lshrrev_b32_e32 v1, 3, v36
	v_and_or_b32 v2, v1, 4, v0
	v_or_b32_e32 v0, s7, v37
	v_add_u32_e32 v0, v0, v38
	s_nop 3
	v_accvgpr_read_b32 v3, a48
	v_ashrrev_i32_e32 v1, 31, v0
	v_lshlrev_b32_e32 v192, 16, v2
	v_mul_f32_e32 v2, 0x3ab504f3, v3
	v_lshl_add_u64 v[0:1], v[0:1], 1, s[0:1]
	v_bfe_u32 v3, v2, 16, 1
	v_mfma_f32_32x32x16_bf16 a[16:31], v[4:7], v[8:11], a[16:31]
	v_add3_u32 v2, v2, v3, s80
	s_mov_b32 s0, 0x20000
	v_accvgpr_read_b32 v8, a51
	v_accvgpr_read_b32 v10, a52
	v_mul_f32_e32 v10, 0x3ab504f3, v10
	v_mov_b32_e32 v9, v193
	v_accvgpr_read_b32 v11, a53
	v_mfma_f32_32x32x16_bf16 a[0:15], v[4:7], v[12:15], a[0:15]
	v_accvgpr_read_b32 v6, a49
	v_lshl_add_u64 v[4:5], v[0:1], 0, v[192:193]
	global_store_short_d16_hi v[4:5], v2, off
	v_mul_f32_e32 v2, 0x3ab504f3, v6
	v_bfe_u32 v3, v2, 16, 1
	v_accvgpr_read_b32 v7, a50
	v_add3_u32 v2, v2, v3, s80
	global_store_short_d16_hi v[4:5], v2, off offset:512
	v_mul_f32_e32 v2, 0x3ab504f3, v7
	v_bfe_u32 v3, v2, 16, 1
	v_add_co_u32_e32 v6, vcc, s0, v4
	v_add3_u32 v2, v2, v3, s80
	s_nop 0
	v_addc_co_u32_e32 v7, vcc, 0, v5, vcc
	global_store_short_d16_hi v[6:7], v2, off
	v_mul_f32_e32 v2, 0x3ab504f3, v8
	v_bfe_u32 v3, v2, 16, 1
	v_add3_u32 v2, v2, v3, s80
	v_or_b32_e32 v8, 0x80000, v192
	v_bfe_u32 v14, v10, 16, 1
	global_store_short_d16_hi v[6:7], v2, off offset:512
	v_lshl_add_u64 v[2:3], v[0:1], 0, v[8:9]
	v_add3_u32 v10, v10, v14, s80
	global_store_short_d16_hi v[2:3], v10, off
	v_mul_f32_e32 v10, 0x3ab504f3, v11
	v_bfe_u32 v11, v10, 16, 1
	v_accvgpr_read_b32 v12, a54
	v_add3_u32 v10, v10, v11, s80
	global_store_short_d16_hi v[2:3], v10, off offset:512
	v_mul_f32_e32 v10, 0x3ab504f3, v12
	v_bfe_u32 v11, v10, 16, 1
	v_add_co_u32_e32 v2, vcc, s0, v2
	v_accvgpr_read_b32 v13, a55
	v_add3_u32 v10, v10, v11, s80
	v_addc_co_u32_e32 v3, vcc, 0, v3, vcc
	global_store_short_d16_hi v[2:3], v10, off
	v_mul_f32_e32 v10, 0x3ab504f3, v13
	v_mfma_f32_32x32x16_bf16 a[32:47], v[16:19], v[28:31], a[32:47]
	v_bfe_u32 v11, v10, 16, 1
	v_accvgpr_read_b32 v12, a56
	v_add3_u32 v10, v10, v11, s80
	v_mul_f32_e32 v12, 0x3ab504f3, v12
	global_store_short_d16_hi v[2:3], v10, off offset:512
	v_or_b32_e32 v10, 0x100000, v192
	v_mov_b32_e32 v11, v193
	v_bfe_u32 v16, v12, 16, 1
	v_accvgpr_read_b32 v13, a57
	v_lshl_add_u64 v[2:3], v[0:1], 0, v[10:11]
	v_add3_u32 v12, v12, v16, s80
	global_store_short_d16_hi v[2:3], v12, off
	v_mul_f32_e32 v12, 0x3ab504f3, v13
	v_bfe_u32 v13, v12, 16, 1
	v_accvgpr_read_b32 v14, a58
	v_add3_u32 v12, v12, v13, s80
	global_store_short_d16_hi v[2:3], v12, off offset:512
	v_mul_f32_e32 v12, 0x3ab504f3, v14
	v_mfma_f32_32x32x16_bf16 a[32:47], v[68:71], v[80:83], a[32:47]
	v_bfe_u32 v13, v12, 16, 1
	v_add_co_u32_e32 v2, vcc, s0, v2
	v_accvgpr_read_b32 v15, a59
	v_add3_u32 v12, v12, v13, s80
	v_addc_co_u32_e32 v3, vcc, 0, v3, vcc
	global_store_short_d16_hi v[2:3], v12, off
	v_mul_f32_e32 v12, 0x3ab504f3, v15
	v_bfe_u32 v13, v12, 16, 1
	v_accvgpr_read_b32 v14, a60
	v_add3_u32 v12, v12, v13, s80
	v_mul_f32_e32 v14, 0x3ab504f3, v14
	global_store_short_d16_hi v[2:3], v12, off offset:512
	v_or_b32_e32 v12, 0x180000, v192
	v_mov_b32_e32 v13, v193
	v_bfe_u32 v18, v14, 16, 1
	v_accvgpr_read_b32 v15, a61
	v_lshl_add_u64 v[2:3], v[0:1], 0, v[12:13]
	v_add3_u32 v14, v14, v18, s80
	global_store_short_d16_hi v[2:3], v14, off
	v_mul_f32_e32 v14, 0x3ab504f3, v15
	v_mfma_f32_32x32x16_bf16 a[32:47], v[84:87], v[96:99], a[32:47]
	v_bfe_u32 v15, v14, 16, 1
	v_accvgpr_read_b32 v16, a62
	v_add3_u32 v14, v14, v15, s80
	global_store_short_d16_hi v[2:3], v14, off offset:512
	v_mul_f32_e32 v14, 0x3ab504f3, v16
	v_bfe_u32 v15, v14, 16, 1
	v_add_co_u32_e32 v2, vcc, s0, v2
	v_accvgpr_read_b32 v17, a63
	v_add3_u32 v14, v14, v15, s80
	v_addc_co_u32_e32 v3, vcc, 0, v3, vcc
	global_store_short_d16_hi v[2:3], v14, off
	v_mul_f32_e32 v14, 0x3ab504f3, v17
	v_bfe_u32 v15, v14, 16, 1
	v_add3_u32 v14, v14, v15, s80
	global_store_short_d16_hi v[2:3], v14, off offset:512
	v_accvgpr_read_b32 v14, a32
	v_mul_f32_e32 v14, 0x3ab504f3, v14
	v_bfe_u32 v18, v14, 16, 1
	v_accvgpr_read_b32 v15, a33
	v_add3_u32 v14, v14, v18, s80
	global_store_short_d16_hi v[4:5], v14, off offset:64
	v_mul_f32_e32 v14, 0x3ab504f3, v15
	v_bfe_u32 v15, v14, 16, 1
	v_accvgpr_read_b32 v16, a34
	v_add3_u32 v14, v14, v15, s80
	global_store_short_d16_hi v[4:5], v14, off offset:576
	v_mul_f32_e32 v4, 0x3ab504f3, v16
	v_bfe_u32 v5, v4, 16, 1
	v_accvgpr_read_b32 v17, a35
	v_add3_u32 v4, v4, v5, s80
	global_store_short_d16_hi v[6:7], v4, off offset:64
	v_mul_f32_e32 v4, 0x3ab504f3, v17
	v_bfe_u32 v5, v4, 16, 1
	v_add3_u32 v4, v4, v5, s80
	global_store_short_d16_hi v[6:7], v4, off offset:576
	v_accvgpr_read_b32 v6, a36
	v_lshl_add_u64 v[2:3], v[0:1], 0, 64
	v_mul_f32_e32 v6, 0x3ab504f3, v6
	v_lshl_add_u64 v[4:5], v[2:3], 0, v[8:9]
	v_bfe_u32 v8, v6, 16, 1
	v_accvgpr_read_b32 v7, a37
	v_add3_u32 v6, v6, v8, s80
	global_store_short_d16_hi v[4:5], v6, off
	v_mul_f32_e32 v6, 0x3ab504f3, v7
	v_bfe_u32 v7, v6, 16, 1
	v_accvgpr_read_b32 v14, a38
	v_add3_u32 v6, v6, v7, s80
	global_store_short_d16_hi v[4:5], v6, off offset:512
	v_mul_f32_e32 v6, 0x3ab504f3, v14
	v_bfe_u32 v7, v6, 16, 1
	v_add_co_u32_e32 v4, vcc, s0, v4
	v_accvgpr_read_b32 v15, a39
	v_add3_u32 v6, v6, v7, s80
	v_addc_co_u32_e32 v5, vcc, 0, v5, vcc
	global_store_short_d16_hi v[4:5], v6, off
	v_mul_f32_e32 v6, 0x3ab504f3, v15
	v_bfe_u32 v7, v6, 16, 1
	v_add3_u32 v6, v6, v7, s80
	v_mfma_f32_32x32x16_bf16 a[16:31], v[20:23], v[24:27], a[16:31]
	global_store_short_d16_hi v[4:5], v6, off offset:512
	v_accvgpr_read_b32 v6, a40
	v_mul_f32_e32 v6, 0x3ab504f3, v6
	v_lshl_add_u64 v[4:5], v[2:3], 0, v[10:11]
	v_bfe_u32 v10, v6, 16, 1
	v_accvgpr_read_b32 v7, a41
	v_add3_u32 v6, v6, v10, s80
	global_store_short_d16_hi v[4:5], v6, off
	v_mul_f32_e32 v6, 0x3ab504f3, v7
	v_bfe_u32 v7, v6, 16, 1
	v_accvgpr_read_b32 v8, a42
	v_add3_u32 v6, v6, v7, s80
	global_store_short_d16_hi v[4:5], v6, off offset:512
	v_mul_f32_e32 v6, 0x3ab504f3, v8
	v_mfma_f32_32x32x16_bf16 a[16:31], v[72:75], v[76:79], a[16:31]
	v_bfe_u32 v7, v6, 16, 1
	v_add_co_u32_e32 v4, vcc, s0, v4
	v_accvgpr_read_b32 v9, a43
	v_add3_u32 v6, v6, v7, s80
	v_addc_co_u32_e32 v5, vcc, 0, v5, vcc
	global_store_short_d16_hi v[4:5], v6, off
	v_mul_f32_e32 v6, 0x3ab504f3, v9
	v_bfe_u32 v7, v6, 16, 1
	v_add3_u32 v6, v6, v7, s80
	global_store_short_d16_hi v[4:5], v6, off offset:512
	v_accvgpr_read_b32 v6, a44
	v_mul_f32_e32 v6, 0x3ab504f3, v6
	v_bfe_u32 v10, v6, 16, 1
	v_mfma_f32_32x32x16_bf16 a[16:31], v[88:91], v[92:95], a[16:31]
	v_accvgpr_read_b32 v7, a45
	v_lshl_add_u64 v[4:5], v[2:3], 0, v[12:13]
	v_add3_u32 v6, v6, v10, s80
	global_store_short_d16_hi v[4:5], v6, off
	v_mul_f32_e32 v6, 0x3ab504f3, v7
	v_bfe_u32 v7, v6, 16, 1
	v_accvgpr_read_b32 v8, a46
	v_add3_u32 v6, v6, v7, s80
	global_store_short_d16_hi v[4:5], v6, off offset:512
	v_mul_f32_e32 v6, 0x3ab504f3, v8
	v_bfe_u32 v7, v6, 16, 1
	v_add_co_u32_e32 v4, vcc, s0, v4
	v_accvgpr_read_b32 v9, a47
	v_add3_u32 v6, v6, v7, s80
	v_addc_co_u32_e32 v5, vcc, 0, v5, vcc
	global_store_short_d16_hi v[4:5], v6, off
	v_mul_f32_e32 v6, 0x3ab504f3, v9
	v_bfe_u32 v7, v6, 16, 1
	v_accvgpr_read_b32 v8, a16
	v_add3_u32 v6, v6, v7, s80
	v_mul_f32_e32 v8, 0x3ab504f3, v8
	global_store_short_d16_hi v[4:5], v6, off offset:512
	v_or_b32_e32 v4, 0x200000, v192
	v_mov_b32_e32 v5, v193
	v_bfe_u32 v12, v8, 16, 1
	v_accvgpr_read_b32 v9, a17
	v_lshl_add_u64 v[6:7], v[0:1], 0, v[4:5]
	v_add3_u32 v8, v8, v12, s80
	global_store_short_d16_hi v[6:7], v8, off
	v_mul_f32_e32 v8, 0x3ab504f3, v9
	v_bfe_u32 v9, v8, 16, 1
	v_accvgpr_read_b32 v10, a18
	v_add3_u32 v8, v8, v9, s80
	global_store_short_d16_hi v[6:7], v8, off offset:512
	v_mul_f32_e32 v8, 0x3ab504f3, v10
	v_bfe_u32 v9, v8, 16, 1
	v_add_co_u32_e32 v6, vcc, s0, v6
	v_accvgpr_read_b32 v11, a19
	v_add3_u32 v8, v8, v9, s80
	v_addc_co_u32_e32 v7, vcc, 0, v7, vcc
	global_store_short_d16_hi v[6:7], v8, off
	v_mul_f32_e32 v8, 0x3ab504f3, v11
	v_bfe_u32 v9, v8, 16, 1
	v_accvgpr_read_b32 v10, a20
	v_add3_u32 v8, v8, v9, s80
	v_mul_f32_e32 v10, 0x3ab504f3, v10
	global_store_short_d16_hi v[6:7], v8, off offset:512
	v_or_b32_e32 v6, 0x280000, v192
	v_mov_b32_e32 v7, v193
	v_bfe_u32 v14, v10, 16, 1
	v_accvgpr_read_b32 v11, a21
	v_lshl_add_u64 v[8:9], v[0:1], 0, v[6:7]
	v_add3_u32 v10, v10, v14, s80
	global_store_short_d16_hi v[8:9], v10, off
	v_mul_f32_e32 v10, 0x3ab504f3, v11
	v_bfe_u32 v11, v10, 16, 1
	v_accvgpr_read_b32 v12, a22
	v_add3_u32 v10, v10, v11, s80
	global_store_short_d16_hi v[8:9], v10, off offset:512
	v_mul_f32_e32 v10, 0x3ab504f3, v12
	v_bfe_u32 v11, v10, 16, 1
	v_add_co_u32_e32 v8, vcc, s0, v8
	v_accvgpr_read_b32 v13, a23
	v_add3_u32 v10, v10, v11, s80
	v_addc_co_u32_e32 v9, vcc, 0, v9, vcc
	global_store_short_d16_hi v[8:9], v10, off
	v_mul_f32_e32 v10, 0x3ab504f3, v13
	v_bfe_u32 v11, v10, 16, 1
	v_accvgpr_read_b32 v12, a24
	v_add3_u32 v10, v10, v11, s80
	v_mul_f32_e32 v12, 0x3ab504f3, v12
	v_mfma_f32_32x32x16_bf16 a[0:15], v[20:23], v[28:31], a[0:15]
	global_store_short_d16_hi v[8:9], v10, off offset:512
	v_or_b32_e32 v8, 0x300000, v192
	v_mov_b32_e32 v9, v193
	v_bfe_u32 v16, v12, 16, 1
	v_accvgpr_read_b32 v13, a25
	v_lshl_add_u64 v[10:11], v[0:1], 0, v[8:9]
	v_add3_u32 v12, v12, v16, s80
	global_store_short_d16_hi v[10:11], v12, off
	v_mul_f32_e32 v12, 0x3ab504f3, v13
	v_bfe_u32 v13, v12, 16, 1
	v_accvgpr_read_b32 v14, a26
	v_add3_u32 v12, v12, v13, s80
	global_store_short_d16_hi v[10:11], v12, off offset:512
	v_mul_f32_e32 v12, 0x3ab504f3, v14
	v_bfe_u32 v13, v12, 16, 1
	v_add_co_u32_e32 v10, vcc, s0, v10
	v_accvgpr_read_b32 v15, a27
	v_add3_u32 v12, v12, v13, s80
	v_addc_co_u32_e32 v11, vcc, 0, v11, vcc
	v_mfma_f32_32x32x16_bf16 a[0:15], v[72:75], v[80:83], a[0:15]
	global_store_short_d16_hi v[10:11], v12, off
	v_mul_f32_e32 v12, 0x3ab504f3, v15
	v_bfe_u32 v13, v12, 16, 1
	v_add3_u32 v12, v12, v13, s80
	global_store_short_d16_hi v[10:11], v12, off offset:512
	v_accvgpr_read_b32 v10, a28
	v_mul_f32_e32 v10, 0x3ab504f3, v10
	v_or_b32_e32 v192, 0x380000, v192
	v_bfe_u32 v14, v10, 16, 1
	v_accvgpr_read_b32 v11, a29
	v_lshl_add_u64 v[0:1], v[0:1], 0, v[192:193]
	v_add3_u32 v10, v10, v14, s80
	global_store_short_d16_hi v[0:1], v10, off
	v_mul_f32_e32 v10, 0x3ab504f3, v11
	v_mfma_f32_32x32x16_bf16 a[0:15], v[88:91], v[96:99], a[0:15]
	v_bfe_u32 v11, v10, 16, 1
	v_accvgpr_read_b32 v12, a30
	v_add3_u32 v10, v10, v11, s80
	global_store_short_d16_hi v[0:1], v10, off offset:512
	v_mul_f32_e32 v10, 0x3ab504f3, v12
	v_bfe_u32 v11, v10, 16, 1
	v_add_co_u32_e32 v0, vcc, s0, v0
	v_accvgpr_read_b32 v13, a31
	v_add3_u32 v10, v10, v11, s80
	v_addc_co_u32_e32 v1, vcc, 0, v1, vcc
	global_store_short_d16_hi v[0:1], v10, off
	v_mul_f32_e32 v10, 0x3ab504f3, v13
	v_bfe_u32 v11, v10, 16, 1
	v_add3_u32 v10, v10, v11, s80
	global_store_short_d16_hi v[0:1], v10, off offset:512
	v_accvgpr_read_b32 v10, a0
	v_lshl_add_u64 v[0:1], v[2:3], 0, v[4:5]
	v_mul_f32_e32 v4, 0x3ab504f3, v10
	v_bfe_u32 v5, v4, 16, 1
	v_accvgpr_read_b32 v11, a1
	v_add3_u32 v4, v4, v5, s80
	global_store_short_d16_hi v[0:1], v4, off
	v_mul_f32_e32 v4, 0x3ab504f3, v11
	v_bfe_u32 v5, v4, 16, 1
	v_accvgpr_read_b32 v12, a2
	v_add3_u32 v4, v4, v5, s80
	global_store_short_d16_hi v[0:1], v4, off offset:512
	v_mul_f32_e32 v4, 0x3ab504f3, v12
	v_bfe_u32 v5, v4, 16, 1
	v_add_co_u32_e32 v0, vcc, s0, v0
	v_accvgpr_read_b32 v13, a3
	v_add3_u32 v4, v4, v5, s80
	v_addc_co_u32_e32 v1, vcc, 0, v1, vcc
	global_store_short_d16_hi v[0:1], v4, off
	v_mul_f32_e32 v4, 0x3ab504f3, v13
	v_bfe_u32 v5, v4, 16, 1
	v_add3_u32 v4, v4, v5, s80
	global_store_short_d16_hi v[0:1], v4, off offset:512
	v_accvgpr_read_b32 v4, a4
	v_mul_f32_e32 v4, 0x3ab504f3, v4
	v_lshl_add_u64 v[0:1], v[2:3], 0, v[6:7]
	v_bfe_u32 v6, v4, 16, 1
	v_accvgpr_read_b32 v5, a5
	v_add3_u32 v4, v4, v6, s80
	global_store_short_d16_hi v[0:1], v4, off
	v_mul_f32_e32 v4, 0x3ab504f3, v5
	v_bfe_u32 v5, v4, 16, 1
	v_accvgpr_read_b32 v10, a6
	v_add3_u32 v4, v4, v5, s80
	global_store_short_d16_hi v[0:1], v4, off offset:512
	v_mul_f32_e32 v4, 0x3ab504f3, v10
	v_bfe_u32 v5, v4, 16, 1
	v_add_co_u32_e32 v0, vcc, s0, v0
	v_accvgpr_read_b32 v11, a7
	v_add3_u32 v4, v4, v5, s80
	v_addc_co_u32_e32 v1, vcc, 0, v1, vcc
	global_store_short_d16_hi v[0:1], v4, off
	v_mul_f32_e32 v4, 0x3ab504f3, v11
	v_bfe_u32 v5, v4, 16, 1
	v_add3_u32 v4, v4, v5, s80
	global_store_short_d16_hi v[0:1], v4, off offset:512
	v_accvgpr_read_b32 v4, a8
	v_mul_f32_e32 v4, 0x3ab504f3, v4
	v_lshl_add_u64 v[0:1], v[2:3], 0, v[8:9]
	v_bfe_u32 v8, v4, 16, 1
	v_accvgpr_read_b32 v5, a9
	v_add3_u32 v4, v4, v8, s80
	global_store_short_d16_hi v[0:1], v4, off
	v_mul_f32_e32 v4, 0x3ab504f3, v5
	v_bfe_u32 v5, v4, 16, 1
	v_accvgpr_read_b32 v6, a10
	v_add3_u32 v4, v4, v5, s80
	global_store_short_d16_hi v[0:1], v4, off offset:512
	v_mul_f32_e32 v4, 0x3ab504f3, v6
	v_bfe_u32 v5, v4, 16, 1
	v_add_co_u32_e32 v0, vcc, s0, v0
	v_accvgpr_read_b32 v7, a11
	v_add3_u32 v4, v4, v5, s80
	v_addc_co_u32_e32 v1, vcc, 0, v1, vcc
	global_store_short_d16_hi v[0:1], v4, off
	v_mul_f32_e32 v4, 0x3ab504f3, v7
	v_bfe_u32 v5, v4, 16, 1
	v_add3_u32 v4, v4, v5, s80
	global_store_short_d16_hi v[0:1], v4, off offset:512
	v_accvgpr_read_b32 v4, a12
	v_lshl_add_u64 v[0:1], v[2:3], 0, v[192:193]
	v_mul_f32_e32 v2, 0x3ab504f3, v4
	v_bfe_u32 v3, v2, 16, 1
	v_accvgpr_read_b32 v5, a13
	v_add3_u32 v2, v2, v3, s80
	global_store_short_d16_hi v[0:1], v2, off
	v_mul_f32_e32 v2, 0x3ab504f3, v5
	v_bfe_u32 v3, v2, 16, 1
	v_accvgpr_read_b32 v6, a14
	v_add3_u32 v2, v2, v3, s80
	global_store_short_d16_hi v[0:1], v2, off offset:512
	v_mul_f32_e32 v2, 0x3ab504f3, v6
	v_bfe_u32 v3, v2, 16, 1
	v_add_co_u32_e32 v0, vcc, 0x20000, v0
	v_accvgpr_read_b32 v7, a15
	v_add3_u32 v2, v2, v3, s80
	v_addc_co_u32_e32 v1, vcc, 0, v1, vcc
	global_store_short_d16_hi v[0:1], v2, off
	v_mul_f32_e32 v2, 0x3ab504f3, v7
	v_bfe_u32 v3, v2, 16, 1
	v_add3_u32 v2, v2, v3, s80
	global_store_short_d16_hi v[0:1], v2, off offset:512
	s_cbranch_execnz .LBB0_249
.LBB0_253:
	s_mul_hi_i32 s0, s6, 0x66666667
	s_lshr_b32 s1, s0, 31
	s_ashr_i32 s0, s0, 3
	s_add_i32 s7, s0, s1
	s_mul_i32 s0, s7, 20
	s_sub_i32 s5, s6, s0
	s_mul_i32 s1, s7, 0xc0000
	v_readlane_b32 s2, v253, 18
	s_mul_hi_i32 s0, s7, 0xc0000
	v_readlane_b32 s3, v253, 19
	s_add_u32 s2, s2, s1
	s_waitcnt vmcnt(0)
	v_mov_b32_e32 v64, v208
	s_addc_u32 s3, s3, s0
	s_mul_i32 s0, s7, 0xc6000
	v_readlane_b32 s8, v254, 7
	s_mul_hi_i32 s1, s7, 0xc6000
	v_ashrrev_i32_e32 v4, 1, v64
	v_readlane_b32 s9, v254, 8
	s_add_u32 s0, s8, s0
	v_and_b32_e32 v65, 31, v64
	v_lshrrev_b32_e32 v0, 5, v64
	v_bfe_u32 v1, v64, 5, 1
	v_and_b32_e32 v2, 7, v64
	v_and_b32_e32 v66, 0xffffffc0, v4
	s_addc_u32 s1, s9, s1
	s_lshl_b32 s4, s5, 7
	s_lshl_b32 s5, s5, 5
	v_lshlrev_b32_e32 v3, 7, v64
	v_or_b32_e32 v4, v66, v65
	v_bitop3_b32 v0, v0, v2, 1 bitop3:0x6c
	v_bitop3_b32 v5, v1, v2, 2 bitop3:0x36
	v_bitop3_b32 v6, v1, v2, 4 bitop3:0x36
	v_bitop3_b32 v1, v1, v2, 6 bitop3:0x36
	s_and_b32 s4, s4, 0x180
	s_and_b32 s5, s5, 0xffffff80
	v_and_b32_e32 v3, 0x2f80, v3
	v_lshl_add_u32 v4, v4, 7, v214
	v_lshlrev_b32_e32 v0, 4, v0
	v_lshlrev_b32_e32 v5, 4, v5
	v_lshlrev_b32_e32 v6, 4, v6
	v_lshlrev_b32_e32 v1, 4, v1
	v_ashrrev_i32_e32 v57, 3, v64
	v_or_b32_e32 v48, v0, v3
	v_bfe_u32 v132, v208, 3, 2
	v_lshlrev_b32_e32 v132, 4, v132
	v_xor_b32_e32 v48, v132, v48
	v_or_b32_e32 v52, v4, v0
	v_bfe_u32 v132, v208, 3, 2
	v_lshlrev_b32_e32 v132, 4, v132
	v_xor_b32_e32 v52, v132, v52
	v_or_b32_e32 v53, v4, v5
	v_bfe_u32 v132, v208, 3, 2
	v_lshlrev_b32_e32 v132, 4, v132
	v_xor_b32_e32 v53, v132, v53
	v_or_b32_e32 v54, v4, v6
	v_bfe_u32 v132, v208, 3, 2
	v_lshlrev_b32_e32 v132, 4, v132
	v_xor_b32_e32 v54, v132, v54
	v_or_b32_e32 v55, v4, v1
	v_bfe_u32 v132, v208, 3, 2
	v_lshlrev_b32_e32 v132, 4, v132
	v_xor_b32_e32 v55, v132, v55
	v_add_u32_e32 v0, s4, v57
	v_mov_b64_e32 v[24:25], s[2:3]
	v_lshlrev_b32_e32 v2, 4, v64
	v_add_u32_e32 v4, s5, v57
	v_or_b32_e32 v51, v1, v3
	v_bfe_u32 v132, v208, 3, 2
	v_lshlrev_b32_e32 v132, 4, v132
	v_xor_b32_e32 v51, v132, v51
	v_mad_i64_i32 v[0:1], s[2:3], v0, s68, v[24:25]
	v_and_b32_e32 v192, 0x70, v2
	v_min_i32_e32 v4, 0x20f, v4
	v_mov_b64_e32 v[28:29], s[0:1]
	v_or_b32_e32 v49, v5, v3
	v_bfe_u32 v132, v208, 3, 2
	v_lshlrev_b32_e32 v132, 4, v132
	v_xor_b32_e32 v49, v132, v49
	v_lshl_add_u64 v[32:33], v[0:1], 0, v[192:193]
	v_mad_i64_i32 v[4:5], s[0:1], v4, s68, v[28:29]
	v_add_u32_e32 v8, 0x100, v64
	v_or_b32_e32 v50, v6, v3
	v_bfe_u32 v132, v208, 3, 2
	v_lshlrev_b32_e32 v132, 4, v132
	v_xor_b32_e32 v50, v132, v50
	global_load_dwordx4 v[0:3], v[32:33], off
	v_lshl_add_u64 v[34:35], v[4:5], 0, v[192:193]
	v_ashrrev_i32_e32 v59, 3, v8
	global_load_dwordx4 v[4:7], v[34:35], off
	v_add_u32_e32 v8, s4, v59
	v_add_u32_e32 v12, s5, v59
	v_mad_i64_i32 v[8:9], s[0:1], v8, s68, v[24:25]
	v_min_i32_e32 v12, 0x20f, v12
	v_lshl_add_u64 v[36:37], v[8:9], 0, v[192:193]
	v_mad_i64_i32 v[12:13], s[0:1], v12, s68, v[28:29]
	v_add_u32_e32 v16, 0x200, v64
	global_load_dwordx4 v[8:11], v[36:37], off
	v_lshl_add_u64 v[38:39], v[12:13], 0, v[192:193]
	v_ashrrev_i32_e32 v61, 3, v16
	global_load_dwordx4 v[12:15], v[38:39], off
	v_add_u32_e32 v16, s4, v61
	v_add_u32_e32 v20, s5, v61
	v_mad_i64_i32 v[16:17], s[0:1], v16, s68, v[24:25]
	v_min_i32_e32 v20, 0x20f, v20
	v_lshl_add_u64 v[40:41], v[16:17], 0, v[192:193]
	v_mad_i64_i32 v[20:21], s[0:1], v20, s68, v[28:29]
	v_add_u32_e32 v26, 0x300, v64
	global_load_dwordx4 v[16:19], v[40:41], off
	v_lshl_add_u64 v[42:43], v[20:21], 0, v[192:193]
	v_ashrrev_i32_e32 v63, 3, v26
	global_load_dwordx4 v[20:23], v[42:43], off
	v_add_u32_e32 v26, s4, v63
	v_mad_i64_i32 v[24:25], s[0:1], v26, s68, v[24:25]
	v_lshl_add_u64 v[44:45], v[24:25], 0, v[192:193]
	global_load_dwordx4 v[24:27], v[44:45], off
	v_add_u32_e32 v30, s5, v63
	v_min_i32_e32 v30, 0x20f, v30
	v_mad_i64_i32 v[28:29], s[0:1], v30, s68, v[28:29]
	v_lshl_add_u64 v[46:47], v[28:29], 0, v[192:193]
	global_load_dwordx4 v[28:31], v[46:47], off
	global_load_dwordx4 v[138:141], v[32:33], off offset:128
	global_load_dwordx4 v[142:145], v[34:35], off offset:128
	global_load_dwordx4 v[146:149], v[36:37], off offset:128
	global_load_dwordx4 v[150:153], v[38:39], off offset:128
	global_load_dwordx4 v[154:157], v[40:41], off offset:128
	global_load_dwordx4 v[158:161], v[42:43], off offset:128
	global_load_dwordx4 v[162:165], v[44:45], off offset:128
	global_load_dwordx4 v[166:169], v[46:47], off offset:128
	v_lshlrev_b32_e32 v56, 7, v57
	v_xor_b32_e32 v57, v57, v64
	v_lshlrev_b32_e32 v57, 4, v57
	v_and_b32_e32 v57, 0x70, v57
	v_or_b32_e32 v58, v56, v57
	v_bfe_u32 v132, v208, 6, 2
	v_lshlrev_b32_e32 v132, 4, v132
	v_xor_b32_e32 v58, v132, v58
	s_waitcnt vmcnt(15)
	ds_write_b128 v58, v[0:3]
	s_waitcnt vmcnt(14)
	ds_write_b128 v58, v[4:7] offset:16384
	v_xor_b32_e32 v0, v59, v64
	v_lshlrev_b32_e32 v0, 4, v0
	v_lshlrev_b32_e32 v58, 7, v59
	v_and_b32_e32 v59, 0x70, v0
	v_or_b32_e32 v0, v58, v59
	v_bfe_u32 v132, v208, 6, 2
	v_lshlrev_b32_e32 v132, 4, v132
	v_xor_b32_e32 v0, v132, v0
	s_waitcnt vmcnt(13)
	ds_write_b128 v0, v[8:11]
	s_waitcnt vmcnt(12)
	ds_write_b128 v0, v[12:15] offset:16384
	v_xor_b32_e32 v0, v61, v64
	v_lshlrev_b32_e32 v0, 4, v0
	v_lshlrev_b32_e32 v60, 7, v61
	v_and_b32_e32 v61, 0x70, v0
	v_or_b32_e32 v0, v60, v61
	v_bfe_u32 v132, v208, 6, 2
	v_lshlrev_b32_e32 v132, 4, v132
	v_xor_b32_e32 v0, v132, v0
	s_waitcnt vmcnt(11)
	ds_write_b128 v0, v[16:19]
	s_waitcnt vmcnt(10)
	ds_write_b128 v0, v[20:23] offset:16384
	v_xor_b32_e32 v0, v63, v64
	v_lshlrev_b32_e32 v0, 4, v0
	v_lshlrev_b32_e32 v62, 7, v63
	v_and_b32_e32 v63, 0x70, v0
	v_or_b32_e32 v0, v62, v63
	v_bfe_u32 v132, v208, 6, 2
	v_lshlrev_b32_e32 v132, 4, v132
	v_xor_b32_e32 v0, v132, v0
	v_accvgpr_write_b32 a47, 0
	v_accvgpr_write_b32 a46, 0
	v_accvgpr_write_b32 a45, 0
	v_accvgpr_write_b32 a44, 0
	v_accvgpr_write_b32 a43, 0
	v_accvgpr_write_b32 a42, 0
	v_accvgpr_write_b32 a41, 0
	v_accvgpr_write_b32 a40, 0
	v_accvgpr_write_b32 a39, 0
	v_accvgpr_write_b32 a38, 0
	v_accvgpr_write_b32 a37, 0
	v_accvgpr_write_b32 a36, 0
	v_accvgpr_write_b32 a35, 0
	v_accvgpr_write_b32 a34, 0
	v_accvgpr_write_b32 a33, 0
	v_accvgpr_write_b32 a32, 0
	v_accvgpr_write_b32 a63, 0
	v_accvgpr_write_b32 a62, 0
	v_accvgpr_write_b32 a61, 0
	v_accvgpr_write_b32 a60, 0
	v_accvgpr_write_b32 a59, 0
	v_accvgpr_write_b32 a58, 0
	v_accvgpr_write_b32 a57, 0
	v_accvgpr_write_b32 a56, 0
	v_accvgpr_write_b32 a55, 0
	v_accvgpr_write_b32 a54, 0
	v_accvgpr_write_b32 a53, 0
	v_accvgpr_write_b32 a52, 0
	v_accvgpr_write_b32 a51, 0
	v_accvgpr_write_b32 a50, 0
	v_accvgpr_write_b32 a49, 0
	v_accvgpr_write_b32 a48, 0
	v_accvgpr_write_b32 a15, 0
	v_accvgpr_write_b32 a14, 0
	v_accvgpr_write_b32 a13, 0
	v_accvgpr_write_b32 a12, 0
	v_accvgpr_write_b32 a11, 0
	v_accvgpr_write_b32 a10, 0
	v_accvgpr_write_b32 a9, 0
	v_accvgpr_write_b32 a8, 0
	v_accvgpr_write_b32 a7, 0
	v_accvgpr_write_b32 a6, 0
	v_accvgpr_write_b32 a5, 0
	v_accvgpr_write_b32 a4, 0
	v_accvgpr_write_b32 a3, 0
	v_accvgpr_write_b32 a2, 0
	v_accvgpr_write_b32 a1, 0
	v_accvgpr_write_b32 a0, 0
	v_accvgpr_write_b32 a31, 0
	v_accvgpr_write_b32 a30, 0
	v_accvgpr_write_b32 a29, 0
	v_accvgpr_write_b32 a28, 0
	v_accvgpr_write_b32 a27, 0
	v_accvgpr_write_b32 a26, 0
	v_accvgpr_write_b32 a25, 0
	v_accvgpr_write_b32 a24, 0
	v_accvgpr_write_b32 a23, 0
	v_accvgpr_write_b32 a22, 0
	v_accvgpr_write_b32 a21, 0
	v_accvgpr_write_b32 a20, 0
	v_accvgpr_write_b32 a19, 0
	v_accvgpr_write_b32 a18, 0
	v_accvgpr_write_b32 a17, 0
	v_accvgpr_write_b32 a16, 0
	s_mov_b32 s0, -2
	s_mov_b32 s1, 0
	s_waitcnt vmcnt(9)
	ds_write_b128 v0, v[24:27]
	s_waitcnt vmcnt(8)
	ds_write_b128 v0, v[28:31] offset:16384
	s_waitcnt lgkmcnt(0)
	s_barrier
.LBB0_254:
	s_add_i32 s2, s1, 0x80
	s_min_u32 s3, s2, 0x2c0
	s_lshl_b32 s78, s3, 1
	v_lshl_add_u64 v[0:1], v[32:33], 0, s[78:79]
	v_lshl_add_u64 v[4:5], v[34:35], 0, s[78:79]
	v_lshl_add_u64 v[8:9], v[36:37], 0, s[78:79]
	v_lshl_add_u64 v[12:13], v[38:39], 0, s[78:79]
	v_lshl_add_u64 v[16:17], v[40:41], 0, s[78:79]
	v_lshl_add_u64 v[20:21], v[42:43], 0, s[78:79]
	v_lshl_add_u64 v[24:25], v[44:45], 0, s[78:79]
	v_lshl_add_u64 v[28:29], v[46:47], 0, s[78:79]
	global_load_dwordx4 v[0:3], v[0:1], off
	s_nop 0
	global_load_dwordx4 v[4:7], v[4:5], off
	s_nop 0
	global_load_dwordx4 v[8:11], v[8:9], off
	s_nop 0
	global_load_dwordx4 v[12:15], v[12:13], off
	s_nop 0
	global_load_dwordx4 v[16:19], v[16:17], off
	s_nop 0
	global_load_dwordx4 v[20:23], v[20:21], off
	s_nop 0
	global_load_dwordx4 v[24:27], v[24:25], off
	s_nop 0
	global_load_dwordx4 v[28:31], v[28:29], off
	ds_read_b128 v[68:71], v48 offset:0
	ds_read_b128 v[72:75], v48 offset:0x1000
	ds_read_b128 v[76:79], v52 offset:0
	ds_read_b128 v[80:83], v52 offset:0x1000
	s_min_u32 s1, s1, 0x200
	ds_read_b128 v[84:87], v49 offset:0
	ds_read_b128 v[88:91], v49 offset:0x1000
	ds_read_b128 v[92:95], v53 offset:0
	ds_read_b128 v[96:99], v53 offset:0x1000
	ds_read_b128 v[100:103], v50 offset:0
	ds_read_b128 v[104:107], v50 offset:0x1000
	ds_read_b128 v[108:111], v54 offset:0
	ds_read_b128 v[112:115], v54 offset:0x1000
	ds_read_b128 v[116:119], v51 offset:0
	ds_read_b128 v[120:123], v51 offset:0x1000
	ds_read_b128 v[124:127], v55 offset:0
	ds_read_b128 v[128:131], v55 offset:0x1000
	s_waitcnt lgkmcnt(12)
	s_lshl_b32 s78, s1, 1
	v_mfma_f32_32x32x16_bf16 a[32:47], v[68:71], v[76:79], a[32:47]
	v_add_u32_e32 v67, v56, v57
	v_bfe_u32 v132, v208, 6, 2
	v_lshlrev_b32_e32 v132, 4, v132
	v_xor_b32_e32 v67, v132, v67
	s_waitcnt lgkmcnt(8)
	s_waitcnt lgkmcnt(4)
	v_add_u32_e32 v170, v58, v59
	v_bfe_u32 v132, v208, 6, 2
	v_lshlrev_b32_e32 v132, 4, v132
	v_xor_b32_e32 v170, v132, v170
	v_add_u32_e32 v171, v60, v61
	v_bfe_u32 v132, v208, 6, 2
	v_lshlrev_b32_e32 v132, 4, v132
	v_xor_b32_e32 v171, v132, v171
	v_add_u32_e32 v172, v62, v63
	v_bfe_u32 v132, v208, 6, 2
	v_lshlrev_b32_e32 v132, 4, v132
	v_xor_b32_e32 v172, v132, v172
	s_waitcnt lgkmcnt(0)
	v_mfma_f32_32x32x16_bf16 a[48:63], v[68:71], v[80:83], a[48:63]
	v_lshl_add_u64 v[68:69], v[32:33], 0, s[78:79]
	v_lshl_add_u64 v[70:71], v[34:35], 0, s[78:79]
	s_waitcnt vmcnt(15)
	ds_write_b128 v67, v[138:141] offset:32768
	s_waitcnt vmcnt(14)
	ds_write_b128 v67, v[142:145] offset:49152
	s_waitcnt vmcnt(13)
	ds_write_b128 v170, v[146:149] offset:32768
	s_waitcnt vmcnt(12)
	ds_write_b128 v170, v[150:153] offset:49152
	s_waitcnt vmcnt(11)
	ds_write_b128 v171, v[154:157] offset:32768
	s_waitcnt vmcnt(10)
	ds_write_b128 v171, v[158:161] offset:49152
	s_waitcnt vmcnt(9)
	ds_write_b128 v172, v[162:165] offset:32768
	s_waitcnt vmcnt(8)
	ds_write_b128 v172, v[166:169] offset:49152
	s_waitcnt lgkmcnt(0)
	s_barrier
	v_mfma_f32_32x32x16_bf16 a[0:15], v[72:75], v[76:79], a[0:15]
	v_lshl_add_u64 v[76:77], v[40:41], 0, s[78:79]
	v_lshl_add_u64 v[78:79], v[42:43], 0, s[78:79]
	s_add_i32 s0, s0, 2
	s_mov_b32 s1, s2
	s_cmp_gt_u32 s0, 9
	v_mfma_f32_32x32x16_bf16 a[16:31], v[72:75], v[80:83], a[16:31]
	v_lshl_add_u64 v[72:73], v[36:37], 0, s[78:79]
	v_lshl_add_u64 v[74:75], v[38:39], 0, s[78:79]
	v_lshl_add_u64 v[80:81], v[44:45], 0, s[78:79]
	v_lshl_add_u64 v[82:83], v[46:47], 0, s[78:79]
	global_load_dwordx4 v[138:141], v[68:69], off offset:384
	global_load_dwordx4 v[142:145], v[70:71], off offset:384
	global_load_dwordx4 v[146:149], v[72:73], off offset:384
	global_load_dwordx4 v[150:153], v[74:75], off offset:384
	global_load_dwordx4 v[154:157], v[76:77], off offset:384
	global_load_dwordx4 v[158:161], v[78:79], off offset:384
	global_load_dwordx4 v[162:165], v[80:81], off offset:384
	global_load_dwordx4 v[166:169], v[82:83], off offset:384
	ds_read_b128 v[68:71], v48 offset:0x8000
	v_mfma_f32_32x32x16_bf16 a[32:47], v[84:87], v[92:95], a[32:47]
	ds_read_b128 v[72:75], v48 offset:0x9000
	ds_read_b128 v[76:79], v52 offset:0x8000
	ds_read_b128 v[80:83], v52 offset:0x9000
	v_mfma_f32_32x32x16_bf16 a[48:63], v[84:87], v[96:99], a[48:63]
	ds_read_b128 v[84:87], v49 offset:0x8000
	v_mfma_f32_32x32x16_bf16 a[0:15], v[88:91], v[92:95], a[0:15]
	v_mfma_f32_32x32x16_bf16 a[16:31], v[88:91], v[96:99], a[16:31]
	ds_read_b128 v[88:91], v49 offset:0x9000
	ds_read_b128 v[92:95], v53 offset:0x8000
	ds_read_b128 v[96:99], v53 offset:0x9000
	v_mfma_f32_32x32x16_bf16 a[32:47], v[100:103], v[108:111], a[32:47]
	v_mfma_f32_32x32x16_bf16 a[48:63], v[100:103], v[112:115], a[48:63]
	ds_read_b128 v[100:103], v50 offset:0x8000
	v_mfma_f32_32x32x16_bf16 a[0:15], v[104:107], v[108:111], a[0:15]
	v_mfma_f32_32x32x16_bf16 a[16:31], v[104:107], v[112:115], a[16:31]
	ds_read_b128 v[104:107], v50 offset:0x9000
	ds_read_b128 v[108:111], v54 offset:0x8000
	ds_read_b128 v[112:115], v54 offset:0x9000
	v_mfma_f32_32x32x16_bf16 a[32:47], v[116:119], v[124:127], a[32:47]
	v_mfma_f32_32x32x16_bf16 a[48:63], v[116:119], v[128:131], a[48:63]
	ds_read_b128 v[116:119], v51 offset:0x8000
	v_mfma_f32_32x32x16_bf16 a[0:15], v[120:123], v[124:127], a[0:15]
	v_mfma_f32_32x32x16_bf16 a[16:31], v[120:123], v[128:131], a[16:31]
	ds_read_b128 v[120:123], v51 offset:0x9000
	ds_read_b128 v[124:127], v55 offset:0x8000
	ds_read_b128 v[128:131], v55 offset:0x9000
	s_waitcnt lgkmcnt(12)
	s_waitcnt lgkmcnt(8)
	s_waitcnt lgkmcnt(4)
	s_nop 0
	v_mfma_f32_32x32x16_bf16 a[32:47], v[68:71], v[76:79], a[32:47]
	s_waitcnt lgkmcnt(0)
	s_waitcnt vmcnt(15)
	ds_write_b128 v67, v[0:3]
	s_waitcnt vmcnt(14)
	ds_write_b128 v67, v[4:7] offset:16384
	s_waitcnt vmcnt(13)
	ds_write_b128 v170, v[8:11]
	s_waitcnt vmcnt(12)
	ds_write_b128 v170, v[12:15] offset:16384
	s_waitcnt vmcnt(11)
	ds_write_b128 v171, v[16:19]
	s_waitcnt vmcnt(10)
	ds_write_b128 v171, v[20:23] offset:16384
	s_waitcnt vmcnt(9)
	ds_write_b128 v172, v[24:27]
	s_waitcnt vmcnt(8)
	ds_write_b128 v172, v[28:31] offset:16384
	s_waitcnt lgkmcnt(0)
	s_barrier
	v_mfma_f32_32x32x16_bf16 a[48:63], v[68:71], v[80:83], a[48:63]
	v_mfma_f32_32x32x16_bf16 a[0:15], v[72:75], v[76:79], a[0:15]
	v_mfma_f32_32x32x16_bf16 a[16:31], v[72:75], v[80:83], a[16:31]
	v_mfma_f32_32x32x16_bf16 a[32:47], v[84:87], v[92:95], a[32:47]
	v_mfma_f32_32x32x16_bf16 a[48:63], v[84:87], v[96:99], a[48:63]
	v_mfma_f32_32x32x16_bf16 a[0:15], v[88:91], v[92:95], a[0:15]
	v_mfma_f32_32x32x16_bf16 a[16:31], v[88:91], v[96:99], a[16:31]
	v_mfma_f32_32x32x16_bf16 a[32:47], v[100:103], v[108:111], a[32:47]
	v_mfma_f32_32x32x16_bf16 a[48:63], v[100:103], v[112:115], a[48:63]
	v_mfma_f32_32x32x16_bf16 a[0:15], v[104:107], v[108:111], a[0:15]
	v_mfma_f32_32x32x16_bf16 a[16:31], v[104:107], v[112:115], a[16:31]
	v_mfma_f32_32x32x16_bf16 a[32:47], v[116:119], v[124:127], a[32:47]
	v_mfma_f32_32x32x16_bf16 a[48:63], v[116:119], v[128:131], a[48:63]
	v_mfma_f32_32x32x16_bf16 a[0:15], v[120:123], v[124:127], a[0:15]
	v_mfma_f32_32x32x16_bf16 a[16:31], v[120:123], v[128:131], a[16:31]
	s_cbranch_scc0 .LBB0_254
	v_or_b32_e32 v65, s5, v65
	v_add_u32_e32 v121, v65, v66
	v_lshrrev_b32_e32 v65, 3, v64
	s_nop 7
	v_accvgpr_read_b32 v0, a16
	v_accvgpr_read_b32 v31, a15
	v_accvgpr_read_b32 v32, a48
	v_accvgpr_read_b32 v63, a47
	v_and_b32_e32 v103, 4, v65
	v_and_or_b32 v104, v64, 64, s4
	s_movk_i32 s0, 0x210
	v_lshlrev_b32_e32 v64, 5, v121
	v_accvgpr_read_b32 v86, a16
	v_accvgpr_read_b32 v85, a17
	v_accvgpr_read_b32 v84, a18
	v_accvgpr_read_b32 v83, a19
	v_accvgpr_read_b32 v81, a20
	v_accvgpr_read_b32 v80, a21
	v_accvgpr_read_b32 v79, a22
	v_accvgpr_read_b32 v78, a23
	v_accvgpr_read_b32 v77, a24
	v_accvgpr_read_b32 v76, a25
	v_accvgpr_read_b32 v75, a26
	v_accvgpr_read_b32 v74, a27
	v_accvgpr_read_b32 v73, a28
	v_accvgpr_read_b32 v72, a29
	v_accvgpr_read_b32 v71, a30
	v_accvgpr_read_b32 v70, a31
	v_accvgpr_read_b32 v102, a0
	v_accvgpr_read_b32 v101, a1
	v_accvgpr_read_b32 v100, a2
	v_accvgpr_read_b32 v99, a3
	v_accvgpr_read_b32 v98, a4
	v_accvgpr_read_b32 v97, a5
	v_accvgpr_read_b32 v96, a6
	v_accvgpr_read_b32 v95, a7
	v_accvgpr_read_b32 v94, a8
	v_accvgpr_read_b32 v93, a9
	v_accvgpr_read_b32 v92, a10
	v_accvgpr_read_b32 v91, a11
	v_accvgpr_read_b32 v90, a12
	v_accvgpr_read_b32 v89, a13
	v_accvgpr_read_b32 v88, a14
	v_accvgpr_read_b32 v87, a15
	v_accvgpr_read_b32 v120, a48
	v_accvgpr_read_b32 v119, a49
	v_accvgpr_read_b32 v118, a50
	v_accvgpr_read_b32 v117, a51
	v_accvgpr_read_b32 v116, a52
	v_accvgpr_read_b32 v115, a53
	v_accvgpr_read_b32 v114, a54
	v_accvgpr_read_b32 v113, a55
	v_accvgpr_read_b32 v112, a56
	v_accvgpr_read_b32 v111, a57
	v_accvgpr_read_b32 v110, a58
	v_accvgpr_read_b32 v109, a59
	v_accvgpr_read_b32 v108, a60
	v_accvgpr_read_b32 v107, a61
	v_accvgpr_read_b32 v106, a62
	v_accvgpr_read_b32 v105, a63
	v_accvgpr_read_b32 v137, a32
	v_accvgpr_read_b32 v136, a33
	v_accvgpr_read_b32 v135, a34
	v_accvgpr_read_b32 v134, a35
	v_accvgpr_read_b32 v133, a36
	v_accvgpr_read_b32 v132, a37
	v_accvgpr_read_b32 v131, a38
	v_accvgpr_read_b32 v130, a39
	v_accvgpr_read_b32 v129, a40
	v_accvgpr_read_b32 v128, a41
	v_accvgpr_read_b32 v127, a42
	v_accvgpr_read_b32 v126, a43
	v_accvgpr_read_b32 v125, a44
	v_accvgpr_read_b32 v124, a45
	v_accvgpr_read_b32 v123, a46
	v_accvgpr_read_b32 v122, a47
	v_accvgpr_read_b32 v1, a17
	v_accvgpr_read_b32 v2, a18
	v_accvgpr_read_b32 v3, a19
	v_accvgpr_read_b32 v4, a20
	v_accvgpr_read_b32 v5, a21
	v_accvgpr_read_b32 v6, a22
	v_accvgpr_read_b32 v7, a23
	v_accvgpr_read_b32 v8, a24
	v_accvgpr_read_b32 v9, a25
	v_accvgpr_read_b32 v10, a26
	v_accvgpr_read_b32 v11, a27
	v_accvgpr_read_b32 v12, a28
	v_accvgpr_read_b32 v13, a29
	v_accvgpr_read_b32 v14, a30
	v_accvgpr_read_b32 v15, a31
	v_accvgpr_read_b32 v30, a14
	v_accvgpr_read_b32 v29, a13
	v_accvgpr_read_b32 v28, a12
	v_accvgpr_read_b32 v27, a11
	v_accvgpr_read_b32 v26, a10
	v_accvgpr_read_b32 v25, a9
	v_accvgpr_read_b32 v24, a8
	v_accvgpr_read_b32 v23, a7
	v_accvgpr_read_b32 v22, a6
	v_accvgpr_read_b32 v21, a5
	v_accvgpr_read_b32 v20, a4
	v_accvgpr_read_b32 v19, a3
	v_accvgpr_read_b32 v18, a2
	v_accvgpr_read_b32 v17, a1
	v_accvgpr_read_b32 v16, a0
	v_accvgpr_read_b32 v33, a49
	v_accvgpr_read_b32 v34, a50
	v_accvgpr_read_b32 v35, a51
	v_accvgpr_read_b32 v36, a52
	v_accvgpr_read_b32 v37, a53
	v_accvgpr_read_b32 v38, a54
	v_accvgpr_read_b32 v39, a55
	v_accvgpr_read_b32 v40, a56
	v_accvgpr_read_b32 v41, a57
	v_accvgpr_read_b32 v42, a58
	v_accvgpr_read_b32 v43, a59
	v_accvgpr_read_b32 v44, a60
	v_accvgpr_read_b32 v45, a61
	v_accvgpr_read_b32 v46, a62
	v_accvgpr_read_b32 v47, a63
	v_accvgpr_read_b32 v62, a46
	v_accvgpr_read_b32 v61, a45
	v_accvgpr_read_b32 v60, a44
	v_accvgpr_read_b32 v59, a43
	v_accvgpr_read_b32 v58, a42
	v_accvgpr_read_b32 v57, a41
	v_accvgpr_read_b32 v56, a40
	v_accvgpr_read_b32 v55, a39
	v_accvgpr_read_b32 v54, a38
	v_accvgpr_read_b32 v53, a37
	v_accvgpr_read_b32 v52, a36
	v_accvgpr_read_b32 v51, a35
	v_accvgpr_read_b32 v50, a34
	v_accvgpr_read_b32 v49, a33
	v_accvgpr_read_b32 v48, a32
	v_cmp_gt_i32_e64 s[2:3], s0, v121
	v_ashrrev_i32_e32 v65, 31, v64
	v_lshrrev_b32_e32 v82, 4, v104
	v_lshlrev_b32_e32 v192, 1, v103
	s_and_saveexec_b64 s[0:1], s[2:3]
	s_cbranch_execz .LBB0_257
	s_waitcnt vmcnt(7)
	v_mul_f32_e32 v138, 0x3d372713, v137
	v_mul_f32_e32 v138, v137, v138
	v_fma_f32 v137, v137, v138, v137
	v_mul_f32_e32 v137, 0x3f4c422a, v137
	v_add_f32_e32 v137, v137, v137
	v_mul_f32_e32 v137, 0x3fb8aa3b, v137
	v_exp_f32_e32 v138, v137
	v_mul_f32_e32 v137, 0x3d372713, v136
	v_mul_f32_e32 v137, v136, v137
	v_fma_f32 v136, v136, v137, v136
	v_mul_f32_e32 v137, 0x3d372713, v135
	v_mul_f32_e32 v137, v135, v137
	v_fma_f32 v135, v135, v137, v135
	v_mul_f32_e32 v135, 0x3f4c422a, v135
	v_add_f32_e32 v135, v135, v135
	v_mul_f32_e32 v135, 0x3fb8aa3b, v135
	v_exp_f32_e32 v139, v135
	v_mul_f32_e32 v135, 0x3d372713, v134
	v_mul_f32_e32 v135, v134, v135
	v_fma_f32 v134, v134, v135, v134
	v_mul_f32_e32 v134, 0x3f4c422a, v134
	v_add_f32_e32 v134, v134, v134
	v_mul_f32_e32 v134, 0x3fb8aa3b, v134
	v_exp_f32_e32 v137, v134
	v_pk_add_f32 v[134:135], v[138:139], 1.0 op_sel_hi:[1,0]
	v_mul_f32_e32 v136, 0x3f4c422a, v136
	v_rcp_f32_e32 v139, v135
	v_add_f32_e32 v136, v136, v136
	v_mul_f32_e32 v136, 0x3fb8aa3b, v136
	v_exp_f32_e32 v136, v136
	s_waitcnt vmcnt(6)
	v_mul_f32_e32 v135, 2.0, v139
	v_rcp_f32_e32 v139, v134
	v_pk_add_f32 v[136:137], v[136:137], 1.0 op_sel_hi:[1,0]
	v_mad_i64_i32 v[66:67], s[4:5], s7, v215, v[64:65]
	v_mul_f32_e32 v134, 2.0, v139
	v_mov_b32_e32 v138, v48
	v_mov_b32_e32 v139, v50
	v_rcp_f32_e32 v50, v137
	v_pk_add_f32 v[134:135], v[134:135], 1.0 op_sel_hi:[1,0] neg_lo:[1,0] neg_hi:[1,0]
	v_pk_mul_f32 v[138:139], v[138:139], 0.5 op_sel_hi:[1,0]
	v_pk_add_f32 v[134:135], v[134:135], 1.0 op_sel_hi:[1,0]
	v_or_b32_e32 v66, v82, v66
	v_pk_mul_f32 v[134:135], v[138:139], v[134:135]
	v_mul_f32_e32 v137, 2.0, v50
	v_rcp_f32_e32 v50, v136
	v_readlane_b32 s8, v254, 3
	v_lshlrev_b64 v[68:69], 5, v[66:67]
	v_readlane_b32 s9, v254, 4
	v_mul_f32_e32 v136, 2.0, v50
	v_pk_add_f32 v[136:137], v[136:137], 1.0 op_sel_hi:[1,0] neg_lo:[1,0] neg_hi:[1,0]
	v_mov_b32_e32 v50, v49
	v_pk_mul_f32 v[48:49], v[50:51], 0.5 op_sel_hi:[1,0]
	v_pk_add_f32 v[50:51], v[136:137], 1.0 op_sel_hi:[1,0]
	v_lshl_add_u64 v[68:69], s[8:9], 0, v[68:69]
	v_pk_mul_f32 v[48:49], v[48:49], v[50:51]
	v_cvt_pk_bf16_f32 v48, v134, v48
	v_cvt_pk_bf16_f32 v49, v135, v49
	v_lshl_add_u64 v[68:69], v[68:69], 0, v[192:193]
	global_store_dwordx2 v[68:69], v[48:49], off
	v_mul_f32_e32 v49, 0x3d372713, v132
	v_mul_f32_e32 v49, v132, v49
	v_fma_f32 v49, v132, v49, v132
	v_mul_f32_e32 v49, 0x3f4c422a, v49
	v_add_f32_e32 v49, v49, v49
	v_mul_f32_e32 v49, 0x3fb8aa3b, v49
	v_mul_f32_e32 v48, 0x3d372713, v133
	v_exp_f32_e32 v50, v49
	v_mul_f32_e32 v49, 0x3d372713, v131
	v_mul_f32_e32 v48, v133, v48
	v_mul_f32_e32 v49, v131, v49
	v_fma_f32 v48, v133, v48, v133
	v_fma_f32 v49, v131, v49, v131
	v_mul_f32_e32 v48, 0x3f4c422a, v48
	v_mul_f32_e32 v49, 0x3f4c422a, v49
	v_add_f32_e32 v48, v48, v48
	v_add_f32_e32 v49, v49, v49
	v_mul_f32_e32 v48, 0x3fb8aa3b, v48
	v_mul_f32_e32 v49, 0x3fb8aa3b, v49
	v_exp_f32_e32 v48, v48
	v_exp_f32_e32 v49, v49
	v_mul_f32_e32 v51, 0x3d372713, v130
	v_mul_f32_e32 v51, v130, v51
	v_fma_f32 v51, v130, v51, v130
	v_pk_add_f32 v[48:49], v[48:49], 1.0 op_sel_hi:[1,0]
	v_mul_f32_e32 v51, 0x3f4c422a, v51
	v_rcp_f32_e32 v131, v49
	v_add_f32_e32 v51, v51, v51
	v_mul_f32_e32 v51, 0x3fb8aa3b, v51
	v_exp_f32_e32 v51, v51
	v_mul_f32_e32 v49, 2.0, v131
	v_rcp_f32_e32 v131, v48
	v_pk_add_f32 v[50:51], v[50:51], 1.0 op_sel_hi:[1,0]
	v_or_b32_e32 v66, 1, v66
	v_mul_f32_e32 v48, 2.0, v131
	v_mov_b32_e32 v130, v52
	v_mov_b32_e32 v131, v54
	v_rcp_f32_e32 v54, v51
	v_pk_add_f32 v[48:49], v[48:49], 1.0 op_sel_hi:[1,0] neg_lo:[1,0] neg_hi:[1,0]
	v_pk_mul_f32 v[130:131], v[130:131], 0.5 op_sel_hi:[1,0]
	v_pk_add_f32 v[48:49], v[48:49], 1.0 op_sel_hi:[1,0]
	s_nop 0
	v_pk_mul_f32 v[48:49], v[130:131], v[48:49]
	v_mul_f32_e32 v51, 2.0, v54
	v_rcp_f32_e32 v54, v50
	s_nop 0
	v_mul_f32_e32 v50, 2.0, v54
	v_pk_add_f32 v[50:51], v[50:51], 1.0 op_sel_hi:[1,0] neg_lo:[1,0] neg_hi:[1,0]
	v_mov_b32_e32 v54, v53
	v_pk_mul_f32 v[52:53], v[54:55], 0.5 op_sel_hi:[1,0]
	v_pk_add_f32 v[50:51], v[50:51], 1.0 op_sel_hi:[1,0]
	s_nop 0
	v_pk_mul_f32 v[50:51], v[52:53], v[50:51]
	v_cvt_pk_bf16_f32 v49, v49, v51
	v_mul_f32_e32 v51, 0x3d372713, v128
	v_mul_f32_e32 v51, v128, v51
	v_cvt_pk_bf16_f32 v48, v48, v50
	v_fma_f32 v51, v128, v51, v128
	v_mul_f32_e32 v51, 0x3f4c422a, v51
	v_add_f32_e32 v51, v51, v51
	v_mul_f32_e32 v51, 0x3fb8aa3b, v51
	v_mul_f32_e32 v50, 0x3d372713, v129
	v_exp_f32_e32 v52, v51
	v_mul_f32_e32 v51, 0x3d372713, v127
	v_mul_f32_e32 v50, v129, v50
	v_mul_f32_e32 v51, v127, v51
	v_fma_f32 v50, v129, v50, v129
	v_fma_f32 v51, v127, v51, v127
	v_mul_f32_e32 v50, 0x3f4c422a, v50
	v_mul_f32_e32 v51, 0x3f4c422a, v51
	v_add_f32_e32 v50, v50, v50
	v_add_f32_e32 v51, v51, v51
	v_mul_f32_e32 v50, 0x3fb8aa3b, v50
	v_mul_f32_e32 v51, 0x3fb8aa3b, v51
	v_exp_f32_e32 v50, v50
	v_exp_f32_e32 v51, v51
	global_store_dwordx2 v[68:69], v[48:49], off offset:16
	v_lshlrev_b64 v[48:49], 5, v[66:67]
	v_mul_f32_e32 v53, 0x3d372713, v126
	v_pk_add_f32 v[50:51], v[50:51], 1.0 op_sel_hi:[1,0]
	v_mul_f32_e32 v53, v126, v53
	v_rcp_f32_e32 v55, v51
	v_fma_f32 v53, v126, v53, v126
	v_mul_f32_e32 v53, 0x3f4c422a, v53
	v_add_f32_e32 v53, v53, v53
	v_mul_f32_e32 v51, 2.0, v55
	v_rcp_f32_e32 v55, v50
	v_mul_f32_e32 v53, 0x3fb8aa3b, v53
	v_exp_f32_e32 v53, v53
	v_lshl_add_u64 v[48:49], s[8:9], 0, v[48:49]
	v_mul_f32_e32 v50, 2.0, v55
	v_pk_add_f32 v[50:51], v[50:51], 1.0 op_sel_hi:[1,0] neg_lo:[1,0] neg_hi:[1,0]
	v_mov_b32_e32 v54, v56
	v_mov_b32_e32 v55, v58
	v_pk_mul_f32 v[54:55], v[54:55], 0.5 op_sel_hi:[1,0]
	v_pk_add_f32 v[50:51], v[50:51], 1.0 op_sel_hi:[1,0]
	v_pk_add_f32 v[52:53], v[52:53], 1.0 op_sel_hi:[1,0]
	v_pk_mul_f32 v[50:51], v[54:55], v[50:51]
	v_rcp_f32_e32 v55, v53
	v_lshl_add_u64 v[48:49], v[48:49], 0, v[192:193]
	v_mul_f32_e32 v53, 2.0, v55
	v_rcp_f32_e32 v55, v52
	s_nop 0
	v_mul_f32_e32 v52, 2.0, v55
	v_pk_add_f32 v[52:53], v[52:53], 1.0 op_sel_hi:[1,0] neg_lo:[1,0] neg_hi:[1,0]
	v_mov_b32_e32 v58, v57
	v_pk_mul_f32 v[54:55], v[58:59], 0.5 op_sel_hi:[1,0]
	v_pk_add_f32 v[52:53], v[52:53], 1.0 op_sel_hi:[1,0]
	s_nop 0
	v_pk_mul_f32 v[52:53], v[54:55], v[52:53]
	v_cvt_pk_bf16_f32 v51, v51, v53
	v_cvt_pk_bf16_f32 v50, v50, v52
	global_store_dwordx2 v[48:49], v[50:51], off
	v_mul_f32_e32 v51, 0x3d372713, v124
	v_mul_f32_e32 v51, v124, v51
	v_fma_f32 v51, v124, v51, v124
	v_mul_f32_e32 v51, 0x3f4c422a, v51
	v_add_f32_e32 v51, v51, v51
	v_mul_f32_e32 v51, 0x3fb8aa3b, v51
	v_mul_f32_e32 v50, 0x3d372713, v125
	v_exp_f32_e32 v52, v51
	v_mul_f32_e32 v51, 0x3d372713, v123
	v_mul_f32_e32 v50, v125, v50
	v_mul_f32_e32 v51, v123, v51
	v_fma_f32 v50, v125, v50, v125
	v_fma_f32 v51, v123, v51, v123
	v_mul_f32_e32 v50, 0x3f4c422a, v50
	v_mul_f32_e32 v51, 0x3f4c422a, v51
	v_add_f32_e32 v50, v50, v50
	v_add_f32_e32 v51, v51, v51
	v_mul_f32_e32 v50, 0x3fb8aa3b, v50
	v_mul_f32_e32 v51, 0x3fb8aa3b, v51
	v_exp_f32_e32 v50, v50
	v_exp_f32_e32 v51, v51
	v_mul_f32_e32 v53, 0x3d372713, v122
	v_mul_f32_e32 v53, v122, v53
	v_fma_f32 v53, v122, v53, v122
	v_pk_add_f32 v[50:51], v[50:51], 1.0 op_sel_hi:[1,0]
	v_mul_f32_e32 v53, 0x3f4c422a, v53
	v_rcp_f32_e32 v55, v51
	v_add_f32_e32 v53, v53, v53
	v_mul_f32_e32 v53, 0x3fb8aa3b, v53
	v_exp_f32_e32 v53, v53
	v_mul_f32_e32 v51, 2.0, v55
	v_rcp_f32_e32 v55, v50
	v_pk_add_f32 v[52:53], v[52:53], 1.0 op_sel_hi:[1,0]
	v_mul_f32_e32 v50, 2.0, v55
	v_pk_add_f32 v[50:51], v[50:51], 1.0 op_sel_hi:[1,0] neg_lo:[1,0] neg_hi:[1,0]
	v_mov_b32_e32 v54, v60
	v_mov_b32_e32 v55, v62
	v_pk_mul_f32 v[54:55], v[54:55], 0.5 op_sel_hi:[1,0]
	v_pk_add_f32 v[50:51], v[50:51], 1.0 op_sel_hi:[1,0]
	v_mov_b32_e32 v62, v61
	v_pk_mul_f32 v[50:51], v[54:55], v[50:51]
	v_rcp_f32_e32 v55, v53
	s_nop 0
	v_mul_f32_e32 v53, 2.0, v55
	v_rcp_f32_e32 v55, v52
	s_nop 0
	v_mul_f32_e32 v52, 2.0, v55
	v_pk_add_f32 v[52:53], v[52:53], 1.0 op_sel_hi:[1,0] neg_lo:[1,0] neg_hi:[1,0]
	v_pk_mul_f32 v[54:55], v[62:63], 0.5 op_sel_hi:[1,0]
	v_pk_add_f32 v[52:53], v[52:53], 1.0 op_sel_hi:[1,0]
	s_nop 0
	v_pk_mul_f32 v[52:53], v[54:55], v[52:53]
	v_cvt_pk_bf16_f32 v51, v51, v53
	v_cvt_pk_bf16_f32 v50, v50, v52
	global_store_dwordx2 v[48:49], v[50:51], off offset:16

.LBB0_374:
	s_andn2_b64 vcc, exec, s[0:1]
	s_cbranch_vccnz .LBB0_376
	s_add_i32 s5, s97, 0xfffffbe0
	s_lshr_b32 s78, s5, 8
	s_lshl_b64 s[0:1], s[78:79], 23
	v_readlane_b32 s2, v254, 5
	s_add_u32 s0, s2, s0
	v_readlane_b32 s2, v254, 6
	s_addc_u32 s1, s2, s1
	s_lshl_b64 s[2:3], s[78:79], 22
	v_readlane_b32 s4, v254, 11
	s_waitcnt vmcnt(7)
	v_mov_b32_e32 v37, v208
	s_add_u32 s2, s4, s2
	v_readlane_b32 s4, v254, 12
	s_addc_u32 s3, s4, s3
	v_lshlrev_b32_e32 v1, 7, v37
	s_lshl_b32 s4, s97, 7
	v_lshrrev_b32_e32 v0, 5, v37
	v_and_b32_e32 v5, 7, v37
	v_and_b32_e32 v39, 0x2f80, v1
	v_ashrrev_i32_e32 v1, 1, v37
	s_and_b32 s4, s4, 0x80
	v_and_b32_e32 v36, 31, v37
	v_and_b32_e32 v38, 0xffffffc0, v1
	v_bitop3_b32 v0, v0, v5, 1 bitop3:0x6c
	v_ashrrev_i32_e32 v110, 3, v37
	v_or_b32_e32 v1, v38, v36
	v_lshlrev_b32_e32 v109, 4, v0
	v_add_u32_e32 v0, s4, v110
	v_lshl_add_u32 v108, v1, 7, v214
	v_ashrrev_i32_e32 v1, 31, v0
	v_readlane_b32 s6, v253, 40
	v_lshlrev_b64 v[0:1], 8, v[0:1]
	v_readlane_b32 s7, v253, 41
	v_lshlrev_b32_e32 v3, 4, v37
	v_and_b32_e32 v192, 0x70, v3
	v_lshl_add_u64 v[0:1], s[6:7], 0, v[0:1]
	v_lshl_add_u64 v[32:33], v[0:1], 0, v[192:193]
	global_load_dwordx4 v[40:43], v[32:33], off
	v_ashrrev_i32_e32 v86, 4, v37
	s_lshl_b32 s5, s5, 6
	v_ashrrev_i32_e32 v87, 31, v86
	s_and_b32 s5, s5, 0x3f80
	v_lshlrev_b32_e32 v2, 3, v37
	v_lshlrev_b64 v[0:1], 15, v[86:87]
	v_lshl_add_u64 v[0:1], s[2:3], 0, v[0:1]
	s_lshl_b32 s78, s5, 1
	v_and_b32_e32 v87, 0x78, v2
	v_add_u32_e32 v7, 0x100, v37
	v_lshl_add_u64 v[0:1], v[0:1], 0, s[78:79]
	v_lshlrev_b32_e32 v2, 1, v87
	v_mov_b32_e32 v3, v193
	v_ashrrev_i32_e32 v111, 3, v7
	v_lshl_add_u64 v[12:13], v[0:1], 0, v[2:3]
	v_add_u32_e32 v0, s4, v111
	v_ashrrev_i32_e32 v1, 31, v0
	v_lshlrev_b64 v[0:1], 8, v[0:1]
	v_bfe_u32 v4, v37, 5, 1
	v_lshl_add_u64 v[0:1], s[6:7], 0, v[0:1]
	v_lshl_add_u64 v[34:35], v[0:1], 0, v[192:193]
	v_bitop3_b32 v0, v4, v5, 4 bitop3:0x36
	v_ashrrev_i32_e32 v88, 4, v7
	v_lshlrev_b32_e32 v113, 4, v0
	v_bitop3_b32 v0, v4, v5, 6 bitop3:0x36
	v_ashrrev_i32_e32 v89, 31, v88
	v_lshlrev_b32_e32 v114, 4, v0
	v_lshlrev_b64 v[0:1], 15, v[88:89]
	v_bitop3_b32 v6, v4, v5, 2 bitop3:0x36
	v_lshl_add_u64 v[0:1], s[2:3], 0, v[0:1]
	v_add_u32_e32 v4, 0x200, v37
	v_lshl_add_u64 v[0:1], v[0:1], 0, s[78:79]
	v_ashrrev_i32_e32 v89, 3, v4
	v_lshl_add_u64 v[14:15], v[0:1], 0, v[2:3]
	v_add_u32_e32 v0, s4, v89
	v_ashrrev_i32_e32 v1, 31, v0
	v_lshlrev_b64 v[0:1], 8, v[0:1]
	v_ashrrev_i32_e32 v94, 4, v4
	v_lshl_add_u64 v[0:1], s[6:7], 0, v[0:1]
	v_ashrrev_i32_e32 v95, 31, v94
	v_lshl_add_u64 v[90:91], v[0:1], 0, v[192:193]
	v_lshlrev_b64 v[0:1], 15, v[94:95]
	v_lshl_add_u64 v[0:1], s[2:3], 0, v[0:1]
	v_add_u32_e32 v8, 0x300, v37
	v_lshl_add_u64 v[0:1], v[0:1], 0, s[78:79]
	v_ashrrev_i32_e32 v95, 3, v8
	v_lshl_add_u64 v[24:25], v[0:1], 0, v[2:3]
	v_add_u32_e32 v0, s4, v95
	v_ashrrev_i32_e32 v1, 31, v0
	v_lshlrev_b64 v[0:1], 8, v[0:1]
	v_ashrrev_i32_e32 v98, 4, v8
	v_lshl_add_u64 v[0:1], s[6:7], 0, v[0:1]
	v_ashrrev_i32_e32 v99, 31, v98
	v_lshl_add_u64 v[96:97], v[0:1], 0, v[192:193]
	v_lshlrev_b64 v[0:1], 15, v[98:99]
	v_lshl_add_u64 v[0:1], s[2:3], 0, v[0:1]
	v_lshl_add_u64 v[0:1], v[0:1], 0, s[78:79]
	v_lshl_add_u64 v[26:27], v[0:1], 0, v[2:3]
	v_xor_b32_e32 v0, v110, v37
	v_lshlrev_b32_e32 v0, 4, v0
	v_and_b32_e32 v0, 0x70, v0
	global_load_dwordx4 v[44:47], v[34:35], off
	global_load_dwordx4 v[48:51], v[12:13], off
	v_lshlrev_b32_e32 v112, 4, v6
	global_load_dwordx4 v[4:7], v[34:35], off offset:128
	global_load_dwordx4 v[52:55], v[14:15], off
	global_load_dwordx4 v[16:19], v[32:33], off offset:128
	global_load_dwordx4 v[56:59], v[90:91], off
	global_load_dwordx4 v[8:11], v[90:91], off offset:128
	s_waitcnt vmcnt(12)
	v_lshl_or_b32 v152, v110, 7, v0
	v_bfe_u32 v231, v208, 6, 2
	v_lshlrev_b32_e32 v231, 4, v231
	v_xor_b32_e32 v152, v231, v152
	global_load_dwordx4 v[60:63], v[96:97], off
	global_load_dwordx4 v[64:67], v[24:25], off
	global_load_dwordx4 v[0:3], v[96:97], off offset:128
	global_load_dwordx4 v[82:85], v[26:27], off
	s_mov_b32 s2, 0x200000
	v_add_co_u32_e32 v100, vcc, s2, v12
	s_movk_i32 s3, 0x50
	s_nop 0
	v_addc_co_u32_e32 v101, vcc, 0, v13, vcc
	v_add_co_u32_e32 v102, vcc, s2, v14
	s_movk_i32 s6, 0x60
	s_nop 0
	v_addc_co_u32_e32 v103, vcc, 0, v15, vcc
	v_add_co_u32_e32 v104, vcc, s2, v24
	global_load_dwordx4 v[28:31], v[100:101], off
	global_load_dwordx4 v[20:23], v[102:103], off
	v_addc_co_u32_e32 v105, vcc, 0, v25, vcc
	v_add_co_u32_e32 v106, vcc, s2, v26
	s_movk_i32 s2, 0x70
	s_nop 0
	v_addc_co_u32_e32 v107, vcc, 0, v27, vcc
	global_load_dwordx4 v[24:27], v[104:105], off
	global_load_dwordx4 v[12:15], v[106:107], off
	s_waitcnt vmcnt(15)
	ds_write_b128 v152, v[40:43]
	v_lshlrev_b32_e32 v40, 1, v86
	v_lshlrev_b32_e32 v41, 7, v87
	v_and_b32_e32 v42, -16, v110
	v_and_b32_e32 v40, 14, v40
	v_add_u32_e32 v43, v41, v42
	v_or_b32_e32 v153, v43, v40
	v_xad_u32 v43, v42, 16, v41
	v_or_b32_e32 v154, v43, v40
	v_xad_u32 v43, v42, 32, v41
	v_or_b32_e32 v155, v43, v40
	v_xad_u32 v43, v42, 48, v41
	v_or_b32_e32 v156, v43, v40
	v_xad_u32 v43, v42, 64, v41
	v_or_b32_e32 v157, v43, v40
	v_xad_u32 v43, v42, s3, v41
	v_or_b32_e32 v158, v43, v40
	v_xad_u32 v43, v42, s6, v41
	v_xad_u32 v42, v42, s2, v41
	v_or_b32_e32 v159, v43, v40
	v_or_b32_e32 v160, v42, v40
	v_xor_b32_e32 v40, v111, v37
	v_lshlrev_b32_e32 v40, 4, v40
	v_and_b32_e32 v40, 0x70, v40
	v_lshl_or_b32 v164, v111, 7, v40
	v_bfe_u32 v231, v208, 6, 2
	v_lshlrev_b32_e32 v231, 4, v231
	v_xor_b32_e32 v164, v231, v164
	v_lshlrev_b32_e32 v40, 1, v88
	v_and_b32_e32 v42, -16, v111
	v_and_b32_e32 v40, 14, v40
	v_add_u32_e32 v43, v41, v42
	v_or_b32_e32 v165, v43, v40
	v_xad_u32 v43, v42, 16, v41
	v_or_b32_e32 v166, v43, v40
	v_xad_u32 v43, v42, 32, v41
	v_or_b32_e32 v167, v43, v40
	v_xad_u32 v43, v42, 48, v41
	v_or_b32_e32 v168, v43, v40
	v_xad_u32 v43, v42, 64, v41
	v_or_b32_e32 v169, v43, v40
	v_xad_u32 v43, v42, s3, v41
	v_or_b32_e32 v170, v43, v40
	v_xad_u32 v43, v42, s6, v41
	v_xad_u32 v42, v42, s2, v41
	v_or_b32_e32 v171, v43, v40
	v_or_b32_e32 v172, v42, v40
	v_xor_b32_e32 v40, v89, v37
	v_lshlrev_b32_e32 v40, 4, v40
	v_and_b32_e32 v40, 0x70, v40
	v_lshl_or_b32 v174, v89, 7, v40
	v_bfe_u32 v231, v208, 6, 2
	v_lshlrev_b32_e32 v231, 4, v231
	v_xor_b32_e32 v174, v231, v174
	v_lshlrev_b32_e32 v40, 1, v94
	v_and_b32_e32 v42, -16, v89
	v_and_b32_e32 v40, 14, v40
	v_add_u32_e32 v43, v41, v42
	v_or_b32_e32 v175, v43, v40
	v_xad_u32 v43, v42, 16, v41
	v_or_b32_e32 v176, v43, v40
	v_xad_u32 v43, v42, 32, v41
	v_or_b32_e32 v177, v43, v40
	v_xad_u32 v43, v42, 48, v41
	v_or_b32_e32 v178, v43, v40
	v_xad_u32 v43, v42, 64, v41
	v_or_b32_e32 v179, v43, v40
	v_xad_u32 v43, v42, s3, v41
	v_or_b32_e32 v180, v43, v40
	v_xad_u32 v43, v42, s6, v41
	v_xad_u32 v42, v42, s2, v41
	v_or_b32_e32 v181, v43, v40
	v_or_b32_e32 v182, v42, v40
	v_xor_b32_e32 v40, v95, v37
	v_lshlrev_b32_e32 v40, 4, v40
	v_and_b32_e32 v40, 0x70, v40
	v_lshl_or_b32 v183, v95, 7, v40
	v_bfe_u32 v231, v208, 6, 2
	v_lshlrev_b32_e32 v231, 4, v231
	v_xor_b32_e32 v183, v231, v183
	v_lshlrev_b32_e32 v40, 1, v98
	v_and_b32_e32 v42, -16, v95
	v_and_b32_e32 v40, 14, v40
	v_add_u32_e32 v43, v41, v42
	v_or_b32_e32 v184, v43, v40
	v_xad_u32 v43, v42, 16, v41
	v_or_b32_e32 v185, v43, v40
	v_xad_u32 v43, v42, 32, v41
	v_or_b32_e32 v186, v43, v40
	v_xad_u32 v43, v42, 48, v41
	v_or_b32_e32 v187, v43, v40
	v_xad_u32 v43, v42, 64, v41
	v_or_b32_e32 v188, v43, v40
	v_xad_u32 v43, v42, s3, v41
	v_or_b32_e32 v189, v43, v40
	v_xad_u32 v43, v42, s6, v41
	v_xad_u32 v41, v42, s2, v41
	v_or_b32_e32 v190, v43, v40
	v_or_b32_e32 v191, v41, v40
	v_and_b32_e32 v75, 7, v208
	v_lshlrev_b32_e32 v75, 4, v75
	v_bfe_u32 v92, v208, 3, 2
	v_lshlrev_b32_e32 v92, 4, v92
	v_xor_b32_e32 v153, v75, v153
	v_xor_b32_e32 v154, v75, v154
	v_xor_b32_e32 v155, v75, v155
	v_xor_b32_e32 v156, v75, v156
	v_xor_b32_e32 v157, v75, v157
	v_xor_b32_e32 v158, v75, v158
	v_xor_b32_e32 v159, v75, v159
	v_xor_b32_e32 v160, v75, v160
	v_xor_b32_e32 v165, v75, v165
	v_xor_b32_e32 v166, v75, v166
	v_xor_b32_e32 v167, v75, v167
	v_xor_b32_e32 v168, v75, v168
	v_xor_b32_e32 v169, v75, v169
	v_xor_b32_e32 v170, v75, v170
	v_xor_b32_e32 v171, v75, v171
	v_xor_b32_e32 v172, v75, v172
	v_xor_b32_e32 v175, v75, v175
	v_xor_b32_e32 v176, v75, v176
	v_xor_b32_e32 v177, v75, v177
	v_xor_b32_e32 v178, v75, v178
	v_xor_b32_e32 v179, v75, v179
	v_xor_b32_e32 v180, v75, v180
	v_xor_b32_e32 v181, v75, v181
	v_xor_b32_e32 v182, v75, v182
	v_xor_b32_e32 v184, v75, v184
	v_xor_b32_e32 v185, v75, v185
	v_xor_b32_e32 v186, v75, v186
	v_xor_b32_e32 v187, v75, v187
	v_xor_b32_e32 v188, v75, v188
	v_xor_b32_e32 v189, v75, v189
	v_xor_b32_e32 v190, v75, v190
	v_xor_b32_e32 v191, v75, v191
	s_waitcnt vmcnt(13)
	ds_write_b16 v153, v48 offset:16384
	ds_write_b16_d16_hi v154, v48 offset:16512
	ds_write_b16 v155, v49 offset:16640
	ds_write_b16_d16_hi v156, v49 offset:16768
	ds_write_b16 v157, v50 offset:16896
	ds_write_b16_d16_hi v158, v50 offset:17024
	ds_write_b16 v159, v51 offset:17152
	ds_write_b16_d16_hi v160, v51 offset:17280
	ds_write_b128 v164, v[44:47]
	s_waitcnt vmcnt(11)
	ds_write_b16 v165, v52 offset:16384
	ds_write_b16_d16_hi v166, v52 offset:16512
	ds_write_b16 v167, v53 offset:16640
	ds_write_b16_d16_hi v168, v53 offset:16768
	ds_write_b16 v169, v54 offset:16896
	ds_write_b16_d16_hi v170, v54 offset:17024
	ds_write_b16 v171, v55 offset:17152
	ds_write_b16_d16_hi v172, v55 offset:17280
	s_waitcnt vmcnt(9)
	ds_write_b128 v174, v[56:59]
	s_waitcnt vmcnt(6)
	ds_write_b16 v175, v64 offset:16384
	ds_write_b16_d16_hi v176, v64 offset:16512
	ds_write_b16 v177, v65 offset:16640
	ds_write_b16_d16_hi v178, v65 offset:16768
	ds_write_b16 v179, v66 offset:16896
	ds_write_b16_d16_hi v180, v66 offset:17024
	ds_write_b16 v181, v67 offset:17152
	ds_write_b16_d16_hi v182, v67 offset:17280
	ds_write_b128 v183, v[60:63]
	s_waitcnt vmcnt(4)
	ds_write_b16 v184, v82 offset:16384
	ds_write_b16_d16_hi v185, v82 offset:16512
	ds_write_b16 v186, v83 offset:16640
	ds_write_b16_d16_hi v187, v83 offset:16768
	ds_write_b16 v188, v84 offset:16896
	ds_write_b16_d16_hi v189, v84 offset:17024
	ds_write_b16 v190, v85 offset:17152
	ds_write_b16_d16_hi v191, v85 offset:17280
	s_waitcnt lgkmcnt(0)
	s_barrier
	global_load_dwordx4 v[40:43], v[32:33], off offset:128
	s_nop 0
	global_load_dwordx4 v[32:35], v[34:35], off offset:128
	s_nop 0
	global_load_dwordx4 v[44:47], v[90:91], off offset:128
	global_load_dwordx4 v[48:51], v[96:97], off offset:128
	global_load_dwordx4 v[52:55], v[100:101], off
	global_load_dwordx4 v[56:59], v[102:103], off
	global_load_dwordx4 v[60:63], v[104:105], off
	global_load_dwordx4 v[64:67], v[106:107], off
	v_or_b32_e32 v150, v108, v109
	v_xor_b32_e32 v150, v92, v150
	v_xor_b32_e32 v207, 64, v150
	v_or_b32_e32 v161, v109, v39
	v_bfe_u32 v231, v208, 3, 2
	v_lshlrev_b32_e32 v231, 4, v231
	v_xor_b32_e32 v161, v231, v161
	ds_read_b128 v[82:85], v161 offset:0
	ds_read_b128 v[86:89], v161 offset:0x1000
	ds_read_b128 v[94:97], v150 offset:0
	ds_read_b128 v[98:101], v207 offset:0x1000
	v_or_b32_e32 v151, v108, v113
	v_xor_b32_e32 v151, v92, v151
	v_xor_b32_e32 v221, 64, v151
	v_or_b32_e32 v162, v113, v39
	v_bfe_u32 v231, v208, 3, 2
	v_lshlrev_b32_e32 v231, 4, v231
	v_xor_b32_e32 v162, v231, v162
	v_or_b32_e32 v163, v108, v112
	v_xor_b32_e32 v163, v92, v163
	v_xor_b32_e32 v224, 64, v163
	v_or_b32_e32 v173, v114, v39
	v_bfe_u32 v231, v208, 3, 2
	v_lshlrev_b32_e32 v231, 4, v231
	v_xor_b32_e32 v173, v231, v173
	v_or_b32_e32 v39, v112, v39
	v_bfe_u32 v231, v208, 3, 2
	v_lshlrev_b32_e32 v231, 4, v231
	v_xor_b32_e32 v39, v231, v39
	v_or_b32_e32 v192, v108, v114
	v_xor_b32_e32 v192, v92, v192
	v_xor_b32_e32 v225, 64, v192
	ds_read_b128 v[102:105], v39 offset:0
	ds_read_b128 v[106:109], v39 offset:0x1000
	ds_read_b128 v[110:113], v163 offset:0
	ds_read_b128 v[114:117], v224 offset:0x1000
	ds_read_b128 v[118:121], v162 offset:0
	ds_read_b128 v[122:125], v162 offset:0x1000
	ds_read_b128 v[126:129], v151 offset:0
	ds_read_b128 v[130:133], v221 offset:0x1000
	ds_read_b128 v[134:137], v173 offset:0
	ds_read_b128 v[138:141], v173 offset:0x1000
	ds_read_b128 v[142:145], v192 offset:0
	ds_read_b128 v[146:149], v225 offset:0x1000
	s_waitcnt lgkmcnt(12)
	s_nop 0
	v_mfma_f32_32x32x16_bf16 a[48:63], v[82:85], v[94:97], 0
	s_waitcnt lgkmcnt(8)
	s_waitcnt lgkmcnt(4)
	s_waitcnt lgkmcnt(0)
	ds_write_b128 v152, v[16:19] offset:32768
	s_waitcnt vmcnt(11)
	ds_write_b16 v153, v28 offset:49152
	ds_write_b16_d16_hi v154, v28 offset:49280
	ds_write_b16 v155, v29 offset:49408
	ds_write_b16_d16_hi v156, v29 offset:49536
	ds_write_b16 v157, v30 offset:49664
	ds_write_b16_d16_hi v158, v30 offset:49792
	ds_write_b16 v159, v31 offset:49920
	ds_write_b16_d16_hi v160, v31 offset:50048
	ds_write_b128 v164, v[4:7] offset:32768
	s_waitcnt vmcnt(10)
	ds_write_b16 v165, v20 offset:49152
	ds_write_b16_d16_hi v166, v20 offset:49280
	ds_write_b16 v167, v21 offset:49408
	ds_write_b16_d16_hi v168, v21 offset:49536
	ds_write_b16 v169, v22 offset:49664
	ds_write_b16_d16_hi v170, v22 offset:49792
	ds_write_b16 v171, v23 offset:49920
	ds_write_b16_d16_hi v172, v23 offset:50048
	ds_write_b128 v174, v[8:11] offset:32768
	s_waitcnt vmcnt(9)
	ds_write_b16 v175, v24 offset:49152
	ds_write_b16_d16_hi v176, v24 offset:49280
	ds_write_b16 v177, v25 offset:49408
	ds_write_b16_d16_hi v178, v25 offset:49536
	ds_write_b16 v179, v26 offset:49664
	ds_write_b16_d16_hi v180, v26 offset:49792
	ds_write_b16 v181, v27 offset:49920
	ds_write_b16_d16_hi v182, v27 offset:50048
	ds_write_b128 v183, v[0:3] offset:32768
	s_waitcnt vmcnt(8)
	ds_write_b16 v184, v12 offset:49152
	ds_write_b16_d16_hi v185, v12 offset:49280
	ds_write_b16 v186, v13 offset:49408
	ds_write_b16_d16_hi v187, v13 offset:49536
	ds_write_b16 v188, v14 offset:49664
	ds_write_b16_d16_hi v189, v14 offset:49792
	ds_write_b16 v190, v15 offset:49920
	ds_write_b16_d16_hi v191, v15 offset:50048
	s_waitcnt lgkmcnt(0)
	s_barrier
	v_mfma_f32_32x32x16_bf16 a[48:63], v[102:105], v[110:113], a[48:63]
	ds_read_b128 v[0:3], v161 offset:0x8000
	ds_read_b128 v[4:7], v161 offset:0x9000
	ds_read_b128 v[8:11], v150 offset:0x8000
	ds_read_b128 v[12:15], v207 offset:0x9000
	ds_read_b128 v[16:19], v39 offset:0x8000
	ds_read_b128 v[20:23], v39 offset:0x9000
	ds_read_b128 v[24:27], v163 offset:0x8000
	v_mfma_f32_32x32x16_bf16 a[48:63], v[118:121], v[126:129], a[48:63]
	ds_read_b128 v[28:31], v224 offset:0x9000
	v_mfma_f32_32x32x16_bf16 a[32:47], v[82:85], v[98:101], 0
	ds_read_b128 v[82:85], v162 offset:0x8000
	v_mfma_f32_32x32x16_bf16 a[16:31], v[86:89], v[94:97], 0
	v_mfma_f32_32x32x16_bf16 a[0:15], v[86:89], v[98:101], 0
	ds_read_b128 v[86:89], v162 offset:0x9000
	ds_read_b128 v[94:97], v151 offset:0x8000
	ds_read_b128 v[98:101], v221 offset:0x9000
	v_mfma_f32_32x32x16_bf16 a[48:63], v[134:137], v[142:145], a[48:63]
	v_mfma_f32_32x32x16_bf16 a[32:47], v[102:105], v[114:117], a[32:47]
	ds_read_b128 v[102:105], v173 offset:0x8000
	v_mfma_f32_32x32x16_bf16 a[16:31], v[106:109], v[110:113], a[16:31]
	v_mfma_f32_32x32x16_bf16 a[0:15], v[106:109], v[114:117], a[0:15]
	ds_read_b128 v[106:109], v173 offset:0x9000
	ds_read_b128 v[110:113], v192 offset:0x8000
	ds_read_b128 v[114:117], v225 offset:0x9000
	s_waitcnt lgkmcnt(12)
	s_waitcnt lgkmcnt(8)
	s_waitcnt lgkmcnt(4)
	s_nop 0
	v_mfma_f32_32x32x16_bf16 a[48:63], v[0:3], v[8:11], a[48:63]
	s_waitcnt lgkmcnt(0)
	s_waitcnt vmcnt(7)
	ds_write_b128 v152, v[40:43]
	s_waitcnt vmcnt(3)
	ds_write_b16 v153, v52 offset:16384
	ds_write_b16_d16_hi v154, v52 offset:16512
	ds_write_b16 v155, v53 offset:16640
	ds_write_b16_d16_hi v156, v53 offset:16768
	ds_write_b16 v157, v54 offset:16896
	ds_write_b16_d16_hi v158, v54 offset:17024
	ds_write_b16 v159, v55 offset:17152
	ds_write_b16_d16_hi v160, v55 offset:17280
	ds_write_b128 v164, v[32:35]
	s_waitcnt vmcnt(2)
	ds_write_b16 v165, v56 offset:16384
	ds_write_b16_d16_hi v166, v56 offset:16512
	ds_write_b16 v167, v57 offset:16640
	ds_write_b16_d16_hi v168, v57 offset:16768
	ds_write_b16 v169, v58 offset:16896
	ds_write_b16_d16_hi v170, v58 offset:17024
	ds_write_b16 v171, v59 offset:17152
	ds_write_b16_d16_hi v172, v59 offset:17280
	ds_write_b128 v174, v[44:47]
	s_waitcnt vmcnt(1)
	ds_write_b16 v175, v60 offset:16384
	ds_write_b16_d16_hi v176, v60 offset:16512
	ds_write_b16 v177, v61 offset:16640
	ds_write_b16_d16_hi v178, v61 offset:16768
	ds_write_b16 v179, v62 offset:16896
	ds_write_b16_d16_hi v180, v62 offset:17024
	ds_write_b16 v181, v63 offset:17152
	ds_write_b16_d16_hi v182, v63 offset:17280
	ds_write_b128 v183, v[48:51]
	s_waitcnt vmcnt(0)
	ds_write_b16 v184, v64 offset:16384
	ds_write_b16_d16_hi v185, v64 offset:16512
	ds_write_b16 v186, v65 offset:16640
	ds_write_b16_d16_hi v187, v65 offset:16768
	ds_write_b16 v188, v66 offset:16896
	ds_write_b16_d16_hi v189, v66 offset:17024
	ds_write_b16 v190, v67 offset:17152
	ds_write_b16_d16_hi v191, v67 offset:17280
	s_waitcnt lgkmcnt(0)
	s_barrier
	v_mfma_f32_32x32x16_bf16 a[32:47], v[118:121], v[130:133], a[32:47]
	v_mfma_f32_32x32x16_bf16 a[48:63], v[16:19], v[24:27], a[48:63]
	v_mfma_f32_32x32x16_bf16 a[16:31], v[122:125], v[126:129], a[16:31]
	v_mfma_f32_32x32x16_bf16 a[0:15], v[122:125], v[130:133], a[0:15]
	v_mfma_f32_32x32x16_bf16 a[32:47], v[134:137], v[146:149], a[32:47]
	v_mfma_f32_32x32x16_bf16 a[48:63], v[82:85], v[94:97], a[48:63]
	v_mfma_f32_32x32x16_bf16 a[16:31], v[138:141], v[142:145], a[16:31]
	v_mfma_f32_32x32x16_bf16 a[0:15], v[138:141], v[146:149], a[0:15]
	v_mfma_f32_32x32x16_bf16 a[32:47], v[0:3], v[12:15], a[32:47]
	v_lshrrev_b32_e32 v1, 3, v37
	v_and_b32_e32 v0, 64, v37
	v_and_b32_e32 v1, 4, v1
	v_or3_b32 v2, v0, v1, s4
	v_or_b32_e32 v0, s5, v36
	v_add_u32_e32 v0, v0, v38
	v_and_b32_e32 v1, 0xdf, v0
	v_mfma_f32_32x32x16_bf16 a[48:63], v[102:105], v[110:113], a[48:63]
	v_ashrrev_i32_e32 v0, 7, v0
	v_and_b32_e32 v3, -2, v0
	v_lshl_add_u32 v2, v2, 6, v3
	v_ashrrev_i32_e32 v3, 31, v2
	v_lshlrev_b32_e32 v192, 1, v1
	v_lshl_add_u64 v[0:1], s[0:1], 0, v[192:193]
	s_mov_b32 s0, 0x10000
	v_mfma_f32_32x32x16_bf16 a[16:31], v[4:7], v[8:11], a[16:31]
	v_mfma_f32_32x32x16_bf16 a[0:15], v[4:7], v[12:15], a[0:15]
	v_lshlrev_b64 v[4:5], 9, v[2:3]
	s_nop 1
	v_accvgpr_read_b32 v3, a48
	v_bfe_u32 v6, v3, 16, 1
	v_lshl_add_u64 v[4:5], v[0:1], 0, v[4:5]
	v_add3_u32 v3, v3, v6, s80
	global_store_short_d16_hi v[4:5], v3, off
	v_accvgpr_read_b32 v3, a49
	v_bfe_u32 v6, v3, 16, 1
	v_add3_u32 v3, v3, v6, s80
	global_store_short_d16_hi v[4:5], v3, off offset:512
	v_accvgpr_read_b32 v3, a50
	v_bfe_u32 v6, v3, 16, 1
	v_add3_u32 v3, v3, v6, s80
	v_add_co_u32_e32 v6, vcc, s0, v4
	v_mfma_f32_32x32x16_bf16 a[32:47], v[16:19], v[28:31], a[32:47]
	s_nop 0
	v_addc_co_u32_e32 v7, vcc, 0, v5, vcc
	global_store_short_d16_hi v[6:7], v3, off
	v_accvgpr_read_b32 v3, a51
	v_bfe_u32 v8, v3, 16, 1
	v_add3_u32 v3, v3, v8, s80
	v_add_u32_e32 v8, 0x200, v2
	global_store_short_d16_hi v[6:7], v3, off offset:512
	v_ashrrev_i32_e32 v9, 31, v8
	v_accvgpr_read_b32 v3, a52
	v_lshlrev_b64 v[8:9], 9, v[8:9]
	v_bfe_u32 v10, v3, 16, 1
	v_lshl_add_u64 v[8:9], v[0:1], 0, v[8:9]
	v_add3_u32 v3, v3, v10, s80
	global_store_short_d16_hi v[8:9], v3, off
	v_accvgpr_read_b32 v3, a53
	v_bfe_u32 v10, v3, 16, 1
	v_add3_u32 v3, v3, v10, s80
	global_store_short_d16_hi v[8:9], v3, off offset:512
	v_accvgpr_read_b32 v3, a54
	v_bfe_u32 v10, v3, 16, 1
	v_add3_u32 v3, v3, v10, s80
	v_add_co_u32_e32 v10, vcc, s0, v8
	v_mfma_f32_32x32x16_bf16 a[32:47], v[82:85], v[98:101], a[32:47]
	s_nop 0
	v_addc_co_u32_e32 v11, vcc, 0, v9, vcc
	global_store_short_d16_hi v[10:11], v3, off
	v_accvgpr_read_b32 v3, a55
	v_bfe_u32 v12, v3, 16, 1
	v_add3_u32 v3, v3, v12, s80
	v_add_u32_e32 v12, 0x400, v2
	global_store_short_d16_hi v[10:11], v3, off offset:512
	v_ashrrev_i32_e32 v13, 31, v12
	v_accvgpr_read_b32 v3, a56
	v_lshlrev_b64 v[12:13], 9, v[12:13]
	v_bfe_u32 v14, v3, 16, 1
	v_lshl_add_u64 v[12:13], v[0:1], 0, v[12:13]
	v_add3_u32 v3, v3, v14, s80
	global_store_short_d16_hi v[12:13], v3, off
	v_accvgpr_read_b32 v3, a57
	v_bfe_u32 v14, v3, 16, 1
	v_add3_u32 v3, v3, v14, s80
	global_store_short_d16_hi v[12:13], v3, off offset:512
	v_accvgpr_read_b32 v3, a58
	v_bfe_u32 v14, v3, 16, 1
	v_add3_u32 v3, v3, v14, s80
	v_add_co_u32_e32 v14, vcc, s0, v12
	v_mfma_f32_32x32x16_bf16 a[32:47], v[102:105], v[114:117], a[32:47]
	s_nop 0
	v_addc_co_u32_e32 v15, vcc, 0, v13, vcc
	global_store_short_d16_hi v[14:15], v3, off
	v_accvgpr_read_b32 v3, a59
	v_bfe_u32 v16, v3, 16, 1
	v_add3_u32 v3, v3, v16, s80
	v_add_u32_e32 v16, 0x600, v2
	global_store_short_d16_hi v[14:15], v3, off offset:512
	v_ashrrev_i32_e32 v17, 31, v16
	v_accvgpr_read_b32 v3, a60
	v_lshlrev_b64 v[16:17], 9, v[16:17]
	v_bfe_u32 v18, v3, 16, 1
	v_lshl_add_u64 v[16:17], v[0:1], 0, v[16:17]
	v_add3_u32 v3, v3, v18, s80
	global_store_short_d16_hi v[16:17], v3, off
	v_accvgpr_read_b32 v3, a61
	v_bfe_u32 v18, v3, 16, 1
	v_add3_u32 v3, v3, v18, s80
	global_store_short_d16_hi v[16:17], v3, off offset:512
	v_accvgpr_read_b32 v3, a62
	v_bfe_u32 v18, v3, 16, 1
	v_add3_u32 v3, v3, v18, s80
	v_add_co_u32_e32 v18, vcc, s0, v16
	v_mfma_f32_32x32x16_bf16 a[16:31], v[20:23], v[24:27], a[16:31]
	s_nop 0
	v_addc_co_u32_e32 v19, vcc, 0, v17, vcc
	global_store_short_d16_hi v[18:19], v3, off
	v_accvgpr_read_b32 v3, a63
	v_mfma_f32_32x32x16_bf16 a[0:15], v[20:23], v[28:31], a[0:15]
	v_bfe_u32 v20, v3, 16, 1
	v_add3_u32 v3, v3, v20, s80
	global_store_short_d16_hi v[18:19], v3, off offset:512
	v_accvgpr_read_b32 v3, a32
	v_bfe_u32 v20, v3, 16, 1
	v_add3_u32 v3, v3, v20, s80
	global_store_short_d16_hi v[4:5], v3, off offset:64
	v_accvgpr_read_b32 v3, a33
	v_bfe_u32 v20, v3, 16, 1
	v_add3_u32 v3, v3, v20, s80
	global_store_short_d16_hi v[4:5], v3, off offset:576
	v_accvgpr_read_b32 v3, a34
	v_bfe_u32 v4, v3, 16, 1
	v_add3_u32 v3, v3, v4, s80
	global_store_short_d16_hi v[6:7], v3, off offset:64
	v_accvgpr_read_b32 v3, a35
	v_bfe_u32 v4, v3, 16, 1
	v_add3_u32 v3, v3, v4, s80
	global_store_short_d16_hi v[6:7], v3, off offset:576
	v_accvgpr_read_b32 v3, a36
	v_bfe_u32 v4, v3, 16, 1
	v_add3_u32 v3, v3, v4, s80
	global_store_short_d16_hi v[8:9], v3, off offset:64
	v_accvgpr_read_b32 v3, a37
	v_bfe_u32 v4, v3, 16, 1
	v_add3_u32 v3, v3, v4, s80
	global_store_short_d16_hi v[8:9], v3, off offset:576
	v_accvgpr_read_b32 v3, a38
	v_bfe_u32 v4, v3, 16, 1
	v_add3_u32 v3, v3, v4, s80
	global_store_short_d16_hi v[10:11], v3, off offset:64
	v_accvgpr_read_b32 v3, a39
	v_bfe_u32 v4, v3, 16, 1
	v_add3_u32 v3, v3, v4, s80
	global_store_short_d16_hi v[10:11], v3, off offset:576
	v_accvgpr_read_b32 v3, a40
	v_bfe_u32 v4, v3, 16, 1
	v_add3_u32 v3, v3, v4, s80
	global_store_short_d16_hi v[12:13], v3, off offset:64
	v_accvgpr_read_b32 v3, a41
	v_bfe_u32 v4, v3, 16, 1
	v_add3_u32 v3, v3, v4, s80
	global_store_short_d16_hi v[12:13], v3, off offset:576
	v_accvgpr_read_b32 v3, a42
	v_bfe_u32 v4, v3, 16, 1
	v_mfma_f32_32x32x16_bf16 a[16:31], v[86:89], v[94:97], a[16:31]
	v_add3_u32 v3, v3, v4, s80
	global_store_short_d16_hi v[14:15], v3, off offset:64
	v_accvgpr_read_b32 v3, a43
	v_bfe_u32 v4, v3, 16, 1
	v_add3_u32 v3, v3, v4, s80
	global_store_short_d16_hi v[14:15], v3, off offset:576
	v_accvgpr_read_b32 v3, a44
	v_bfe_u32 v4, v3, 16, 1
	v_add3_u32 v3, v3, v4, s80
	global_store_short_d16_hi v[16:17], v3, off offset:64
	v_accvgpr_read_b32 v3, a45
	v_mfma_f32_32x32x16_bf16 a[16:31], v[106:109], v[110:113], a[16:31]
	v_bfe_u32 v4, v3, 16, 1
	v_add3_u32 v3, v3, v4, s80
	global_store_short_d16_hi v[16:17], v3, off offset:576
	v_accvgpr_read_b32 v3, a46
	v_bfe_u32 v4, v3, 16, 1
	v_add3_u32 v3, v3, v4, s80
	global_store_short_d16_hi v[18:19], v3, off offset:64
	v_accvgpr_read_b32 v3, a47
	v_bfe_u32 v4, v3, 16, 1
	v_add3_u32 v3, v3, v4, s80
	v_add_u32_e32 v4, 0x800, v2
	global_store_short_d16_hi v[18:19], v3, off offset:576
	v_ashrrev_i32_e32 v5, 31, v4
	v_accvgpr_read_b32 v3, a16
	v_lshlrev_b64 v[4:5], 9, v[4:5]
	v_bfe_u32 v6, v3, 16, 1
	v_lshl_add_u64 v[4:5], v[0:1], 0, v[4:5]
	v_add3_u32 v3, v3, v6, s80
	global_store_short_d16_hi v[4:5], v3, off
	v_accvgpr_read_b32 v3, a17
	v_bfe_u32 v6, v3, 16, 1
	v_add3_u32 v3, v3, v6, s80
	global_store_short_d16_hi v[4:5], v3, off offset:512
	v_accvgpr_read_b32 v3, a18
	v_bfe_u32 v6, v3, 16, 1
	v_add3_u32 v3, v3, v6, s80
	v_add_co_u32_e32 v6, vcc, s0, v4
	v_mfma_f32_32x32x16_bf16 a[0:15], v[86:89], v[98:101], a[0:15]
	s_nop 0
	v_addc_co_u32_e32 v7, vcc, 0, v5, vcc
	global_store_short_d16_hi v[6:7], v3, off
	v_accvgpr_read_b32 v3, a19
	v_bfe_u32 v8, v3, 16, 1
	v_add3_u32 v3, v3, v8, s80
	v_add_u32_e32 v8, 0xa00, v2
	global_store_short_d16_hi v[6:7], v3, off offset:512
	v_ashrrev_i32_e32 v9, 31, v8
	v_accvgpr_read_b32 v3, a20
	v_lshlrev_b64 v[8:9], 9, v[8:9]
	v_bfe_u32 v10, v3, 16, 1
	v_lshl_add_u64 v[8:9], v[0:1], 0, v[8:9]
	v_add3_u32 v3, v3, v10, s80
	global_store_short_d16_hi v[8:9], v3, off
	v_accvgpr_read_b32 v3, a21
	v_bfe_u32 v10, v3, 16, 1
	v_add3_u32 v3, v3, v10, s80
	global_store_short_d16_hi v[8:9], v3, off offset:512
	v_accvgpr_read_b32 v3, a22
	v_bfe_u32 v10, v3, 16, 1
	v_add3_u32 v3, v3, v10, s80
	v_add_co_u32_e32 v10, vcc, s0, v8
	v_mfma_f32_32x32x16_bf16 a[0:15], v[106:109], v[114:117], a[0:15]
	s_nop 0
	v_addc_co_u32_e32 v11, vcc, 0, v9, vcc
	global_store_short_d16_hi v[10:11], v3, off
	v_accvgpr_read_b32 v3, a23
	v_bfe_u32 v12, v3, 16, 1
	v_add3_u32 v3, v3, v12, s80
	v_add_u32_e32 v12, 0xc00, v2
	global_store_short_d16_hi v[10:11], v3, off offset:512
	v_ashrrev_i32_e32 v13, 31, v12
	v_accvgpr_read_b32 v3, a24
	v_lshlrev_b64 v[12:13], 9, v[12:13]
	v_bfe_u32 v14, v3, 16, 1
	v_lshl_add_u64 v[12:13], v[0:1], 0, v[12:13]
	v_add3_u32 v3, v3, v14, s80
	global_store_short_d16_hi v[12:13], v3, off
	v_accvgpr_read_b32 v3, a25
	v_bfe_u32 v14, v3, 16, 1
	v_add3_u32 v3, v3, v14, s80
	global_store_short_d16_hi v[12:13], v3, off offset:512
	v_accvgpr_read_b32 v3, a26
	v_bfe_u32 v14, v3, 16, 1
	v_add3_u32 v3, v3, v14, s80
	v_add_co_u32_e32 v14, vcc, s0, v12
	v_add_u32_e32 v2, 0xe00, v2
	s_nop 0
	v_addc_co_u32_e32 v15, vcc, 0, v13, vcc
	global_store_short_d16_hi v[14:15], v3, off
	v_accvgpr_read_b32 v3, a27
	v_bfe_u32 v16, v3, 16, 1
	v_add3_u32 v3, v3, v16, s80
	global_store_short_d16_hi v[14:15], v3, off offset:512
	v_ashrrev_i32_e32 v3, 31, v2
	v_lshlrev_b64 v[2:3], 9, v[2:3]
	v_lshl_add_u64 v[0:1], v[0:1], 0, v[2:3]
	v_accvgpr_read_b32 v2, a28
	v_bfe_u32 v3, v2, 16, 1
	v_add3_u32 v2, v2, v3, s80
	global_store_short_d16_hi v[0:1], v2, off
	v_accvgpr_read_b32 v2, a29
	v_bfe_u32 v3, v2, 16, 1
	v_add3_u32 v2, v2, v3, s80
	global_store_short_d16_hi v[0:1], v2, off offset:512
	v_accvgpr_read_b32 v2, a30
	v_bfe_u32 v3, v2, 16, 1
	v_add3_u32 v16, v2, v3, s80
	v_add_co_u32_e32 v2, vcc, s0, v0
	s_nop 1
	v_addc_co_u32_e32 v3, vcc, 0, v1, vcc
	global_store_short_d16_hi v[2:3], v16, off
	v_accvgpr_read_b32 v16, a31
	v_bfe_u32 v17, v16, 16, 1
	v_add3_u32 v16, v16, v17, s80
	global_store_short_d16_hi v[2:3], v16, off offset:512
	v_accvgpr_read_b32 v16, a0
	v_bfe_u32 v17, v16, 16, 1
	v_add3_u32 v16, v16, v17, s80
	global_store_short_d16_hi v[4:5], v16, off offset:64
	v_accvgpr_read_b32 v16, a1
	v_bfe_u32 v17, v16, 16, 1
	v_add3_u32 v16, v16, v17, s80
	global_store_short_d16_hi v[4:5], v16, off offset:576
	v_accvgpr_read_b32 v4, a2
	v_bfe_u32 v5, v4, 16, 1
	v_add3_u32 v4, v4, v5, s80
	global_store_short_d16_hi v[6:7], v4, off offset:64
	v_accvgpr_read_b32 v4, a3
	v_bfe_u32 v5, v4, 16, 1
	v_add3_u32 v4, v4, v5, s80
	global_store_short_d16_hi v[6:7], v4, off offset:576
	v_accvgpr_read_b32 v4, a4
	v_bfe_u32 v5, v4, 16, 1
	v_add3_u32 v4, v4, v5, s80
	global_store_short_d16_hi v[8:9], v4, off offset:64
	v_accvgpr_read_b32 v4, a5
	v_bfe_u32 v5, v4, 16, 1
	v_add3_u32 v4, v4, v5, s80
	global_store_short_d16_hi v[8:9], v4, off offset:576
	v_accvgpr_read_b32 v4, a6
	v_bfe_u32 v5, v4, 16, 1
	v_add3_u32 v4, v4, v5, s80
	global_store_short_d16_hi v[10:11], v4, off offset:64
	v_accvgpr_read_b32 v4, a7
	v_bfe_u32 v5, v4, 16, 1
	v_add3_u32 v4, v4, v5, s80
	global_store_short_d16_hi v[10:11], v4, off offset:576
	v_accvgpr_read_b32 v4, a8
	v_bfe_u32 v5, v4, 16, 1
	v_add3_u32 v4, v4, v5, s80
	global_store_short_d16_hi v[12:13], v4, off offset:64
	v_accvgpr_read_b32 v4, a9
	v_bfe_u32 v5, v4, 16, 1
	v_add3_u32 v4, v4, v5, s80
	global_store_short_d16_hi v[12:13], v4, off offset:576
	v_accvgpr_read_b32 v4, a10
	v_bfe_u32 v5, v4, 16, 1
	v_add3_u32 v4, v4, v5, s80
	global_store_short_d16_hi v[14:15], v4, off offset:64
	v_accvgpr_read_b32 v4, a11
	v_bfe_u32 v5, v4, 16, 1
	v_add3_u32 v4, v4, v5, s80
	global_store_short_d16_hi v[14:15], v4, off offset:576
	v_accvgpr_read_b32 v4, a12
	v_bfe_u32 v5, v4, 16, 1
	v_add3_u32 v4, v4, v5, s80
	global_store_short_d16_hi v[0:1], v4, off offset:64
	v_accvgpr_read_b32 v4, a13
	v_bfe_u32 v5, v4, 16, 1
	v_add3_u32 v4, v4, v5, s80
	global_store_short_d16_hi v[0:1], v4, off offset:576
	v_accvgpr_read_b32 v0, a14
	v_bfe_u32 v1, v0, 16, 1
	v_add3_u32 v0, v0, v1, s80
	global_store_short_d16_hi v[2:3], v0, off offset:64
	v_accvgpr_read_b32 v0, a15
	v_bfe_u32 v1, v0, 16, 1
	v_add3_u32 v0, v0, v1, s80
	global_store_short_d16_hi v[2:3], v0, off offset:576

.LBB0_377:
	s_andn2_b64 vcc, exec, s[0:1]
	s_cbranch_vccnz .LBB0_387
	s_add_i32 s0, s97, 0xffd0
	s_and_b32 s1, s0, 0xff
	s_mulk_i32 s1, 0xcd
	s_bfe_u32 s4, s1, 0x5000b
	s_mul_i32 s1, s4, 10
	s_sub_i32 s6, s0, s1
	s_lshl_b32 s0, s4, 18
	v_readlane_b32 s2, v253, 24
	v_readlane_b32 s3, v253, 25
	s_add_u32 s0, s2, s0
	v_mov_b32_e32 v16, v208
	s_addc_u32 s1, s3, 0
	s_mul_i32 s2, s4, 0xc6000
	v_readlane_b32 s8, v254, 7
	v_readlane_b32 s9, v254, 8
	v_ashrrev_i32_e32 v4, 1, v16
	s_add_u32 s2, s8, s2
	v_and_b32_e32 v17, 31, v16
	v_lshrrev_b32_e32 v0, 5, v16
	v_and_b32_e32 v2, 7, v16
	v_and_b32_e32 v18, 0xffffffc0, v4
	s_addc_u32 s3, s9, 0
	s_lshl_b32 s5, s6, 7
	v_bfe_u32 v1, v16, 5, 1
	v_lshlrev_b32_e32 v3, 7, v16
	v_or_b32_e32 v4, v18, v17
	v_bitop3_b32 v0, v0, v2, 1 bitop3:0x6c
	s_and_b32 s5, s5, 0x80
	v_and_b32_e32 v3, 0x2f80, v3
	v_lshl_add_u32 v4, v4, 7, v214
	v_lshlrev_b32_e32 v0, 4, v0
	v_bitop3_b32 v5, v1, v2, 2 bitop3:0x36
	v_bitop3_b32 v6, v1, v2, 4 bitop3:0x36
	v_bitop3_b32 v1, v1, v2, 6 bitop3:0x36
	v_ashrrev_i32_e32 v28, 3, v16
	s_lshl_b32 s6, s6, 6
	v_or_b32_e32 v19, v0, v3
	v_bfe_u32 v75, v208, 3, 2
	v_lshlrev_b32_e32 v75, 4, v75
	v_xor_b32_e32 v19, v75, v19
	v_lshlrev_b32_e32 v1, 4, v1
	v_or_b32_e32 v23, v4, v0
	v_bfe_u32 v75, v208, 3, 2
	v_lshlrev_b32_e32 v75, 4, v75
	v_xor_b32_e32 v23, v75, v23
	v_add_u32_e32 v0, s5, v28
	s_and_b32 s6, s6, 0x380
	v_lshlrev_b32_e32 v5, 4, v5
	v_lshlrev_b32_e32 v6, 4, v6
	v_or_b32_e32 v22, v1, v3
	v_bfe_u32 v75, v208, 3, 2
	v_lshlrev_b32_e32 v75, 4, v75
	v_xor_b32_e32 v22, v75, v22
	v_or_b32_e32 v26, v4, v1
	v_bfe_u32 v75, v208, 3, 2
	v_lshlrev_b32_e32 v75, 4, v75
	v_xor_b32_e32 v26, v75, v26
	v_ashrrev_i32_e32 v1, 31, v0
	v_lshlrev_b32_e32 v2, 4, v16
	v_or_b32_e32 v24, v4, v5
	v_bfe_u32 v75, v208, 3, 2
	v_lshlrev_b32_e32 v75, 4, v75
	v_xor_b32_e32 v24, v75, v24
	v_or_b32_e32 v25, v4, v6
	v_bfe_u32 v75, v208, 3, 2
	v_lshlrev_b32_e32 v75, 4, v75
	v_xor_b32_e32 v25, v75, v25
	v_lshlrev_b64 v[0:1], 10, v[0:1]
	v_and_b32_e32 v192, 0x70, v2
	v_add_u32_e32 v2, s6, v28
	v_add_u32_e32 v4, 0x100, v16
	v_lshl_add_u64 v[0:1], s[0:1], 0, v[0:1]
	v_min_i32_e32 v2, 0x20f, v2
	v_mov_b64_e32 v[14:15], s[2:3]
	v_ashrrev_i32_e32 v34, 3, v4
	v_or_b32_e32 v20, v5, v3
	v_bfe_u32 v75, v208, 3, 2
	v_lshlrev_b32_e32 v75, 4, v75
	v_xor_b32_e32 v20, v75, v20
	v_or_b32_e32 v21, v6, v3
	v_bfe_u32 v75, v208, 3, 2
	v_lshlrev_b32_e32 v75, 4, v75
	v_xor_b32_e32 v21, v75, v21
	v_lshl_add_u64 v[0:1], v[0:1], 0, v[192:193]
	v_mad_i64_i32 v[2:3], s[2:3], v2, s68, v[14:15]
	v_add_u32_e32 v4, s5, v34
	v_add_u32_e32 v8, 0x200, v16
	global_load_dwordx4 v[30:33], v[0:1], off
	v_lshl_add_u64 v[2:3], v[2:3], 0, v[192:193]
	v_ashrrev_i32_e32 v5, 31, v4
	v_ashrrev_i32_e32 v35, 3, v8
	global_load_dwordx4 v[82:85], v[2:3], off
	v_lshlrev_b64 v[4:5], 10, v[4:5]
	v_add_u32_e32 v6, s6, v34
	v_add_u32_e32 v8, s5, v35
	v_add_u32_e32 v12, 0x300, v16
	v_lshl_add_u64 v[4:5], s[0:1], 0, v[4:5]
	v_min_i32_e32 v6, 0x20f, v6
	v_ashrrev_i32_e32 v9, 31, v8
	v_ashrrev_i32_e32 v90, 3, v12
	v_lshl_add_u64 v[4:5], v[4:5], 0, v[192:193]
	v_mad_i64_i32 v[6:7], s[2:3], v6, s68, v[14:15]
	v_lshlrev_b64 v[8:9], 10, v[8:9]
	v_add_u32_e32 v10, s6, v35
	v_add_u32_e32 v12, s5, v90
	global_load_dwordx4 v[86:89], v[4:5], off
	v_lshl_add_u64 v[6:7], v[6:7], 0, v[192:193]
	v_lshl_add_u64 v[8:9], s[0:1], 0, v[8:9]
	v_min_i32_e32 v10, 0x20f, v10
	v_ashrrev_i32_e32 v13, 31, v12
	global_load_dwordx4 v[94:97], v[6:7], off
	v_lshl_add_u64 v[8:9], v[8:9], 0, v[192:193]
	v_mad_i64_i32 v[10:11], s[2:3], v10, s68, v[14:15]
	v_lshlrev_b64 v[12:13], 10, v[12:13]
	global_load_dwordx4 v[98:101], v[8:9], off
	v_lshl_add_u64 v[10:11], v[10:11], 0, v[192:193]
	v_lshl_add_u64 v[12:13], s[0:1], 0, v[12:13]
	global_load_dwordx4 v[102:105], v[10:11], off
	v_lshl_add_u64 v[12:13], v[12:13], 0, v[192:193]
	global_load_dwordx4 v[106:109], v[12:13], off
	v_add_u32_e32 v27, s6, v90
	v_min_i32_e32 v27, 0x20f, v27
	v_mad_i64_i32 v[14:15], s[0:1], v27, s68, v[14:15]
	v_lshl_add_u64 v[14:15], v[14:15], 0, v[192:193]
	global_load_dwordx4 v[110:113], v[14:15], off
	global_load_dwordx4 v[36:39], v[0:1], off offset:128
	global_load_dwordx4 v[40:43], v[2:3], off offset:128
	global_load_dwordx4 v[44:47], v[4:5], off offset:128
	global_load_dwordx4 v[48:51], v[6:7], off offset:128
	global_load_dwordx4 v[52:55], v[8:9], off offset:128
	global_load_dwordx4 v[56:59], v[10:11], off offset:128
	global_load_dwordx4 v[60:63], v[12:13], off offset:128
	global_load_dwordx4 v[64:67], v[14:15], off offset:128
	v_lshlrev_b32_e32 v27, 7, v28
	v_xor_b32_e32 v28, v28, v16
	v_lshlrev_b32_e32 v28, 4, v28
	v_and_b32_e32 v28, 0x70, v28
	v_or_b32_e32 v29, v27, v28
	v_bfe_u32 v75, v208, 6, 2
	v_lshlrev_b32_e32 v75, 4, v75
	v_xor_b32_e32 v29, v75, v29
	s_waitcnt vmcnt(15)
	ds_write_b128 v29, v[30:33]
	s_waitcnt vmcnt(14)
	ds_write_b128 v29, v[82:85] offset:16384
	v_xor_b32_e32 v30, v34, v16
	v_lshlrev_b32_e32 v30, 4, v30
	v_lshlrev_b32_e32 v29, 7, v34
	v_and_b32_e32 v30, 0x70, v30
	v_xor_b32_e32 v32, v35, v16
	v_or_b32_e32 v31, v29, v30
	v_bfe_u32 v75, v208, 6, 2
	v_lshlrev_b32_e32 v75, 4, v75
	v_xor_b32_e32 v31, v75, v31
	v_lshlrev_b32_e32 v32, 4, v32
	s_waitcnt vmcnt(13)
	ds_write_b128 v31, v[86:89]
	s_waitcnt vmcnt(12)
	ds_write_b128 v31, v[94:97] offset:16384
	v_lshlrev_b32_e32 v31, 7, v35
	v_and_b32_e32 v32, 0x70, v32
	v_xor_b32_e32 v34, v90, v16
	v_or_b32_e32 v33, v31, v32
	v_bfe_u32 v75, v208, 6, 2
	v_lshlrev_b32_e32 v75, 4, v75
	v_xor_b32_e32 v33, v75, v33
	v_lshlrev_b32_e32 v34, 4, v34
	s_waitcnt vmcnt(11)
	ds_write_b128 v33, v[98:101]
	s_waitcnt vmcnt(10)
	ds_write_b128 v33, v[102:105] offset:16384
	v_lshlrev_b32_e32 v33, 7, v90
	v_and_b32_e32 v34, 0x70, v34
	v_or_b32_e32 v35, v33, v34
	v_bfe_u32 v75, v208, 6, 2
	v_lshlrev_b32_e32 v75, 4, v75
	v_xor_b32_e32 v35, v75, v35
	v_accvgpr_write_b32 a47, 0
	v_accvgpr_write_b32 a46, 0
	v_accvgpr_write_b32 a45, 0
	v_accvgpr_write_b32 a44, 0
	v_accvgpr_write_b32 a43, 0
	v_accvgpr_write_b32 a42, 0
	v_accvgpr_write_b32 a41, 0
	v_accvgpr_write_b32 a40, 0
	v_accvgpr_write_b32 a39, 0
	v_accvgpr_write_b32 a38, 0
	v_accvgpr_write_b32 a37, 0
	v_accvgpr_write_b32 a36, 0
	v_accvgpr_write_b32 a35, 0
	v_accvgpr_write_b32 a34, 0
	v_accvgpr_write_b32 a33, 0
	v_accvgpr_write_b32 a32, 0
	v_accvgpr_write_b32 a63, 0
	v_accvgpr_write_b32 a62, 0
	v_accvgpr_write_b32 a61, 0
	v_accvgpr_write_b32 a60, 0
	v_accvgpr_write_b32 a59, 0
	v_accvgpr_write_b32 a58, 0
	v_accvgpr_write_b32 a57, 0
	v_accvgpr_write_b32 a56, 0
	v_accvgpr_write_b32 a55, 0
	v_accvgpr_write_b32 a54, 0
	v_accvgpr_write_b32 a53, 0
	v_accvgpr_write_b32 a52, 0
	v_accvgpr_write_b32 a51, 0
	v_accvgpr_write_b32 a50, 0
	v_accvgpr_write_b32 a49, 0
	v_accvgpr_write_b32 a48, 0
	v_accvgpr_write_b32 a31, 0
	v_accvgpr_write_b32 a30, 0
	v_accvgpr_write_b32 a29, 0
	v_accvgpr_write_b32 a28, 0
	v_accvgpr_write_b32 a27, 0
	v_accvgpr_write_b32 a26, 0
	v_accvgpr_write_b32 a25, 0
	v_accvgpr_write_b32 a24, 0
	v_accvgpr_write_b32 a23, 0
	v_accvgpr_write_b32 a22, 0
	v_accvgpr_write_b32 a21, 0
	v_accvgpr_write_b32 a20, 0
	v_accvgpr_write_b32 a19, 0
	v_accvgpr_write_b32 a18, 0
	v_accvgpr_write_b32 a17, 0
	v_accvgpr_write_b32 a16, 0
	v_accvgpr_write_b32 a15, 0
	v_accvgpr_write_b32 a14, 0
	v_accvgpr_write_b32 a13, 0
	v_accvgpr_write_b32 a12, 0
	v_accvgpr_write_b32 a11, 0
	v_accvgpr_write_b32 a10, 0
	v_accvgpr_write_b32 a9, 0
	v_accvgpr_write_b32 a8, 0
	v_accvgpr_write_b32 a7, 0
	v_accvgpr_write_b32 a6, 0
	v_accvgpr_write_b32 a5, 0
	v_accvgpr_write_b32 a4, 0
	v_accvgpr_write_b32 a3, 0
	v_accvgpr_write_b32 a2, 0
	v_accvgpr_write_b32 a1, 0
	v_accvgpr_write_b32 a0, 0
	s_mov_b32 s0, -2
	s_mov_b32 s1, 0
	s_waitcnt vmcnt(9)
	ds_write_b128 v35, v[106:109]
	s_waitcnt vmcnt(8)
	ds_write_b128 v35, v[110:113] offset:16384
	s_waitcnt lgkmcnt(0)
	s_barrier
.LBB0_379:
	s_add_i32 s2, s1, 0x80
	s_min_u32 s3, s2, 0x1c0
	s_lshl_b32 s78, s3, 1
	v_lshl_add_u64 v[82:83], v[0:1], 0, s[78:79]
	v_lshl_add_u64 v[86:87], v[2:3], 0, s[78:79]
	v_lshl_add_u64 v[98:99], v[6:7], 0, s[78:79]
	v_lshl_add_u64 v[102:103], v[8:9], 0, s[78:79]
	v_lshl_add_u64 v[106:107], v[10:11], 0, s[78:79]
	v_lshl_add_u64 v[110:111], v[12:13], 0, s[78:79]
	v_lshl_add_u64 v[114:115], v[14:15], 0, s[78:79]
	v_lshl_add_u64 v[90:91], v[4:5], 0, s[78:79]
	global_load_dwordx4 v[82:85], v[82:83], off
	s_nop 0
	global_load_dwordx4 v[86:89], v[86:87], off
	s_nop 0
	global_load_dwordx4 v[94:97], v[90:91], off
	s_nop 0
	global_load_dwordx4 v[98:101], v[98:99], off
	s_nop 0
	global_load_dwordx4 v[102:105], v[102:103], off
	s_nop 0
	global_load_dwordx4 v[106:109], v[106:107], off
	s_nop 0
	global_load_dwordx4 v[110:113], v[110:111], off
	s_nop 0
	global_load_dwordx4 v[114:117], v[114:115], off
	ds_read_b128 v[118:121], v19 offset:0
	ds_read_b128 v[122:125], v19 offset:0x1000
	ds_read_b128 v[126:129], v23 offset:0
	ds_read_b128 v[130:133], v23 offset:0x1000
	s_min_u32 s1, s1, 0x100
	ds_read_b128 v[134:137], v20 offset:0
	ds_read_b128 v[138:141], v20 offset:0x1000
	ds_read_b128 v[142:145], v24 offset:0
	ds_read_b128 v[146:149], v24 offset:0x1000
	ds_read_b128 v[150:153], v21 offset:0
	ds_read_b128 v[154:157], v21 offset:0x1000
	ds_read_b128 v[158:161], v25 offset:0
	ds_read_b128 v[162:165], v25 offset:0x1000
	ds_read_b128 v[166:169], v22 offset:0
	ds_read_b128 v[170:173], v22 offset:0x1000
	ds_read_b128 v[174:177], v26 offset:0
	ds_read_b128 v[178:181], v26 offset:0x1000
	s_waitcnt lgkmcnt(12)
	s_lshl_b32 s78, s1, 1
	v_mfma_f32_32x32x16_bf16 a[16:31], v[122:125], v[126:129], a[16:31]
	v_add_u32_e32 v35, v27, v28
	v_bfe_u32 v75, v208, 6, 2
	v_lshlrev_b32_e32 v75, 4, v75
	v_xor_b32_e32 v35, v75, v35
	v_lshl_add_u64 v[90:91], v[0:1], 0, s[78:79]
	s_waitcnt lgkmcnt(8)
	s_waitcnt lgkmcnt(4)
	v_add_u32_e32 v182, v29, v30
	v_bfe_u32 v75, v208, 6, 2
	v_lshlrev_b32_e32 v75, 4, v75
	v_xor_b32_e32 v182, v75, v182
	v_add_u32_e32 v183, v31, v32
	v_bfe_u32 v75, v208, 6, 2
	v_lshlrev_b32_e32 v75, 4, v75
	v_xor_b32_e32 v183, v75, v183
	v_add_u32_e32 v184, v33, v34
	v_bfe_u32 v75, v208, 6, 2
	v_lshlrev_b32_e32 v75, 4, v75
	v_xor_b32_e32 v184, v75, v184
	v_mfma_f32_32x32x16_bf16 a[0:15], v[122:125], v[130:133], a[0:15]
	v_lshl_add_u64 v[124:125], v[8:9], 0, s[78:79]
	v_lshl_add_u64 v[122:123], v[6:7], 0, s[78:79]
	s_waitcnt lgkmcnt(0)
	s_waitcnt vmcnt(15)
	ds_write_b128 v35, v[36:39] offset:32768
	s_waitcnt vmcnt(14)
	ds_write_b128 v35, v[40:43] offset:49152
	s_waitcnt vmcnt(13)
	ds_write_b128 v182, v[44:47] offset:32768
	s_waitcnt vmcnt(12)
	ds_write_b128 v182, v[48:51] offset:49152
	s_waitcnt vmcnt(11)
	ds_write_b128 v183, v[52:55] offset:32768
	s_waitcnt vmcnt(10)
	ds_write_b128 v183, v[56:59] offset:49152
	s_waitcnt vmcnt(9)
	ds_write_b128 v184, v[60:63] offset:32768
	s_waitcnt vmcnt(8)
	ds_write_b128 v184, v[64:67] offset:49152
	s_waitcnt lgkmcnt(0)
	s_barrier
	v_mfma_f32_32x32x16_bf16 a[32:47], v[118:121], v[126:129], a[32:47]
	v_lshl_add_u64 v[126:127], v[10:11], 0, s[78:79]
	v_lshl_add_u64 v[128:129], v[12:13], 0, s[78:79]
	s_add_i32 s0, s0, 2
	s_mov_b32 s1, s2
	s_cmp_gt_u32 s0, 5
	v_mfma_f32_32x32x16_bf16 a[48:63], v[118:121], v[130:133], a[48:63]
	v_lshl_add_u64 v[118:119], v[2:3], 0, s[78:79]
	v_lshl_add_u64 v[120:121], v[4:5], 0, s[78:79]
	v_lshl_add_u64 v[130:131], v[14:15], 0, s[78:79]
	global_load_dwordx4 v[36:39], v[90:91], off offset:384
	global_load_dwordx4 v[40:43], v[118:119], off offset:384
	global_load_dwordx4 v[44:47], v[120:121], off offset:384
	global_load_dwordx4 v[48:51], v[122:123], off offset:384
	global_load_dwordx4 v[52:55], v[124:125], off offset:384
	global_load_dwordx4 v[56:59], v[126:127], off offset:384
	global_load_dwordx4 v[60:63], v[128:129], off offset:384
	global_load_dwordx4 v[64:67], v[130:131], off offset:384
	ds_read_b128 v[118:121], v19 offset:0x8000
	ds_read_b128 v[122:125], v19 offset:0x9000
	v_mfma_f32_32x32x16_bf16 a[32:47], v[134:137], v[142:145], a[32:47]
	ds_read_b128 v[126:129], v23 offset:0x8000
	ds_read_b128 v[130:133], v23 offset:0x9000
	v_mfma_f32_32x32x16_bf16 a[48:63], v[134:137], v[146:149], a[48:63]
	ds_read_b128 v[134:137], v20 offset:0x8000
	v_mfma_f32_32x32x16_bf16 a[16:31], v[138:141], v[142:145], a[16:31]
	v_mfma_f32_32x32x16_bf16 a[0:15], v[138:141], v[146:149], a[0:15]
	ds_read_b128 v[138:141], v20 offset:0x9000
	ds_read_b128 v[142:145], v24 offset:0x8000
	ds_read_b128 v[146:149], v24 offset:0x9000
	v_mfma_f32_32x32x16_bf16 a[32:47], v[150:153], v[158:161], a[32:47]
	v_mfma_f32_32x32x16_bf16 a[48:63], v[150:153], v[162:165], a[48:63]
	ds_read_b128 v[150:153], v21 offset:0x8000
	v_mfma_f32_32x32x16_bf16 a[16:31], v[154:157], v[158:161], a[16:31]
	v_mfma_f32_32x32x16_bf16 a[0:15], v[154:157], v[162:165], a[0:15]
	ds_read_b128 v[154:157], v21 offset:0x9000
	ds_read_b128 v[158:161], v25 offset:0x8000
	ds_read_b128 v[162:165], v25 offset:0x9000
	v_mfma_f32_32x32x16_bf16 a[32:47], v[166:169], v[174:177], a[32:47]
	v_mfma_f32_32x32x16_bf16 a[48:63], v[166:169], v[178:181], a[48:63]
	ds_read_b128 v[166:169], v22 offset:0x8000
	v_mfma_f32_32x32x16_bf16 a[16:31], v[170:173], v[174:177], a[16:31]
	v_mfma_f32_32x32x16_bf16 a[0:15], v[170:173], v[178:181], a[0:15]
	ds_read_b128 v[170:173], v22 offset:0x9000
	ds_read_b128 v[174:177], v26 offset:0x8000
	ds_read_b128 v[178:181], v26 offset:0x9000
	s_waitcnt lgkmcnt(12)
	s_waitcnt lgkmcnt(8)
	s_waitcnt lgkmcnt(4)
	s_nop 0
	v_mfma_f32_32x32x16_bf16 a[32:47], v[118:121], v[126:129], a[32:47]
	s_waitcnt lgkmcnt(0)
	s_waitcnt vmcnt(15)
	ds_write_b128 v35, v[82:85]
	s_waitcnt vmcnt(14)
	ds_write_b128 v35, v[86:89] offset:16384
	s_waitcnt vmcnt(13)
	ds_write_b128 v182, v[94:97]
	s_waitcnt vmcnt(12)
	ds_write_b128 v182, v[98:101] offset:16384
	s_waitcnt vmcnt(11)
	ds_write_b128 v183, v[102:105]
	s_waitcnt vmcnt(10)
	ds_write_b128 v183, v[106:109] offset:16384
	s_waitcnt vmcnt(9)
	ds_write_b128 v184, v[110:113]
	s_waitcnt vmcnt(8)
	ds_write_b128 v184, v[114:117] offset:16384
	s_waitcnt lgkmcnt(0)
	s_barrier
	v_mfma_f32_32x32x16_bf16 a[48:63], v[118:121], v[130:133], a[48:63]
	v_mfma_f32_32x32x16_bf16 a[16:31], v[122:125], v[126:129], a[16:31]
	v_mfma_f32_32x32x16_bf16 a[0:15], v[122:125], v[130:133], a[0:15]
	v_mfma_f32_32x32x16_bf16 a[32:47], v[134:137], v[142:145], a[32:47]
	v_mfma_f32_32x32x16_bf16 a[48:63], v[134:137], v[146:149], a[48:63]
	v_mfma_f32_32x32x16_bf16 a[16:31], v[138:141], v[142:145], a[16:31]
	v_mfma_f32_32x32x16_bf16 a[0:15], v[138:141], v[146:149], a[0:15]
	v_mfma_f32_32x32x16_bf16 a[32:47], v[150:153], v[158:161], a[32:47]
	v_mfma_f32_32x32x16_bf16 a[48:63], v[150:153], v[162:165], a[48:63]
	v_mfma_f32_32x32x16_bf16 a[16:31], v[154:157], v[158:161], a[16:31]
	v_mfma_f32_32x32x16_bf16 a[0:15], v[154:157], v[162:165], a[0:15]
	v_mfma_f32_32x32x16_bf16 a[32:47], v[166:169], v[174:177], a[32:47]
	v_mfma_f32_32x32x16_bf16 a[48:63], v[166:169], v[178:181], a[48:63]
	v_mfma_f32_32x32x16_bf16 a[16:31], v[170:173], v[174:177], a[16:31]
	v_mfma_f32_32x32x16_bf16 a[0:15], v[170:173], v[178:181], a[0:15]
	s_cbranch_scc0 .LBB0_379
	v_or_b32_e32 v1, s6, v17
	s_mul_i32 s4, s4, 0x84000
	v_readlane_b32 s0, v254, 9
	v_add_u32_e32 v2, v1, v18
	v_lshrrev_b32_e32 v1, 3, v16
	v_readlane_b32 s1, v254, 10
	s_add_u32 s0, s0, s4
	v_and_b32_e32 v0, 64, v16
	v_and_b32_e32 v1, 4, v1
	v_ashrrev_i32_e32 v3, 31, v2
	s_addc_u32 s1, s1, 0
	v_or3_b32 v4, v0, v1, s5
	s_movk_i32 s2, 0x210
	v_lshlrev_b64 v[0:1], 10, v[2:3]
	v_cmp_gt_i32_e32 vcc, s2, v2
	v_lshl_add_u64 v[0:1], s[0:1], 0, v[0:1]
	v_lshlrev_b32_e32 v192, 2, v4
	s_and_saveexec_b64 s[2:3], vcc
	s_cbranch_execz .LBB0_382
	v_lshl_add_u64 v[4:5], v[0:1], 0, v[192:193]
	global_store_dwordx4 v[4:5], a[32:35], off
	global_store_dwordx4 v[4:5], a[36:39], off offset:32
	global_store_dwordx4 v[4:5], a[40:43], off offset:64
	global_store_dwordx4 v[4:5], a[44:47], off offset:96
